# speedup vs baseline: 1.0157x; 1.0157x over previous
; #define GAS __attribute__((address_space(1)))
; __device__ __forceinline__ uint2 pack4(f32x4 v) { return make_uint2(pack2(v[0], v[1]), pack2(v[2], v[3])); }
; template <int MODE>
; __device__ __forceinline__ void epi_elem(char* ws, float* outp, const float* b_gate, int g0, int rl, int col, f32x4 v) {
;     ...
;   } else if (MODE == E_T || MODE == E_FF) {
;     *(GAS uint2*)((u16*)(ws + (MODE == E_T ? W_T : W_FF)) + (size_t)rl * 1024 + col) = pack4(v);
; template <int MODE>
; __device__ __forceinline__ void epi_store(char* ws, float* outp, const float* b_gate, int g0, const f32x4 (&acc)[2][2][4][2], int rbase, int cbase) {
; #pragma unroll
;   for (int ai = 0; ai < 2; ++ai)
; #pragma unroll
;     for (int bj = 0; bj < 2; ++bj)
; #pragma unroll
;       for (int m = 0; m < 4; ++m) {
; #pragma unroll
;         for (int n = 0; n < 2; ++n)
;           epi_elem<MODE>(ws, outp, b_gate, g0, rbase + ai * HALF + m * 16, cbase + bj * HALF + n * 16, acc[ai][bj][m][n]);
;         if ((m & 1) && (MODE != E_M1 && MODE != E_MG)) __builtin_amdgcn_sched_barrier(0);
;         if (m == 3 && (MODE == E_M1 || MODE == E_MG)) __builtin_amdgcn_sched_barrier(0);
;       }
.LBB0_960:
	v_readlane_b32 s2, v255, 21
	v_readlane_b32 s3, v255, 22
	s_mov_b64 s[6:7], -1
	s_and_b64 vcc, exec, s[2:3]
	s_cbranch_vccz .LBB0_997
	s_and_b64 s[4:5], s[4:5], exec
	s_cselect_b32 s8, 6, 7
	s_and_b64 s[4:5], s[30:31], exec
	v_readlane_b32 s4, v255, 29
	v_add_u32_e32 v142, s86, v1
	v_add_u32_e32 v140, s70, v184
	s_cselect_b32 s8, s8, s4
	s_ashr_i32 s4, s70, 10
	s_load_dwordx2 s[6:7], s[0:1], 0xb8
	s_load_dwordx2 s[10:11], s[0:1], 0x60
	s_load_dwordx2 s[2:3], s[0:1], 0xc0
	s_min_i32 s9, s4, 5
	v_readlane_b32 s4, v255, 14
	v_readlane_b32 s5, v255, 15
	s_and_b64 s[4:5], s[4:5], exec
	s_cselect_b32 s16, s9, s8
	s_mov_b64 s[12:13], -1
	s_mov_b64 s[8:9], 0
	s_cmp_lt_i32 s16, 4
	s_mov_b64 s[4:5], 0
	s_waitcnt lgkmcnt(0)
	s_cbranch_scc1 .LBB0_980
	s_cmp_gt_i32 s16, 5
	s_cbranch_scc0 .LBB0_974
	s_cmp_gt_i32 s16, 6
	s_cbranch_scc0 .LBB0_971
	s_cmp_gt_i32 s16, 7
	s_cbranch_scc0 .LBB0_968
	s_cmp_eq_u32 s16, 8
	s_mov_b64 s[4:5], -1
	s_cbranch_scc0 .LBB0_967
	v_ashrrev_i32_e32 v143, 31, v142
	v_lshlrev_b64 v[144:145], 11, v[142:143]
	v_lshl_add_u64 v[144:145], s[2:3], 0, v[144:145]
	v_ashrrev_i32_e32 v141, 31, v140
	v_lshl_add_u64 v[144:145], v[140:141], 1, v[144:145]
	s_mov_b64 s[4:5], 0x2aec0000
	v_add_co_u32_e32 v150, vcc, 0x2aec0000, v144
	v_cvt_pk_bf16_f32 v146, v126, v127
	v_cvt_pk_bf16_f32 v147, v128, v129
	v_lshl_add_u64 v[148:149], v[144:145], 0, s[4:5]
	v_addc_co_u32_e32 v151, vcc, 0, v145, vcc
	s_mov_b64 s[4:5], 0x2aec8000
	global_store_dwordx2 v[150:151], v[146:147], off
	v_lshl_add_u64 v[150:151], v[144:145], 0, s[4:5]
	s_mov_b32 s4, 0x2aec8000
	v_cvt_pk_bf16_f32 v146, v122, v123
	v_cvt_pk_bf16_f32 v147, v124, v125
	v_add_co_u32_e32 v152, vcc, s4, v144
	global_store_dwordx2 v[148:149], v[146:147], off offset:32
	v_cvt_pk_bf16_f32 v146, v118, v119
	v_cvt_pk_bf16_f32 v147, v120, v121
	v_addc_co_u32_e32 v153, vcc, 0, v145, vcc
	global_store_dwordx2 v[152:153], v[146:147], off
	v_cvt_pk_bf16_f32 v146, v114, v115
	v_cvt_pk_bf16_f32 v147, v116, v117
	global_store_dwordx2 v[150:151], v[146:147], off offset:32
	s_mov_b64 s[4:5], 0x2aed0000
	v_lshl_add_u64 v[152:153], v[144:145], 0, s[4:5]
	s_mov_b32 s4, 0x2aed0000
	v_add_co_u32_e32 v154, vcc, s4, v144
	v_cvt_pk_bf16_f32 v146, v110, v111
	v_cvt_pk_bf16_f32 v147, v112, v113
	v_addc_co_u32_e32 v155, vcc, 0, v145, vcc
	s_mov_b64 s[4:5], 0x2aed8000
	global_store_dwordx2 v[154:155], v[146:147], off
	v_lshl_add_u64 v[154:155], v[144:145], 0, s[4:5]
	s_mov_b32 s4, 0x2aed8000
	v_cvt_pk_bf16_f32 v146, v106, v107
	v_cvt_pk_bf16_f32 v147, v108, v109
	v_add_co_u32_e32 v156, vcc, s4, v144
	global_store_dwordx2 v[152:153], v[146:147], off offset:32
	v_cvt_pk_bf16_f32 v146, v102, v103
	v_cvt_pk_bf16_f32 v147, v104, v105
	v_addc_co_u32_e32 v157, vcc, 0, v145, vcc
	global_store_dwordx2 v[156:157], v[146:147], off
	v_cvt_pk_bf16_f32 v146, v98, v99
	v_cvt_pk_bf16_f32 v147, v100, v101
	global_store_dwordx2 v[154:155], v[146:147], off offset:32
	v_cvt_pk_bf16_f32 v146, v94, v95
	v_cvt_pk_bf16_f32 v147, v96, v97
	global_store_dwordx2 v[148:149], v[146:147], off offset:256
	v_cvt_pk_bf16_f32 v146, v90, v91
	v_cvt_pk_bf16_f32 v147, v92, v93
	global_store_dwordx2 v[148:149], v[146:147], off offset:288
	v_cvt_pk_bf16_f32 v146, v86, v87
	v_cvt_pk_bf16_f32 v147, v88, v89
	global_store_dwordx2 v[150:151], v[146:147], off offset:256
	v_cvt_pk_bf16_f32 v146, v82, v83
	v_cvt_pk_bf16_f32 v147, v84, v85
	global_store_dwordx2 v[150:151], v[146:147], off offset:288
	v_cvt_pk_bf16_f32 v146, v78, v79
	v_cvt_pk_bf16_f32 v147, v80, v81
	global_store_dwordx2 v[152:153], v[146:147], off offset:256
	v_cvt_pk_bf16_f32 v146, v74, v75
	v_cvt_pk_bf16_f32 v147, v76, v77
	global_store_dwordx2 v[152:153], v[146:147], off offset:288
	v_cvt_pk_bf16_f32 v146, v70, v71
	v_cvt_pk_bf16_f32 v147, v72, v73
	global_store_dwordx2 v[154:155], v[146:147], off offset:256
	v_cvt_pk_bf16_f32 v146, v66, v67
	v_cvt_pk_bf16_f32 v147, v68, v69
	global_store_dwordx2 v[154:155], v[146:147], off offset:288
	s_mov_b64 s[4:5], 0x2af00000
	v_lshl_add_u64 v[148:149], v[144:145], 0, s[4:5]
	s_mov_b32 s4, 0x2af00000
	v_add_co_u32_e32 v150, vcc, s4, v144
	v_cvt_pk_bf16_f32 v146, v62, v63
	v_cvt_pk_bf16_f32 v147, v64, v65
	v_addc_co_u32_e32 v151, vcc, 0, v145, vcc
	s_mov_b64 s[4:5], 0x2af08000
	global_store_dwordx2 v[150:151], v[146:147], off
	v_lshl_add_u64 v[150:151], v[144:145], 0, s[4:5]
	s_mov_b32 s4, 0x2af08000
	v_cvt_pk_bf16_f32 v146, v58, v59
	v_cvt_pk_bf16_f32 v147, v60, v61
	v_add_co_u32_e32 v152, vcc, s4, v144
	global_store_dwordx2 v[148:149], v[146:147], off offset:32
	v_cvt_pk_bf16_f32 v146, v54, v55
	v_cvt_pk_bf16_f32 v147, v56, v57
	v_addc_co_u32_e32 v153, vcc, 0, v145, vcc
	global_store_dwordx2 v[152:153], v[146:147], off
	v_cvt_pk_bf16_f32 v146, v50, v51
	v_cvt_pk_bf16_f32 v147, v52, v53
	global_store_dwordx2 v[150:151], v[146:147], off offset:32
	s_mov_b64 s[4:5], 0x2af10000
	v_lshl_add_u64 v[152:153], v[144:145], 0, s[4:5]
	s_mov_b32 s4, 0x2af10000
	v_add_co_u32_e32 v154, vcc, s4, v144
	v_cvt_pk_bf16_f32 v146, v46, v47
	v_cvt_pk_bf16_f32 v147, v48, v49
	v_addc_co_u32_e32 v155, vcc, 0, v145, vcc
	s_mov_b64 s[4:5], 0x2af18000
	global_store_dwordx2 v[154:155], v[146:147], off
	v_lshl_add_u64 v[154:155], v[144:145], 0, s[4:5]
	s_mov_b32 s4, 0x2af18000
	v_cvt_pk_bf16_f32 v146, v42, v43
	v_cvt_pk_bf16_f32 v147, v44, v45
	v_add_co_u32_e32 v144, vcc, s4, v144
	global_store_dwordx2 v[152:153], v[146:147], off offset:32
	v_cvt_pk_bf16_f32 v146, v38, v39
	v_cvt_pk_bf16_f32 v147, v40, v41
	v_addc_co_u32_e32 v145, vcc, 0, v145, vcc
	global_store_dwordx2 v[144:145], v[146:147], off
	v_cvt_pk_bf16_f32 v144, v34, v35
	v_cvt_pk_bf16_f32 v145, v36, v37
	global_store_dwordx2 v[154:155], v[144:145], off offset:32
	v_cvt_pk_bf16_f32 v144, v30, v31
	v_cvt_pk_bf16_f32 v145, v32, v33
	global_store_dwordx2 v[148:149], v[144:145], off offset:256
	v_cvt_pk_bf16_f32 v144, v26, v27
	v_cvt_pk_bf16_f32 v145, v28, v29
	global_store_dwordx2 v[148:149], v[144:145], off offset:288
	v_cvt_pk_bf16_f32 v144, v22, v23
	v_cvt_pk_bf16_f32 v145, v24, v25
	global_store_dwordx2 v[150:151], v[144:145], off offset:256
	v_cvt_pk_bf16_f32 v144, v18, v19
	v_cvt_pk_bf16_f32 v145, v20, v21
	global_store_dwordx2 v[150:151], v[144:145], off offset:288
	v_cvt_pk_bf16_f32 v144, v14, v15
	v_cvt_pk_bf16_f32 v145, v16, v17
	global_store_dwordx2 v[152:153], v[144:145], off offset:256
	v_cvt_pk_bf16_f32 v144, v10, v11
	v_cvt_pk_bf16_f32 v145, v12, v13
	global_store_dwordx2 v[152:153], v[144:145], off offset:288
	v_cvt_pk_bf16_f32 v144, v6, v7
	v_cvt_pk_bf16_f32 v145, v8, v9
	global_store_dwordx2 v[154:155], v[144:145], off offset:256
	v_cvt_pk_bf16_f32 v144, v2, v3
	v_cvt_pk_bf16_f32 v145, v4, v5
	global_store_dwordx2 v[154:155], v[144:145], off offset:288
	s_mov_b64 s[4:5], 0

; #define GAS __attribute__((address_space(1)))
; __device__ __forceinline__ float bf2f(u16 b) { return __uint_as_float(((uint32_t)b) << 16); }
; __device__ __forceinline__ uint2 pack4(f32x4 v) { return make_uint2(pack2(v[0], v[1]), pack2(v[2], v[3])); }
; template <int MODE>
; __device__ __forceinline__ void epi_elem(char* ws, float* outp, const float* b_gate, int g0, int rl, int col, f32x4 v) {
;     ...
;   } else if (MODE == E_MG) {
;     uint2 g = *(GAS const uint2*)((const u16*)(ws + W_G) + (size_t)rl * 2048 + 1024 + col);
;     uint2 m = *(GAS const uint2*)((const u16*)(ws + W_M1) + (size_t)rl * 1024 + col);
;     f32x4 o;
;     o[0] = bf2f((u16)(m.x & 0xffff)) + v[0] * bf2f((u16)(g.x & 0xffff));
;     o[1] = bf2f((u16)(m.x >> 16)) + v[1] * bf2f((u16)(g.x >> 16));
;     o[2] = bf2f((u16)(m.y & 0xffff)) + v[2] * bf2f((u16)(g.y & 0xffff));
;     o[3] = bf2f((u16)(m.y >> 16)) + v[3] * bf2f((u16)(g.y >> 16));
;     *(GAS uint2*)((u16*)(ws + W_MG) + (size_t)rl * 1024 + col) = pack4(o);
; template <int MODE>
; __device__ __forceinline__ void epi_store(char* ws, float* outp, const float* b_gate, int g0, const f32x4 (&acc)[2][2][4][2], int rbase, int cbase) {
; #pragma unroll
;   for (int ai = 0; ai < 2; ++ai)
; #pragma unroll
;     for (int bj = 0; bj < 2; ++bj)
; #pragma unroll
;       for (int m = 0; m < 4; ++m) {
; #pragma unroll
;         for (int n = 0; n < 2; ++n)
;           epi_elem<MODE>(ws, outp, b_gate, g0, rbase + ai * HALF + m * 16, cbase + bj * HALF + n * 16, acc[ai][bj][m][n]);
;         if ((m & 1) && (MODE != E_M1 && MODE != E_MG)) __builtin_amdgcn_sched_barrier(0);
;         if (m == 3 && (MODE == E_M1 || MODE == E_MG)) __builtin_amdgcn_sched_barrier(0);
;       }
.LBB0_968:
	s_and_b64 vcc, exec, s[12:13]
	s_cbranch_vccz .LBB0_970
	v_lshlrev_b32_e32 v141, 12, v142
	v_lshlrev_b32_e32 v143, 11, v142
	v_lshl_add_u32 v246, v140, 1, v141
	v_lshl_add_u32 v250, v140, 1, v143
	s_add_u32 s4, s2, 0x1aac0800
	s_addc_u32 s5, s3, 0
	s_add_u32 s6, s2, 0x1ab40800
	s_addc_u32 s7, s3, 0
	v_add_u32_e32 v247, 0x10000, v246
	v_add_u32_e32 v248, 0x20000, v246
	v_add_u32_e32 v249, 0x30000, v246
	s_add_u32 s8, s2, 0x2aec0000
	s_addc_u32 s9, s3, 0
	s_add_u32 s12, s2, 0x2af00000
	s_addc_u32 s13, s3, 0
	v_add_u32_e32 v251, 0x8000, v250
	v_add_u32_e32 v252, 0x10000, v250
	v_add_u32_e32 v253, 0x18000, v250
	s_add_u32 s14, s2, 0x2efc0000
	s_addc_u32 s15, s3, 0
	s_add_u32 s16, s2, 0x2f000000
	s_addc_u32 s17, s3, 0
	s_mov_b32 s18, 0xffff0000
	global_load_dwordx2 v[144:145], v246, s[4:5]
	global_load_dwordx2 v[146:147], v250, s[8:9]
	global_load_dwordx2 v[148:149], v246, s[4:5] offset:32
	global_load_dwordx2 v[150:151], v250, s[8:9] offset:32
	global_load_dwordx2 v[152:153], v247, s[4:5]
	global_load_dwordx2 v[154:155], v251, s[8:9]
	global_load_dwordx2 v[156:157], v247, s[4:5] offset:32
	global_load_dwordx2 v[158:159], v251, s[8:9] offset:32
	global_load_dwordx2 v[160:161], v248, s[4:5]
	global_load_dwordx2 v[162:163], v252, s[8:9]
	global_load_dwordx2 v[164:165], v248, s[4:5] offset:32
	global_load_dwordx2 v[166:167], v252, s[8:9] offset:32
	global_load_dwordx2 v[168:169], v249, s[4:5]
	global_load_dwordx2 v[170:171], v253, s[8:9]
	global_load_dwordx2 v[172:173], v249, s[4:5] offset:32
	global_load_dwordx2 v[174:175], v253, s[8:9] offset:32
	global_load_dwordx2 v[214:215], v246, s[4:5] offset:256
	global_load_dwordx2 v[216:217], v250, s[8:9] offset:256
	global_load_dwordx2 v[218:219], v246, s[4:5] offset:288
	global_load_dwordx2 v[220:221], v250, s[8:9] offset:288
	global_load_dwordx2 v[222:223], v247, s[4:5] offset:256
	global_load_dwordx2 v[224:225], v251, s[8:9] offset:256
	global_load_dwordx2 v[226:227], v247, s[4:5] offset:288
	global_load_dwordx2 v[228:229], v251, s[8:9] offset:288
	global_load_dwordx2 v[230:231], v248, s[4:5] offset:256
	global_load_dwordx2 v[232:233], v252, s[8:9] offset:256
	global_load_dwordx2 v[234:235], v248, s[4:5] offset:288
	global_load_dwordx2 v[236:237], v252, s[8:9] offset:288
	global_load_dwordx2 v[238:239], v249, s[4:5] offset:256
	global_load_dwordx2 v[240:241], v253, s[8:9] offset:256
	global_load_dwordx2 v[242:243], v249, s[4:5] offset:288
	global_load_dwordx2 v[244:245], v253, s[8:9] offset:288
	s_waitcnt vmcnt(16)
	v_lshlrev_b32_e32 v176, 16, v144
	v_and_b32_e32 v177, s18, v144
	v_lshlrev_b32_e32 v178, 16, v145
	v_and_b32_e32 v179, s18, v145
	v_lshlrev_b32_e32 v180, 16, v146
	v_and_b32_e32 v181, s18, v146
	v_lshlrev_b32_e32 v182, 16, v147
	v_and_b32_e32 v183, s18, v147
	v_pk_fma_f32 v[180:181], v[126:127], v[176:177], v[180:181]
	v_pk_fma_f32 v[182:183], v[128:129], v[178:179], v[182:183]
	v_cvt_pk_bf16_f32 v180, v180, v181
	v_cvt_pk_bf16_f32 v181, v182, v183
	global_store_dwordx2 v250, v[180:181], s[14:15]
	v_lshlrev_b32_e32 v188, 16, v148
	v_and_b32_e32 v189, s18, v148
	v_lshlrev_b32_e32 v190, 16, v149
	v_and_b32_e32 v191, s18, v149
	v_lshlrev_b32_e32 v192, 16, v150
	v_and_b32_e32 v193, s18, v150
	v_lshlrev_b32_e32 v194, 16, v151
	v_and_b32_e32 v195, s18, v151
	v_pk_fma_f32 v[192:193], v[122:123], v[188:189], v[192:193]
	v_pk_fma_f32 v[194:195], v[124:125], v[190:191], v[194:195]
	v_cvt_pk_bf16_f32 v192, v192, v193
	v_cvt_pk_bf16_f32 v193, v194, v195
	global_store_dwordx2 v250, v[192:193], s[14:15] offset:32
	v_lshlrev_b32_e32 v176, 16, v152
	v_and_b32_e32 v177, s18, v152
	v_lshlrev_b32_e32 v178, 16, v153
	v_and_b32_e32 v179, s18, v153
	v_lshlrev_b32_e32 v180, 16, v154
	v_and_b32_e32 v181, s18, v154
	v_lshlrev_b32_e32 v182, 16, v155
	v_and_b32_e32 v183, s18, v155
	v_pk_fma_f32 v[180:181], v[118:119], v[176:177], v[180:181]
	v_pk_fma_f32 v[182:183], v[120:121], v[178:179], v[182:183]
	v_cvt_pk_bf16_f32 v180, v180, v181
	v_cvt_pk_bf16_f32 v181, v182, v183
	global_store_dwordx2 v251, v[180:181], s[14:15]
	v_lshlrev_b32_e32 v188, 16, v156
	v_and_b32_e32 v189, s18, v156
	v_lshlrev_b32_e32 v190, 16, v157
	v_and_b32_e32 v191, s18, v157
	v_lshlrev_b32_e32 v192, 16, v158
	v_and_b32_e32 v193, s18, v158
	v_lshlrev_b32_e32 v194, 16, v159
	v_and_b32_e32 v195, s18, v159
	v_pk_fma_f32 v[192:193], v[114:115], v[188:189], v[192:193]
	v_pk_fma_f32 v[194:195], v[116:117], v[190:191], v[194:195]
	v_cvt_pk_bf16_f32 v192, v192, v193
	v_cvt_pk_bf16_f32 v193, v194, v195
	global_store_dwordx2 v251, v[192:193], s[14:15] offset:32
	v_lshlrev_b32_e32 v176, 16, v160
	v_and_b32_e32 v177, s18, v160
	v_lshlrev_b32_e32 v178, 16, v161
	v_and_b32_e32 v179, s18, v161
	v_lshlrev_b32_e32 v180, 16, v162
	v_and_b32_e32 v181, s18, v162
	v_lshlrev_b32_e32 v182, 16, v163
	v_and_b32_e32 v183, s18, v163
	v_pk_fma_f32 v[180:181], v[110:111], v[176:177], v[180:181]
	v_pk_fma_f32 v[182:183], v[112:113], v[178:179], v[182:183]
	v_cvt_pk_bf16_f32 v180, v180, v181
	v_cvt_pk_bf16_f32 v181, v182, v183
	global_store_dwordx2 v252, v[180:181], s[14:15]
	v_lshlrev_b32_e32 v188, 16, v164
	v_and_b32_e32 v189, s18, v164
	v_lshlrev_b32_e32 v190, 16, v165
	v_and_b32_e32 v191, s18, v165
	v_lshlrev_b32_e32 v192, 16, v166
	v_and_b32_e32 v193, s18, v166
	v_lshlrev_b32_e32 v194, 16, v167
	v_and_b32_e32 v195, s18, v167
	v_pk_fma_f32 v[192:193], v[106:107], v[188:189], v[192:193]
	v_pk_fma_f32 v[194:195], v[108:109], v[190:191], v[194:195]
	v_cvt_pk_bf16_f32 v192, v192, v193
	v_cvt_pk_bf16_f32 v193, v194, v195
	global_store_dwordx2 v252, v[192:193], s[14:15] offset:32
	v_lshlrev_b32_e32 v176, 16, v168
	v_and_b32_e32 v177, s18, v168
; #define GAS __attribute__((address_space(1)))
; __device__ __forceinline__ float bf2f(u16 b) { return __uint_as_float(((uint32_t)b) << 16); }
; __device__ __forceinline__ uint2 pack4(f32x4 v) { return make_uint2(pack2(v[0], v[1]), pack2(v[2], v[3])); }
; template <int MODE>
; __device__ __forceinline__ void epi_elem(char* ws, float* outp, const float* b_gate, int g0, int rl, int col, f32x4 v) {
;     ...
;   } else if (MODE == E_MG) {
;     uint2 g = *(GAS const uint2*)((const u16*)(ws + W_G) + (size_t)rl * 2048 + 1024 + col);
;     uint2 m = *(GAS const uint2*)((const u16*)(ws + W_M1) + (size_t)rl * 1024 + col);
;     f32x4 o;
;     o[0] = bf2f((u16)(m.x & 0xffff)) + v[0] * bf2f((u16)(g.x & 0xffff));
;     o[1] = bf2f((u16)(m.x >> 16)) + v[1] * bf2f((u16)(g.x >> 16));
;     o[2] = bf2f((u16)(m.y & 0xffff)) + v[2] * bf2f((u16)(g.y & 0xffff));
;     o[3] = bf2f((u16)(m.y >> 16)) + v[3] * bf2f((u16)(g.y >> 16));
;     *(GAS uint2*)((u16*)(ws + W_MG) + (size_t)rl * 1024 + col) = pack4(o);
	v_lshlrev_b32_e32 v178, 16, v169
	v_and_b32_e32 v179, s18, v169
	v_lshlrev_b32_e32 v180, 16, v170
	v_and_b32_e32 v181, s18, v170
	v_lshlrev_b32_e32 v182, 16, v171
	v_and_b32_e32 v183, s18, v171
	v_pk_fma_f32 v[180:181], v[102:103], v[176:177], v[180:181]
	v_pk_fma_f32 v[182:183], v[104:105], v[178:179], v[182:183]
	v_cvt_pk_bf16_f32 v180, v180, v181
	v_cvt_pk_bf16_f32 v181, v182, v183
	global_store_dwordx2 v253, v[180:181], s[14:15]
	v_lshlrev_b32_e32 v188, 16, v172
	v_and_b32_e32 v189, s18, v172
	v_lshlrev_b32_e32 v190, 16, v173
	v_and_b32_e32 v191, s18, v173
	v_lshlrev_b32_e32 v192, 16, v174
	v_and_b32_e32 v193, s18, v174
	v_lshlrev_b32_e32 v194, 16, v175
	v_and_b32_e32 v195, s18, v175
	v_pk_fma_f32 v[192:193], v[98:99], v[188:189], v[192:193]
	v_pk_fma_f32 v[194:195], v[100:101], v[190:191], v[194:195]
	v_cvt_pk_bf16_f32 v192, v192, v193
	v_cvt_pk_bf16_f32 v193, v194, v195
	global_store_dwordx2 v253, v[192:193], s[14:15] offset:32
	global_load_dwordx2 v[144:145], v246, s[6:7]
	global_load_dwordx2 v[146:147], v250, s[12:13]
	global_load_dwordx2 v[148:149], v246, s[6:7] offset:32
	global_load_dwordx2 v[150:151], v250, s[12:13] offset:32
	global_load_dwordx2 v[152:153], v247, s[6:7]
	global_load_dwordx2 v[154:155], v251, s[12:13]
	global_load_dwordx2 v[156:157], v247, s[6:7] offset:32
	global_load_dwordx2 v[158:159], v251, s[12:13] offset:32
	global_load_dwordx2 v[160:161], v248, s[6:7]
	global_load_dwordx2 v[162:163], v252, s[12:13]
	global_load_dwordx2 v[164:165], v248, s[6:7] offset:32
	global_load_dwordx2 v[166:167], v252, s[12:13] offset:32
	global_load_dwordx2 v[168:169], v249, s[6:7]
	global_load_dwordx2 v[170:171], v253, s[12:13]
	global_load_dwordx2 v[172:173], v249, s[6:7] offset:32
	global_load_dwordx2 v[174:175], v253, s[12:13] offset:32
	s_waitcnt vmcnt(24)
	v_lshlrev_b32_e32 v176, 16, v214
	v_and_b32_e32 v177, s18, v214
	v_lshlrev_b32_e32 v178, 16, v215
	v_and_b32_e32 v179, s18, v215
	v_lshlrev_b32_e32 v180, 16, v216
	v_and_b32_e32 v181, s18, v216
	v_lshlrev_b32_e32 v182, 16, v217
	v_and_b32_e32 v183, s18, v217
	v_pk_fma_f32 v[180:181], v[94:95], v[176:177], v[180:181]
	v_pk_fma_f32 v[182:183], v[96:97], v[178:179], v[182:183]
	v_cvt_pk_bf16_f32 v180, v180, v181
	v_cvt_pk_bf16_f32 v181, v182, v183
	global_store_dwordx2 v250, v[180:181], s[14:15] offset:256
	v_lshlrev_b32_e32 v188, 16, v218
	v_and_b32_e32 v189, s18, v218
	v_lshlrev_b32_e32 v190, 16, v219
	v_and_b32_e32 v191, s18, v219
	v_lshlrev_b32_e32 v192, 16, v220
	v_and_b32_e32 v193, s18, v220
	v_lshlrev_b32_e32 v194, 16, v221
	v_and_b32_e32 v195, s18, v221
	v_pk_fma_f32 v[192:193], v[90:91], v[188:189], v[192:193]
	v_pk_fma_f32 v[194:195], v[92:93], v[190:191], v[194:195]
	v_cvt_pk_bf16_f32 v192, v192, v193
	v_cvt_pk_bf16_f32 v193, v194, v195
	global_store_dwordx2 v250, v[192:193], s[14:15] offset:288
	v_lshlrev_b32_e32 v176, 16, v222
	v_and_b32_e32 v177, s18, v222
	v_lshlrev_b32_e32 v178, 16, v223
	v_and_b32_e32 v179, s18, v223
	v_lshlrev_b32_e32 v180, 16, v224
	v_and_b32_e32 v181, s18, v224
	v_lshlrev_b32_e32 v182, 16, v225
	v_and_b32_e32 v183, s18, v225
	v_pk_fma_f32 v[180:181], v[86:87], v[176:177], v[180:181]
	v_pk_fma_f32 v[182:183], v[88:89], v[178:179], v[182:183]
	v_cvt_pk_bf16_f32 v180, v180, v181
	v_cvt_pk_bf16_f32 v181, v182, v183
	global_store_dwordx2 v251, v[180:181], s[14:15] offset:256
	v_lshlrev_b32_e32 v188, 16, v226
	v_and_b32_e32 v189, s18, v226
	v_lshlrev_b32_e32 v190, 16, v227
	v_and_b32_e32 v191, s18, v227
	v_lshlrev_b32_e32 v192, 16, v228
	v_and_b32_e32 v193, s18, v228
	v_lshlrev_b32_e32 v194, 16, v229
	v_and_b32_e32 v195, s18, v229
	v_pk_fma_f32 v[192:193], v[82:83], v[188:189], v[192:193]
	v_pk_fma_f32 v[194:195], v[84:85], v[190:191], v[194:195]
	v_cvt_pk_bf16_f32 v192, v192, v193
	v_cvt_pk_bf16_f32 v193, v194, v195
	global_store_dwordx2 v251, v[192:193], s[14:15] offset:288
	v_lshlrev_b32_e32 v176, 16, v230
	v_and_b32_e32 v177, s18, v230
	v_lshlrev_b32_e32 v178, 16, v231
	v_and_b32_e32 v179, s18, v231
	v_lshlrev_b32_e32 v180, 16, v232
	v_and_b32_e32 v181, s18, v232
	v_lshlrev_b32_e32 v182, 16, v233
	v_and_b32_e32 v183, s18, v233
	v_pk_fma_f32 v[180:181], v[78:79], v[176:177], v[180:181]
	v_pk_fma_f32 v[182:183], v[80:81], v[178:179], v[182:183]
	v_cvt_pk_bf16_f32 v180, v180, v181
	v_cvt_pk_bf16_f32 v181, v182, v183
	global_store_dwordx2 v252, v[180:181], s[14:15] offset:256
	v_lshlrev_b32_e32 v188, 16, v234
	v_and_b32_e32 v189, s18, v234
	v_lshlrev_b32_e32 v190, 16, v235
	v_and_b32_e32 v191, s18, v235
	v_lshlrev_b32_e32 v192, 16, v236
	v_and_b32_e32 v193, s18, v236
	v_lshlrev_b32_e32 v194, 16, v237
	v_and_b32_e32 v195, s18, v237
	v_pk_fma_f32 v[192:193], v[74:75], v[188:189], v[192:193]
	v_pk_fma_f32 v[194:195], v[76:77], v[190:191], v[194:195]
	v_cvt_pk_bf16_f32 v192, v192, v193
	v_cvt_pk_bf16_f32 v193, v194, v195
	global_store_dwordx2 v252, v[192:193], s[14:15] offset:288
	v_lshlrev_b32_e32 v176, 16, v238
	v_and_b32_e32 v177, s18, v238
	v_lshlrev_b32_e32 v178, 16, v239
	v_and_b32_e32 v179, s18, v239
	v_lshlrev_b32_e32 v180, 16, v240
	v_and_b32_e32 v181, s18, v240
	v_lshlrev_b32_e32 v182, 16, v241
	v_and_b32_e32 v183, s18, v241
	v_pk_fma_f32 v[180:181], v[70:71], v[176:177], v[180:181]
	v_pk_fma_f32 v[182:183], v[72:73], v[178:179], v[182:183]
	v_cvt_pk_bf16_f32 v180, v180, v181
	v_cvt_pk_bf16_f32 v181, v182, v183
	global_store_dwordx2 v253, v[180:181], s[14:15] offset:256
	v_lshlrev_b32_e32 v188, 16, v242
	v_and_b32_e32 v189, s18, v242
	v_lshlrev_b32_e32 v190, 16, v243
	v_and_b32_e32 v191, s18, v243
	v_lshlrev_b32_e32 v192, 16, v244
	v_and_b32_e32 v193, s18, v244
	v_lshlrev_b32_e32 v194, 16, v245
	v_and_b32_e32 v195, s18, v245
	v_pk_fma_f32 v[192:193], v[66:67], v[188:189], v[192:193]
	v_pk_fma_f32 v[194:195], v[68:69], v[190:191], v[194:195]
	v_cvt_pk_bf16_f32 v192, v192, v193
	v_cvt_pk_bf16_f32 v193, v194, v195
	global_store_dwordx2 v253, v[192:193], s[14:15] offset:288
	global_load_dwordx2 v[214:215], v246, s[6:7] offset:256
	global_load_dwordx2 v[216:217], v250, s[12:13] offset:256
	global_load_dwordx2 v[218:219], v246, s[6:7] offset:288
	global_load_dwordx2 v[220:221], v250, s[12:13] offset:288
	global_load_dwordx2 v[222:223], v247, s[6:7] offset:256
	global_load_dwordx2 v[224:225], v251, s[12:13] offset:256
	global_load_dwordx2 v[226:227], v247, s[6:7] offset:288
	global_load_dwordx2 v[228:229], v251, s[12:13] offset:288
	global_load_dwordx2 v[230:231], v248, s[6:7] offset:256
	global_load_dwordx2 v[232:233], v252, s[12:13] offset:256
	global_load_dwordx2 v[234:235], v248, s[6:7] offset:288
	global_load_dwordx2 v[236:237], v252, s[12:13] offset:288
	global_load_dwordx2 v[238:239], v249, s[6:7] offset:256
	global_load_dwordx2 v[240:241], v253, s[12:13] offset:256
	global_load_dwordx2 v[242:243], v249, s[6:7] offset:288
	global_load_dwordx2 v[244:245], v253, s[12:13] offset:288
	s_waitcnt vmcnt(24)
; #define GAS __attribute__((address_space(1)))
; __device__ __forceinline__ float bf2f(u16 b) { return __uint_as_float(((uint32_t)b) << 16); }
; __device__ __forceinline__ uint2 pack4(f32x4 v) { return make_uint2(pack2(v[0], v[1]), pack2(v[2], v[3])); }
; template <int MODE>
; __device__ __forceinline__ void epi_elem(char* ws, float* outp, const float* b_gate, int g0, int rl, int col, f32x4 v) {
;     ...
;   } else if (MODE == E_MG) {
;     uint2 g = *(GAS const uint2*)((const u16*)(ws + W_G) + (size_t)rl * 2048 + 1024 + col);
;     uint2 m = *(GAS const uint2*)((const u16*)(ws + W_M1) + (size_t)rl * 1024 + col);
;     f32x4 o;
;     o[0] = bf2f((u16)(m.x & 0xffff)) + v[0] * bf2f((u16)(g.x & 0xffff));
;     o[1] = bf2f((u16)(m.x >> 16)) + v[1] * bf2f((u16)(g.x >> 16));
;     o[2] = bf2f((u16)(m.y & 0xffff)) + v[2] * bf2f((u16)(g.y & 0xffff));
;     o[3] = bf2f((u16)(m.y >> 16)) + v[3] * bf2f((u16)(g.y >> 16));
;     *(GAS uint2*)((u16*)(ws + W_MG) + (size_t)rl * 1024 + col) = pack4(o);
	v_lshlrev_b32_e32 v176, 16, v144
	v_and_b32_e32 v177, s18, v144
	v_lshlrev_b32_e32 v178, 16, v145
	v_and_b32_e32 v179, s18, v145
	v_lshlrev_b32_e32 v180, 16, v146
	v_and_b32_e32 v181, s18, v146
	v_lshlrev_b32_e32 v182, 16, v147
	v_and_b32_e32 v183, s18, v147
	v_pk_fma_f32 v[180:181], v[62:63], v[176:177], v[180:181]
	v_pk_fma_f32 v[182:183], v[64:65], v[178:179], v[182:183]
	v_cvt_pk_bf16_f32 v180, v180, v181
	v_cvt_pk_bf16_f32 v181, v182, v183
	global_store_dwordx2 v250, v[180:181], s[16:17]
	v_lshlrev_b32_e32 v188, 16, v148
	v_and_b32_e32 v189, s18, v148
	v_lshlrev_b32_e32 v190, 16, v149
	v_and_b32_e32 v191, s18, v149
	v_lshlrev_b32_e32 v192, 16, v150
	v_and_b32_e32 v193, s18, v150
	v_lshlrev_b32_e32 v194, 16, v151
	v_and_b32_e32 v195, s18, v151
	v_pk_fma_f32 v[192:193], v[58:59], v[188:189], v[192:193]
	v_pk_fma_f32 v[194:195], v[60:61], v[190:191], v[194:195]
	v_cvt_pk_bf16_f32 v192, v192, v193
	v_cvt_pk_bf16_f32 v193, v194, v195
	global_store_dwordx2 v250, v[192:193], s[16:17] offset:32
	v_lshlrev_b32_e32 v176, 16, v152
	v_and_b32_e32 v177, s18, v152
	v_lshlrev_b32_e32 v178, 16, v153
	v_and_b32_e32 v179, s18, v153
	v_lshlrev_b32_e32 v180, 16, v154
	v_and_b32_e32 v181, s18, v154
	v_lshlrev_b32_e32 v182, 16, v155
	v_and_b32_e32 v183, s18, v155
	v_pk_fma_f32 v[180:181], v[54:55], v[176:177], v[180:181]
	v_pk_fma_f32 v[182:183], v[56:57], v[178:179], v[182:183]
	v_cvt_pk_bf16_f32 v180, v180, v181
	v_cvt_pk_bf16_f32 v181, v182, v183
	global_store_dwordx2 v251, v[180:181], s[16:17]
	v_lshlrev_b32_e32 v188, 16, v156
	v_and_b32_e32 v189, s18, v156
	v_lshlrev_b32_e32 v190, 16, v157
	v_and_b32_e32 v191, s18, v157
	v_lshlrev_b32_e32 v192, 16, v158
	v_and_b32_e32 v193, s18, v158
	v_lshlrev_b32_e32 v194, 16, v159
	v_and_b32_e32 v195, s18, v159
	v_pk_fma_f32 v[192:193], v[50:51], v[188:189], v[192:193]
	v_pk_fma_f32 v[194:195], v[52:53], v[190:191], v[194:195]
	v_cvt_pk_bf16_f32 v192, v192, v193
	v_cvt_pk_bf16_f32 v193, v194, v195
	global_store_dwordx2 v251, v[192:193], s[16:17] offset:32
	v_lshlrev_b32_e32 v176, 16, v160
	v_and_b32_e32 v177, s18, v160
	v_lshlrev_b32_e32 v178, 16, v161
	v_and_b32_e32 v179, s18, v161
	v_lshlrev_b32_e32 v180, 16, v162
	v_and_b32_e32 v181, s18, v162
	v_lshlrev_b32_e32 v182, 16, v163
	v_and_b32_e32 v183, s18, v163
	v_pk_fma_f32 v[180:181], v[46:47], v[176:177], v[180:181]
	v_pk_fma_f32 v[182:183], v[48:49], v[178:179], v[182:183]
	v_cvt_pk_bf16_f32 v180, v180, v181
	v_cvt_pk_bf16_f32 v181, v182, v183
	global_store_dwordx2 v252, v[180:181], s[16:17]
	v_lshlrev_b32_e32 v188, 16, v164
	v_and_b32_e32 v189, s18, v164
	v_lshlrev_b32_e32 v190, 16, v165
	v_and_b32_e32 v191, s18, v165
	v_lshlrev_b32_e32 v192, 16, v166
	v_and_b32_e32 v193, s18, v166
	v_lshlrev_b32_e32 v194, 16, v167
	v_and_b32_e32 v195, s18, v167
	v_pk_fma_f32 v[192:193], v[42:43], v[188:189], v[192:193]
	v_pk_fma_f32 v[194:195], v[44:45], v[190:191], v[194:195]
	v_cvt_pk_bf16_f32 v192, v192, v193
	v_cvt_pk_bf16_f32 v193, v194, v195
	global_store_dwordx2 v252, v[192:193], s[16:17] offset:32
	v_lshlrev_b32_e32 v176, 16, v168
	v_and_b32_e32 v177, s18, v168
	v_lshlrev_b32_e32 v178, 16, v169
	v_and_b32_e32 v179, s18, v169
	v_lshlrev_b32_e32 v180, 16, v170
	v_and_b32_e32 v181, s18, v170
	v_lshlrev_b32_e32 v182, 16, v171
	v_and_b32_e32 v183, s18, v171
	v_pk_fma_f32 v[180:181], v[38:39], v[176:177], v[180:181]
	v_pk_fma_f32 v[182:183], v[40:41], v[178:179], v[182:183]
	v_cvt_pk_bf16_f32 v180, v180, v181
	v_cvt_pk_bf16_f32 v181, v182, v183
	global_store_dwordx2 v253, v[180:181], s[16:17]
	v_lshlrev_b32_e32 v188, 16, v172
	v_and_b32_e32 v189, s18, v172
	v_lshlrev_b32_e32 v190, 16, v173
	v_and_b32_e32 v191, s18, v173
	v_lshlrev_b32_e32 v192, 16, v174
	v_and_b32_e32 v193, s18, v174
	v_lshlrev_b32_e32 v194, 16, v175
	v_and_b32_e32 v195, s18, v175
	v_pk_fma_f32 v[192:193], v[34:35], v[188:189], v[192:193]
	v_pk_fma_f32 v[194:195], v[36:37], v[190:191], v[194:195]
	v_cvt_pk_bf16_f32 v192, v192, v193
	v_cvt_pk_bf16_f32 v193, v194, v195
	global_store_dwordx2 v253, v[192:193], s[16:17] offset:32
	s_waitcnt vmcnt(8)
; #define GAS __attribute__((address_space(1)))
; __device__ __forceinline__ float bf2f(u16 b) { return __uint_as_float(((uint32_t)b) << 16); }
; __device__ __forceinline__ uint2 pack4(f32x4 v) { return make_uint2(pack2(v[0], v[1]), pack2(v[2], v[3])); }
; template <int MODE>
; __device__ __forceinline__ void epi_elem(char* ws, float* outp, const float* b_gate, int g0, int rl, int col, f32x4 v) {
;     ...
;   } else if (MODE == E_MG) {
;     uint2 g = *(GAS const uint2*)((const u16*)(ws + W_G) + (size_t)rl * 2048 + 1024 + col);
;     uint2 m = *(GAS const uint2*)((const u16*)(ws + W_M1) + (size_t)rl * 1024 + col);
;     f32x4 o;
;     o[0] = bf2f((u16)(m.x & 0xffff)) + v[0] * bf2f((u16)(g.x & 0xffff));
;     o[1] = bf2f((u16)(m.x >> 16)) + v[1] * bf2f((u16)(g.x >> 16));
;     o[2] = bf2f((u16)(m.y & 0xffff)) + v[2] * bf2f((u16)(g.y & 0xffff));
;     o[3] = bf2f((u16)(m.y >> 16)) + v[3] * bf2f((u16)(g.y >> 16));
;     *(GAS uint2*)((u16*)(ws + W_MG) + (size_t)rl * 1024 + col) = pack4(o);
	v_lshlrev_b32_e32 v176, 16, v214
	v_and_b32_e32 v177, s18, v214
	v_lshlrev_b32_e32 v178, 16, v215
	v_and_b32_e32 v179, s18, v215
	v_lshlrev_b32_e32 v180, 16, v216
	v_and_b32_e32 v181, s18, v216
	v_lshlrev_b32_e32 v182, 16, v217
	v_and_b32_e32 v183, s18, v217
	v_pk_fma_f32 v[180:181], v[30:31], v[176:177], v[180:181]
	v_pk_fma_f32 v[182:183], v[32:33], v[178:179], v[182:183]
	v_cvt_pk_bf16_f32 v180, v180, v181
	v_cvt_pk_bf16_f32 v181, v182, v183
	global_store_dwordx2 v250, v[180:181], s[16:17] offset:256
	v_lshlrev_b32_e32 v188, 16, v218
	v_and_b32_e32 v189, s18, v218
	v_lshlrev_b32_e32 v190, 16, v219
	v_and_b32_e32 v191, s18, v219
	v_lshlrev_b32_e32 v192, 16, v220
	v_and_b32_e32 v193, s18, v220
	v_lshlrev_b32_e32 v194, 16, v221
	v_and_b32_e32 v195, s18, v221
	v_pk_fma_f32 v[192:193], v[26:27], v[188:189], v[192:193]
	v_pk_fma_f32 v[194:195], v[28:29], v[190:191], v[194:195]
	v_cvt_pk_bf16_f32 v192, v192, v193
	v_cvt_pk_bf16_f32 v193, v194, v195
	global_store_dwordx2 v250, v[192:193], s[16:17] offset:288
	v_lshlrev_b32_e32 v176, 16, v222
	v_and_b32_e32 v177, s18, v222
	v_lshlrev_b32_e32 v178, 16, v223
	v_and_b32_e32 v179, s18, v223
	v_lshlrev_b32_e32 v180, 16, v224
	v_and_b32_e32 v181, s18, v224
	v_lshlrev_b32_e32 v182, 16, v225
	v_and_b32_e32 v183, s18, v225
	v_pk_fma_f32 v[180:181], v[22:23], v[176:177], v[180:181]
	v_pk_fma_f32 v[182:183], v[24:25], v[178:179], v[182:183]
	v_cvt_pk_bf16_f32 v180, v180, v181
	v_cvt_pk_bf16_f32 v181, v182, v183
	global_store_dwordx2 v251, v[180:181], s[16:17] offset:256
	v_lshlrev_b32_e32 v188, 16, v226
	v_and_b32_e32 v189, s18, v226
	v_lshlrev_b32_e32 v190, 16, v227
	v_and_b32_e32 v191, s18, v227
	v_lshlrev_b32_e32 v192, 16, v228
	v_and_b32_e32 v193, s18, v228
	v_lshlrev_b32_e32 v194, 16, v229
	v_and_b32_e32 v195, s18, v229
	v_pk_fma_f32 v[192:193], v[18:19], v[188:189], v[192:193]
	v_pk_fma_f32 v[194:195], v[20:21], v[190:191], v[194:195]
	v_cvt_pk_bf16_f32 v192, v192, v193
	v_cvt_pk_bf16_f32 v193, v194, v195
	global_store_dwordx2 v251, v[192:193], s[16:17] offset:288
	v_lshlrev_b32_e32 v176, 16, v230
	v_and_b32_e32 v177, s18, v230
	v_lshlrev_b32_e32 v178, 16, v231
	v_and_b32_e32 v179, s18, v231
	v_lshlrev_b32_e32 v180, 16, v232
	v_and_b32_e32 v181, s18, v232
	v_lshlrev_b32_e32 v182, 16, v233
	v_and_b32_e32 v183, s18, v233
	v_pk_fma_f32 v[180:181], v[14:15], v[176:177], v[180:181]
	v_pk_fma_f32 v[182:183], v[16:17], v[178:179], v[182:183]
	v_cvt_pk_bf16_f32 v180, v180, v181
	v_cvt_pk_bf16_f32 v181, v182, v183
	global_store_dwordx2 v252, v[180:181], s[16:17] offset:256
	v_lshlrev_b32_e32 v188, 16, v234
	v_and_b32_e32 v189, s18, v234
	v_lshlrev_b32_e32 v190, 16, v235
	v_and_b32_e32 v191, s18, v235
	v_lshlrev_b32_e32 v192, 16, v236
	v_and_b32_e32 v193, s18, v236
	v_lshlrev_b32_e32 v194, 16, v237
	v_and_b32_e32 v195, s18, v237
	v_pk_fma_f32 v[192:193], v[10:11], v[188:189], v[192:193]
	v_pk_fma_f32 v[194:195], v[12:13], v[190:191], v[194:195]
	v_cvt_pk_bf16_f32 v192, v192, v193
	v_cvt_pk_bf16_f32 v193, v194, v195
	global_store_dwordx2 v252, v[192:193], s[16:17] offset:288
	v_lshlrev_b32_e32 v176, 16, v238
	v_and_b32_e32 v177, s18, v238
	v_lshlrev_b32_e32 v178, 16, v239
	v_and_b32_e32 v179, s18, v239
	v_lshlrev_b32_e32 v180, 16, v240
	v_and_b32_e32 v181, s18, v240
	v_lshlrev_b32_e32 v182, 16, v241
	v_and_b32_e32 v183, s18, v241
	v_pk_fma_f32 v[180:181], v[6:7], v[176:177], v[180:181]
	v_pk_fma_f32 v[182:183], v[8:9], v[178:179], v[182:183]
	v_cvt_pk_bf16_f32 v180, v180, v181
	v_cvt_pk_bf16_f32 v181, v182, v183
	global_store_dwordx2 v253, v[180:181], s[16:17] offset:256
	v_lshlrev_b32_e32 v188, 16, v242
	v_and_b32_e32 v189, s18, v242
	v_lshlrev_b32_e32 v190, 16, v243
	v_and_b32_e32 v191, s18, v243
	v_lshlrev_b32_e32 v192, 16, v244
	v_and_b32_e32 v193, s18, v244
	v_lshlrev_b32_e32 v194, 16, v245
	v_and_b32_e32 v195, s18, v245
	v_pk_fma_f32 v[192:193], v[2:3], v[188:189], v[192:193]
	v_pk_fma_f32 v[194:195], v[4:5], v[190:191], v[194:195]
	v_cvt_pk_bf16_f32 v192, v192, v193
	v_cvt_pk_bf16_f32 v193, v194, v195
	global_store_dwordx2 v253, v[192:193], s[16:17] offset:288
	s_branch .LBB0_996

; #define GAS __attribute__((address_space(1)))
; __device__ __forceinline__ float bf2f(u16 b) { return __uint_as_float(((uint32_t)b) << 16); }
; __device__ __forceinline__ uint2 pack4(f32x4 v) { return make_uint2(pack2(v[0], v[1]), pack2(v[2], v[3])); }
; template <int MODE>
; __device__ __forceinline__ void epi_elem(char* ws, float* outp, const float* b_gate, int g0, int rl, int col, f32x4 v) {
;     ...
;   } else if (MODE == E_M1) {
;     uint2 g = *(GAS const uint2*)((const u16*)(ws + W_G) + (size_t)rl * 2048 + col);
;     f32x4 o;
;     o[0] = v[0] * bf2f((u16)(g.x & 0xffff)); o[1] = v[1] * bf2f((u16)(g.x >> 16));
;     o[2] = v[2] * bf2f((u16)(g.y & 0xffff)); o[3] = v[3] * bf2f((u16)(g.y >> 16));
;     *(GAS uint2*)((u16*)(ws + W_M1) + (size_t)rl * 1024 + col) = pack4(o);
.LBB0_971:
	s_and_b64 vcc, exec, s[12:13]
	s_cbranch_vccz .LBB0_973
	v_lshlrev_b32_e32 v141, 12, v142
	v_lshlrev_b32_e32 v143, 11, v142
	v_lshl_add_u32 v246, v140, 1, v141
	v_lshl_add_u32 v250, v140, 1, v143
	s_add_u32 s4, s2, 0x1aac0000
	s_addc_u32 s5, s3, 0
	s_add_u32 s6, s2, 0x1ab40000
	s_addc_u32 s7, s3, 0
	v_add_u32_e32 v247, 0x10000, v246
	v_add_u32_e32 v248, 0x20000, v246
	v_add_u32_e32 v249, 0x30000, v246
	s_add_u32 s8, s2, 0x2aec0000
	s_addc_u32 s9, s3, 0
	s_add_u32 s12, s2, 0x2af00000
	s_addc_u32 s13, s3, 0
	v_add_u32_e32 v251, 0x8000, v250
	v_add_u32_e32 v252, 0x10000, v250
	v_add_u32_e32 v253, 0x18000, v250
	s_mov_b32 s18, 0xffff0000
	global_load_dwordx2 v[144:145], v246, s[4:5]
	global_load_dwordx2 v[146:147], v246, s[4:5] offset:32
	global_load_dwordx2 v[148:149], v247, s[4:5]
	global_load_dwordx2 v[150:151], v247, s[4:5] offset:32
	global_load_dwordx2 v[152:153], v248, s[4:5]
	global_load_dwordx2 v[154:155], v248, s[4:5] offset:32
	global_load_dwordx2 v[156:157], v249, s[4:5]
	global_load_dwordx2 v[158:159], v249, s[4:5] offset:32
	global_load_dwordx2 v[160:161], v246, s[4:5] offset:256
	global_load_dwordx2 v[162:163], v246, s[4:5] offset:288
	global_load_dwordx2 v[164:165], v247, s[4:5] offset:256
	global_load_dwordx2 v[166:167], v247, s[4:5] offset:288
	global_load_dwordx2 v[168:169], v248, s[4:5] offset:256
	global_load_dwordx2 v[170:171], v248, s[4:5] offset:288
	global_load_dwordx2 v[172:173], v249, s[4:5] offset:256
	global_load_dwordx2 v[174:175], v249, s[4:5] offset:288
	global_load_dwordx2 v[214:215], v246, s[6:7]
	global_load_dwordx2 v[216:217], v246, s[6:7] offset:32
	global_load_dwordx2 v[218:219], v247, s[6:7]
	global_load_dwordx2 v[220:221], v247, s[6:7] offset:32
	global_load_dwordx2 v[222:223], v248, s[6:7]
	global_load_dwordx2 v[224:225], v248, s[6:7] offset:32
	global_load_dwordx2 v[226:227], v249, s[6:7]
	global_load_dwordx2 v[228:229], v249, s[6:7] offset:32
	global_load_dwordx2 v[230:231], v246, s[6:7] offset:256
	global_load_dwordx2 v[232:233], v246, s[6:7] offset:288
	global_load_dwordx2 v[234:235], v247, s[6:7] offset:256
	global_load_dwordx2 v[236:237], v247, s[6:7] offset:288
	global_load_dwordx2 v[238:239], v248, s[6:7] offset:256
	global_load_dwordx2 v[240:241], v248, s[6:7] offset:288
	global_load_dwordx2 v[242:243], v249, s[6:7] offset:256
	global_load_dwordx2 v[244:245], v249, s[6:7] offset:288
	s_waitcnt vmcnt(24)
	v_lshlrev_b32_e32 v176, 16, v144
	v_and_b32_e32 v177, s18, v144
	v_lshlrev_b32_e32 v178, 16, v145
	v_and_b32_e32 v179, s18, v145
	v_pk_mul_f32 v[176:177], v[126:127], v[176:177]
	v_pk_mul_f32 v[178:179], v[128:129], v[178:179]
	v_cvt_pk_bf16_f32 v176, v176, v177
	v_cvt_pk_bf16_f32 v177, v178, v179
	global_store_dwordx2 v250, v[176:177], s[8:9]
	v_lshlrev_b32_e32 v180, 16, v146
	v_and_b32_e32 v181, s18, v146
	v_lshlrev_b32_e32 v182, 16, v147
	v_and_b32_e32 v183, s18, v147
	v_pk_mul_f32 v[180:181], v[122:123], v[180:181]
	v_pk_mul_f32 v[182:183], v[124:125], v[182:183]
	v_cvt_pk_bf16_f32 v180, v180, v181
	v_cvt_pk_bf16_f32 v181, v182, v183
	global_store_dwordx2 v250, v[180:181], s[8:9] offset:32
	v_lshlrev_b32_e32 v188, 16, v148
	v_and_b32_e32 v189, s18, v148
	v_lshlrev_b32_e32 v190, 16, v149
	v_and_b32_e32 v191, s18, v149
	v_pk_mul_f32 v[188:189], v[118:119], v[188:189]
	v_pk_mul_f32 v[190:191], v[120:121], v[190:191]
	v_cvt_pk_bf16_f32 v188, v188, v189
	v_cvt_pk_bf16_f32 v189, v190, v191
	global_store_dwordx2 v251, v[188:189], s[8:9]
	v_lshlrev_b32_e32 v192, 16, v150
	v_and_b32_e32 v193, s18, v150
	v_lshlrev_b32_e32 v194, 16, v151
	v_and_b32_e32 v195, s18, v151
	v_pk_mul_f32 v[192:193], v[114:115], v[192:193]
	v_pk_mul_f32 v[194:195], v[116:117], v[194:195]
	v_cvt_pk_bf16_f32 v192, v192, v193
	v_cvt_pk_bf16_f32 v193, v194, v195
	global_store_dwordx2 v251, v[192:193], s[8:9] offset:32
	v_lshlrev_b32_e32 v176, 16, v152
	v_and_b32_e32 v177, s18, v152
	v_lshlrev_b32_e32 v178, 16, v153
	v_and_b32_e32 v179, s18, v153
	v_pk_mul_f32 v[176:177], v[110:111], v[176:177]
	v_pk_mul_f32 v[178:179], v[112:113], v[178:179]
	v_cvt_pk_bf16_f32 v176, v176, v177
	v_cvt_pk_bf16_f32 v177, v178, v179
	global_store_dwordx2 v252, v[176:177], s[8:9]
	v_lshlrev_b32_e32 v180, 16, v154
	v_and_b32_e32 v181, s18, v154
	v_lshlrev_b32_e32 v182, 16, v155
	v_and_b32_e32 v183, s18, v155
	v_pk_mul_f32 v[180:181], v[106:107], v[180:181]
	v_pk_mul_f32 v[182:183], v[108:109], v[182:183]
	v_cvt_pk_bf16_f32 v180, v180, v181
	v_cvt_pk_bf16_f32 v181, v182, v183
	global_store_dwordx2 v252, v[180:181], s[8:9] offset:32
	v_lshlrev_b32_e32 v188, 16, v156
	v_and_b32_e32 v189, s18, v156
	v_lshlrev_b32_e32 v190, 16, v157
	v_and_b32_e32 v191, s18, v157
	v_pk_mul_f32 v[188:189], v[102:103], v[188:189]
	v_pk_mul_f32 v[190:191], v[104:105], v[190:191]
	v_cvt_pk_bf16_f32 v188, v188, v189
	v_cvt_pk_bf16_f32 v189, v190, v191
	global_store_dwordx2 v253, v[188:189], s[8:9]
	v_lshlrev_b32_e32 v192, 16, v158
	v_and_b32_e32 v193, s18, v158
	v_lshlrev_b32_e32 v194, 16, v159
	v_and_b32_e32 v195, s18, v159
	v_pk_mul_f32 v[192:193], v[98:99], v[192:193]
	v_pk_mul_f32 v[194:195], v[100:101], v[194:195]
	v_cvt_pk_bf16_f32 v192, v192, v193
	v_cvt_pk_bf16_f32 v193, v194, v195
	global_store_dwordx2 v253, v[192:193], s[8:9] offset:32
	s_waitcnt vmcnt(24)
; #define GAS __attribute__((address_space(1)))
; __device__ __forceinline__ float bf2f(u16 b) { return __uint_as_float(((uint32_t)b) << 16); }
; __device__ __forceinline__ uint2 pack4(f32x4 v) { return make_uint2(pack2(v[0], v[1]), pack2(v[2], v[3])); }
; template <int MODE>
; __device__ __forceinline__ void epi_elem(char* ws, float* outp, const float* b_gate, int g0, int rl, int col, f32x4 v) {
;     ...
;   } else if (MODE == E_M1) {
;     uint2 g = *(GAS const uint2*)((const u16*)(ws + W_G) + (size_t)rl * 2048 + col);
;     f32x4 o;
;     o[0] = v[0] * bf2f((u16)(g.x & 0xffff)); o[1] = v[1] * bf2f((u16)(g.x >> 16));
;     o[2] = v[2] * bf2f((u16)(g.y & 0xffff)); o[3] = v[3] * bf2f((u16)(g.y >> 16));
;     *(GAS uint2*)((u16*)(ws + W_M1) + (size_t)rl * 1024 + col) = pack4(o);
	v_lshlrev_b32_e32 v176, 16, v160
	v_and_b32_e32 v177, s18, v160
	v_lshlrev_b32_e32 v178, 16, v161
	v_and_b32_e32 v179, s18, v161
	v_pk_mul_f32 v[176:177], v[94:95], v[176:177]
	v_pk_mul_f32 v[178:179], v[96:97], v[178:179]
	v_cvt_pk_bf16_f32 v176, v176, v177
	v_cvt_pk_bf16_f32 v177, v178, v179
	global_store_dwordx2 v250, v[176:177], s[8:9] offset:256
	v_lshlrev_b32_e32 v180, 16, v162
	v_and_b32_e32 v181, s18, v162
	v_lshlrev_b32_e32 v182, 16, v163
	v_and_b32_e32 v183, s18, v163
	v_pk_mul_f32 v[180:181], v[90:91], v[180:181]
	v_pk_mul_f32 v[182:183], v[92:93], v[182:183]
	v_cvt_pk_bf16_f32 v180, v180, v181
	v_cvt_pk_bf16_f32 v181, v182, v183
	global_store_dwordx2 v250, v[180:181], s[8:9] offset:288
	v_lshlrev_b32_e32 v188, 16, v164
	v_and_b32_e32 v189, s18, v164
	v_lshlrev_b32_e32 v190, 16, v165
	v_and_b32_e32 v191, s18, v165
	v_pk_mul_f32 v[188:189], v[86:87], v[188:189]
	v_pk_mul_f32 v[190:191], v[88:89], v[190:191]
	v_cvt_pk_bf16_f32 v188, v188, v189
	v_cvt_pk_bf16_f32 v189, v190, v191
	global_store_dwordx2 v251, v[188:189], s[8:9] offset:256
	v_lshlrev_b32_e32 v192, 16, v166
	v_and_b32_e32 v193, s18, v166
	v_lshlrev_b32_e32 v194, 16, v167
	v_and_b32_e32 v195, s18, v167
	v_pk_mul_f32 v[192:193], v[82:83], v[192:193]
	v_pk_mul_f32 v[194:195], v[84:85], v[194:195]
	v_cvt_pk_bf16_f32 v192, v192, v193
	v_cvt_pk_bf16_f32 v193, v194, v195
	global_store_dwordx2 v251, v[192:193], s[8:9] offset:288
	v_lshlrev_b32_e32 v176, 16, v168
	v_and_b32_e32 v177, s18, v168
	v_lshlrev_b32_e32 v178, 16, v169
	v_and_b32_e32 v179, s18, v169
	v_pk_mul_f32 v[176:177], v[78:79], v[176:177]
	v_pk_mul_f32 v[178:179], v[80:81], v[178:179]
	v_cvt_pk_bf16_f32 v176, v176, v177
	v_cvt_pk_bf16_f32 v177, v178, v179
	global_store_dwordx2 v252, v[176:177], s[8:9] offset:256
	v_lshlrev_b32_e32 v180, 16, v170
	v_and_b32_e32 v181, s18, v170
	v_lshlrev_b32_e32 v182, 16, v171
	v_and_b32_e32 v183, s18, v171
	v_pk_mul_f32 v[180:181], v[74:75], v[180:181]
	v_pk_mul_f32 v[182:183], v[76:77], v[182:183]
	v_cvt_pk_bf16_f32 v180, v180, v181
	v_cvt_pk_bf16_f32 v181, v182, v183
	global_store_dwordx2 v252, v[180:181], s[8:9] offset:288
	v_lshlrev_b32_e32 v188, 16, v172
	v_and_b32_e32 v189, s18, v172
	v_lshlrev_b32_e32 v190, 16, v173
	v_and_b32_e32 v191, s18, v173
	v_pk_mul_f32 v[188:189], v[70:71], v[188:189]
	v_pk_mul_f32 v[190:191], v[72:73], v[190:191]
	v_cvt_pk_bf16_f32 v188, v188, v189
	v_cvt_pk_bf16_f32 v189, v190, v191
	global_store_dwordx2 v253, v[188:189], s[8:9] offset:256
	v_lshlrev_b32_e32 v192, 16, v174
	v_and_b32_e32 v193, s18, v174
	v_lshlrev_b32_e32 v194, 16, v175
	v_and_b32_e32 v195, s18, v175
	v_pk_mul_f32 v[192:193], v[66:67], v[192:193]
	v_pk_mul_f32 v[194:195], v[68:69], v[194:195]
	v_cvt_pk_bf16_f32 v192, v192, v193
	v_cvt_pk_bf16_f32 v193, v194, v195
	global_store_dwordx2 v253, v[192:193], s[8:9] offset:288
	s_waitcnt vmcnt(24)
	v_lshlrev_b32_e32 v176, 16, v214
	v_and_b32_e32 v177, s18, v214
	v_lshlrev_b32_e32 v178, 16, v215
	v_and_b32_e32 v179, s18, v215
	v_pk_mul_f32 v[176:177], v[62:63], v[176:177]
	v_pk_mul_f32 v[178:179], v[64:65], v[178:179]
	v_cvt_pk_bf16_f32 v176, v176, v177
	v_cvt_pk_bf16_f32 v177, v178, v179
	global_store_dwordx2 v250, v[176:177], s[12:13]
	v_lshlrev_b32_e32 v180, 16, v216
	v_and_b32_e32 v181, s18, v216
	v_lshlrev_b32_e32 v182, 16, v217
	v_and_b32_e32 v183, s18, v217
	v_pk_mul_f32 v[180:181], v[58:59], v[180:181]
	v_pk_mul_f32 v[182:183], v[60:61], v[182:183]
	v_cvt_pk_bf16_f32 v180, v180, v181
	v_cvt_pk_bf16_f32 v181, v182, v183
	global_store_dwordx2 v250, v[180:181], s[12:13] offset:32
	v_lshlrev_b32_e32 v188, 16, v218
	v_and_b32_e32 v189, s18, v218
	v_lshlrev_b32_e32 v190, 16, v219
	v_and_b32_e32 v191, s18, v219
	v_pk_mul_f32 v[188:189], v[54:55], v[188:189]
	v_pk_mul_f32 v[190:191], v[56:57], v[190:191]
	v_cvt_pk_bf16_f32 v188, v188, v189
	v_cvt_pk_bf16_f32 v189, v190, v191
	global_store_dwordx2 v251, v[188:189], s[12:13]
	v_lshlrev_b32_e32 v192, 16, v220
	v_and_b32_e32 v193, s18, v220
	v_lshlrev_b32_e32 v194, 16, v221
	v_and_b32_e32 v195, s18, v221
	v_pk_mul_f32 v[192:193], v[50:51], v[192:193]
	v_pk_mul_f32 v[194:195], v[52:53], v[194:195]
	v_cvt_pk_bf16_f32 v192, v192, v193
	v_cvt_pk_bf16_f32 v193, v194, v195
	global_store_dwordx2 v251, v[192:193], s[12:13] offset:32
	v_lshlrev_b32_e32 v176, 16, v222
	v_and_b32_e32 v177, s18, v222
	v_lshlrev_b32_e32 v178, 16, v223
	v_and_b32_e32 v179, s18, v223
	v_pk_mul_f32 v[176:177], v[46:47], v[176:177]
	v_pk_mul_f32 v[178:179], v[48:49], v[178:179]
	v_cvt_pk_bf16_f32 v176, v176, v177
	v_cvt_pk_bf16_f32 v177, v178, v179
	global_store_dwordx2 v252, v[176:177], s[12:13]
	v_lshlrev_b32_e32 v180, 16, v224
	v_and_b32_e32 v181, s18, v224
	v_lshlrev_b32_e32 v182, 16, v225
	v_and_b32_e32 v183, s18, v225
	v_pk_mul_f32 v[180:181], v[42:43], v[180:181]
	v_pk_mul_f32 v[182:183], v[44:45], v[182:183]
	v_cvt_pk_bf16_f32 v180, v180, v181
	v_cvt_pk_bf16_f32 v181, v182, v183
	global_store_dwordx2 v252, v[180:181], s[12:13] offset:32
	v_lshlrev_b32_e32 v188, 16, v226
	v_and_b32_e32 v189, s18, v226
	v_lshlrev_b32_e32 v190, 16, v227
	v_and_b32_e32 v191, s18, v227
	v_pk_mul_f32 v[188:189], v[38:39], v[188:189]
	v_pk_mul_f32 v[190:191], v[40:41], v[190:191]
	v_cvt_pk_bf16_f32 v188, v188, v189
	v_cvt_pk_bf16_f32 v189, v190, v191
	global_store_dwordx2 v253, v[188:189], s[12:13]
	v_lshlrev_b32_e32 v192, 16, v228
	v_and_b32_e32 v193, s18, v228
	v_lshlrev_b32_e32 v194, 16, v229
	v_and_b32_e32 v195, s18, v229
	v_pk_mul_f32 v[192:193], v[34:35], v[192:193]
	v_pk_mul_f32 v[194:195], v[36:37], v[194:195]
	v_cvt_pk_bf16_f32 v192, v192, v193
	v_cvt_pk_bf16_f32 v193, v194, v195
	global_store_dwordx2 v253, v[192:193], s[12:13] offset:32
	s_waitcnt vmcnt(24)
; #define GAS __attribute__((address_space(1)))
; __device__ __forceinline__ float bf2f(u16 b) { return __uint_as_float(((uint32_t)b) << 16); }
; __device__ __forceinline__ uint2 pack4(f32x4 v) { return make_uint2(pack2(v[0], v[1]), pack2(v[2], v[3])); }
; template <int MODE>
; __device__ __forceinline__ void epi_elem(char* ws, float* outp, const float* b_gate, int g0, int rl, int col, f32x4 v) {
;     ...
;   } else if (MODE == E_M1) {
;     uint2 g = *(GAS const uint2*)((const u16*)(ws + W_G) + (size_t)rl * 2048 + col);
;     f32x4 o;
;     o[0] = v[0] * bf2f((u16)(g.x & 0xffff)); o[1] = v[1] * bf2f((u16)(g.x >> 16));
;     o[2] = v[2] * bf2f((u16)(g.y & 0xffff)); o[3] = v[3] * bf2f((u16)(g.y >> 16));
;     *(GAS uint2*)((u16*)(ws + W_M1) + (size_t)rl * 1024 + col) = pack4(o);
	v_lshlrev_b32_e32 v176, 16, v230
	v_and_b32_e32 v177, s18, v230
	v_lshlrev_b32_e32 v178, 16, v231
	v_and_b32_e32 v179, s18, v231
	v_pk_mul_f32 v[176:177], v[30:31], v[176:177]
	v_pk_mul_f32 v[178:179], v[32:33], v[178:179]
	v_cvt_pk_bf16_f32 v176, v176, v177
	v_cvt_pk_bf16_f32 v177, v178, v179
	global_store_dwordx2 v250, v[176:177], s[12:13] offset:256
	v_lshlrev_b32_e32 v180, 16, v232
	v_and_b32_e32 v181, s18, v232
	v_lshlrev_b32_e32 v182, 16, v233
	v_and_b32_e32 v183, s18, v233
	v_pk_mul_f32 v[180:181], v[26:27], v[180:181]
	v_pk_mul_f32 v[182:183], v[28:29], v[182:183]
	v_cvt_pk_bf16_f32 v180, v180, v181
	v_cvt_pk_bf16_f32 v181, v182, v183
	global_store_dwordx2 v250, v[180:181], s[12:13] offset:288
	v_lshlrev_b32_e32 v188, 16, v234
	v_and_b32_e32 v189, s18, v234
	v_lshlrev_b32_e32 v190, 16, v235
	v_and_b32_e32 v191, s18, v235
	v_pk_mul_f32 v[188:189], v[22:23], v[188:189]
	v_pk_mul_f32 v[190:191], v[24:25], v[190:191]
	v_cvt_pk_bf16_f32 v188, v188, v189
	v_cvt_pk_bf16_f32 v189, v190, v191
	global_store_dwordx2 v251, v[188:189], s[12:13] offset:256
	v_lshlrev_b32_e32 v192, 16, v236
	v_and_b32_e32 v193, s18, v236
	v_lshlrev_b32_e32 v194, 16, v237
	v_and_b32_e32 v195, s18, v237
	v_pk_mul_f32 v[192:193], v[18:19], v[192:193]
	v_pk_mul_f32 v[194:195], v[20:21], v[194:195]
	v_cvt_pk_bf16_f32 v192, v192, v193
	v_cvt_pk_bf16_f32 v193, v194, v195
	global_store_dwordx2 v251, v[192:193], s[12:13] offset:288
	v_lshlrev_b32_e32 v176, 16, v238
	v_and_b32_e32 v177, s18, v238
	v_lshlrev_b32_e32 v178, 16, v239
	v_and_b32_e32 v179, s18, v239
	v_pk_mul_f32 v[176:177], v[14:15], v[176:177]
	v_pk_mul_f32 v[178:179], v[16:17], v[178:179]
	v_cvt_pk_bf16_f32 v176, v176, v177
	v_cvt_pk_bf16_f32 v177, v178, v179
	global_store_dwordx2 v252, v[176:177], s[12:13] offset:256
	v_lshlrev_b32_e32 v180, 16, v240
	v_and_b32_e32 v181, s18, v240
	v_lshlrev_b32_e32 v182, 16, v241
	v_and_b32_e32 v183, s18, v241
	v_pk_mul_f32 v[180:181], v[10:11], v[180:181]
	v_pk_mul_f32 v[182:183], v[12:13], v[182:183]
	v_cvt_pk_bf16_f32 v180, v180, v181
	v_cvt_pk_bf16_f32 v181, v182, v183
	global_store_dwordx2 v252, v[180:181], s[12:13] offset:288
	v_lshlrev_b32_e32 v188, 16, v242
	v_and_b32_e32 v189, s18, v242
	v_lshlrev_b32_e32 v190, 16, v243
	v_and_b32_e32 v191, s18, v243
	v_pk_mul_f32 v[188:189], v[6:7], v[188:189]
	v_pk_mul_f32 v[190:191], v[8:9], v[190:191]
	v_cvt_pk_bf16_f32 v188, v188, v189
	v_cvt_pk_bf16_f32 v189, v190, v191
	global_store_dwordx2 v253, v[188:189], s[12:13] offset:256
	v_lshlrev_b32_e32 v192, 16, v244
	v_and_b32_e32 v193, s18, v244
	v_lshlrev_b32_e32 v194, 16, v245
	v_and_b32_e32 v195, s18, v245
	v_pk_mul_f32 v[192:193], v[2:3], v[192:193]
	v_pk_mul_f32 v[194:195], v[4:5], v[194:195]
	v_cvt_pk_bf16_f32 v192, v192, v193
	v_cvt_pk_bf16_f32 v193, v194, v195
	global_store_dwordx2 v253, v[192:193], s[12:13] offset:288
	s_branch .LBB0_996

; #define GAS __attribute__((address_space(1)))
; __device__ __forceinline__ uint2 pack4(f32x4 v) { return make_uint2(pack2(v[0], v[1]), pack2(v[2], v[3])); }
; __device__ __forceinline__ float sigmoid_f(float x) { return __builtin_amdgcn_rcpf(1.0f + __builtin_amdgcn_exp2f(x * -1.4426950408889634f)); }
; template <int MODE>
; __device__ __forceinline__ void epi_elem(char* ws, float* outp, const float* b_gate, int g0, int rl, int col, f32x4 v) {
;     ...
;   } else if (MODE == E_G) {
;     int gc = col - 5120;
;     float4 bg = *(GAS const float4*)(b_gate + gc);
;     f32x4 o;
;     o[0] = sigmoid_f(v[0] + bg.x); o[1] = sigmoid_f(v[1] + bg.y); o[2] = sigmoid_f(v[2] + bg.z); o[3] = sigmoid_f(v[3] + bg.w);
;     *(GAS uint2*)((u16*)(ws + W_G) + (size_t)rl * 2048 + gc) = pack4(o);
.LBB0_974:
	s_and_b64 vcc, exec, s[12:13]
	s_cbranch_vccz .LBB0_979
	s_cmp_gt_i32 s16, 4
	s_mov_b64 s[12:13], -1
	s_cbranch_scc0 .LBB0_977
	v_add_u32_e32 v141, 0xffffec00, v140
	v_lshlrev_b32_e32 v143, 2, v141
	v_lshlrev_b32_e32 v246, 12, v142
	global_load_dwordx4 v[144:147], v143, s[10:11]
	global_load_dwordx4 v[148:151], v143, s[10:11] offset:64
	global_load_dwordx4 v[152:155], v143, s[10:11] offset:512
	global_load_dwordx4 v[156:159], v143, s[10:11] offset:576
	v_lshl_add_u32 v246, v141, 1, v246
	s_add_u32 s4, s2, 0x1aac0000
	s_addc_u32 s5, s3, 0
	s_add_u32 s6, s2, 0x1ab40000
	s_addc_u32 s7, s3, 0
	v_add_u32_e32 v247, 0x10000, v246
	v_add_u32_e32 v248, 0x20000, v246
	v_add_u32_e32 v249, 0x30000, v246
	s_mov_b32 s18, 0xbfb8aa3b
	s_waitcnt vmcnt(0)
	v_add_f32_e32 v160, v126, v144
	v_add_f32_e32 v161, v127, v145
	v_add_f32_e32 v162, v128, v146
	v_add_f32_e32 v163, v129, v147
	v_mul_f32_e32 v160, s18, v160
	v_mul_f32_e32 v161, s18, v161
	v_mul_f32_e32 v162, s18, v162
	v_mul_f32_e32 v163, s18, v163
	v_exp_f32_e32 v160, v160
	v_exp_f32_e32 v161, v161
	v_exp_f32_e32 v162, v162
	v_exp_f32_e32 v163, v163
	v_add_f32_e32 v160, 1.0, v160
	v_add_f32_e32 v161, 1.0, v161
	v_add_f32_e32 v162, 1.0, v162
	v_add_f32_e32 v163, 1.0, v163
	v_rcp_f32_e32 v160, v160
	v_rcp_f32_e32 v161, v161
	v_rcp_f32_e32 v162, v162
	v_rcp_f32_e32 v163, v163
	v_cvt_pk_bf16_f32 v160, v160, v161
	v_cvt_pk_bf16_f32 v161, v162, v163
	global_store_dwordx2 v246, v[160:161], s[4:5]
	v_add_f32_e32 v164, v122, v148
	v_add_f32_e32 v165, v123, v149
	v_add_f32_e32 v166, v124, v150
	v_add_f32_e32 v167, v125, v151
	v_mul_f32_e32 v164, s18, v164
	v_mul_f32_e32 v165, s18, v165
	v_mul_f32_e32 v166, s18, v166
	v_mul_f32_e32 v167, s18, v167
	v_exp_f32_e32 v164, v164
	v_exp_f32_e32 v165, v165
	v_exp_f32_e32 v166, v166
	v_exp_f32_e32 v167, v167
	v_add_f32_e32 v164, 1.0, v164
	v_add_f32_e32 v165, 1.0, v165
	v_add_f32_e32 v166, 1.0, v166
	v_add_f32_e32 v167, 1.0, v167
	v_rcp_f32_e32 v164, v164
	v_rcp_f32_e32 v165, v165
	v_rcp_f32_e32 v166, v166
	v_rcp_f32_e32 v167, v167
	v_cvt_pk_bf16_f32 v164, v164, v165
	v_cvt_pk_bf16_f32 v165, v166, v167
	global_store_dwordx2 v246, v[164:165], s[4:5] offset:32
	v_add_f32_e32 v168, v118, v144
	v_add_f32_e32 v169, v119, v145
	v_add_f32_e32 v170, v120, v146
	v_add_f32_e32 v171, v121, v147
	v_mul_f32_e32 v168, s18, v168
	v_mul_f32_e32 v169, s18, v169
	v_mul_f32_e32 v170, s18, v170
	v_mul_f32_e32 v171, s18, v171
	v_exp_f32_e32 v168, v168
	v_exp_f32_e32 v169, v169
	v_exp_f32_e32 v170, v170
	v_exp_f32_e32 v171, v171
	v_add_f32_e32 v168, 1.0, v168
	v_add_f32_e32 v169, 1.0, v169
	v_add_f32_e32 v170, 1.0, v170
	v_add_f32_e32 v171, 1.0, v171
	v_rcp_f32_e32 v168, v168
	v_rcp_f32_e32 v169, v169
	v_rcp_f32_e32 v170, v170
	v_rcp_f32_e32 v171, v171
	v_cvt_pk_bf16_f32 v168, v168, v169
	v_cvt_pk_bf16_f32 v169, v170, v171
	global_store_dwordx2 v247, v[168:169], s[4:5]
	v_add_f32_e32 v172, v114, v148
	v_add_f32_e32 v173, v115, v149
	v_add_f32_e32 v174, v116, v150
	v_add_f32_e32 v175, v117, v151
	v_mul_f32_e32 v172, s18, v172
	v_mul_f32_e32 v173, s18, v173
	v_mul_f32_e32 v174, s18, v174
	v_mul_f32_e32 v175, s18, v175
	v_exp_f32_e32 v172, v172
	v_exp_f32_e32 v173, v173
	v_exp_f32_e32 v174, v174
	v_exp_f32_e32 v175, v175
	v_add_f32_e32 v172, 1.0, v172
	v_add_f32_e32 v173, 1.0, v173
	v_add_f32_e32 v174, 1.0, v174
	v_add_f32_e32 v175, 1.0, v175
	v_rcp_f32_e32 v172, v172
	v_rcp_f32_e32 v173, v173
	v_rcp_f32_e32 v174, v174
	v_rcp_f32_e32 v175, v175
	v_cvt_pk_bf16_f32 v172, v172, v173
	v_cvt_pk_bf16_f32 v173, v174, v175
	global_store_dwordx2 v247, v[172:173], s[4:5] offset:32
	v_add_f32_e32 v160, v110, v144
	v_add_f32_e32 v161, v111, v145
	v_add_f32_e32 v162, v112, v146
	v_add_f32_e32 v163, v113, v147
	v_mul_f32_e32 v160, s18, v160
	v_mul_f32_e32 v161, s18, v161
	v_mul_f32_e32 v162, s18, v162
	v_mul_f32_e32 v163, s18, v163
	v_exp_f32_e32 v160, v160
	v_exp_f32_e32 v161, v161
	v_exp_f32_e32 v162, v162
	v_exp_f32_e32 v163, v163
	v_add_f32_e32 v160, 1.0, v160
	v_add_f32_e32 v161, 1.0, v161
	v_add_f32_e32 v162, 1.0, v162
	v_add_f32_e32 v163, 1.0, v163
	v_rcp_f32_e32 v160, v160
	v_rcp_f32_e32 v161, v161
	v_rcp_f32_e32 v162, v162
	v_rcp_f32_e32 v163, v163
	v_cvt_pk_bf16_f32 v160, v160, v161
	v_cvt_pk_bf16_f32 v161, v162, v163
	global_store_dwordx2 v248, v[160:161], s[4:5]
	v_add_f32_e32 v164, v106, v148
	v_add_f32_e32 v165, v107, v149
	v_add_f32_e32 v166, v108, v150
	v_add_f32_e32 v167, v109, v151
	v_mul_f32_e32 v164, s18, v164
	v_mul_f32_e32 v165, s18, v165
	v_mul_f32_e32 v166, s18, v166
	v_mul_f32_e32 v167, s18, v167
	v_exp_f32_e32 v164, v164
	v_exp_f32_e32 v165, v165
	v_exp_f32_e32 v166, v166
	v_exp_f32_e32 v167, v167
	v_add_f32_e32 v164, 1.0, v164
	v_add_f32_e32 v165, 1.0, v165
	v_add_f32_e32 v166, 1.0, v166
	v_add_f32_e32 v167, 1.0, v167
	v_rcp_f32_e32 v164, v164
	v_rcp_f32_e32 v165, v165
	v_rcp_f32_e32 v166, v166
	v_rcp_f32_e32 v167, v167
	v_cvt_pk_bf16_f32 v164, v164, v165
	v_cvt_pk_bf16_f32 v165, v166, v167
	global_store_dwordx2 v248, v[164:165], s[4:5] offset:32
	v_add_f32_e32 v168, v102, v144
	v_add_f32_e32 v169, v103, v145
	v_add_f32_e32 v170, v104, v146
	v_add_f32_e32 v171, v105, v147
	v_mul_f32_e32 v168, s18, v168
	v_mul_f32_e32 v169, s18, v169
	v_mul_f32_e32 v170, s18, v170
	v_mul_f32_e32 v171, s18, v171
	v_exp_f32_e32 v168, v168
	v_exp_f32_e32 v169, v169
	v_exp_f32_e32 v170, v170
	v_exp_f32_e32 v171, v171
	v_add_f32_e32 v168, 1.0, v168
	v_add_f32_e32 v169, 1.0, v169
	v_add_f32_e32 v170, 1.0, v170
	v_add_f32_e32 v171, 1.0, v171
	v_rcp_f32_e32 v168, v168
	v_rcp_f32_e32 v169, v169
	v_rcp_f32_e32 v170, v170
	v_rcp_f32_e32 v171, v171
	v_cvt_pk_bf16_f32 v168, v168, v169
; #define GAS __attribute__((address_space(1)))
; __device__ __forceinline__ uint2 pack4(f32x4 v) { return make_uint2(pack2(v[0], v[1]), pack2(v[2], v[3])); }
; __device__ __forceinline__ float sigmoid_f(float x) { return __builtin_amdgcn_rcpf(1.0f + __builtin_amdgcn_exp2f(x * -1.4426950408889634f)); }
; template <int MODE>
; __device__ __forceinline__ void epi_elem(char* ws, float* outp, const float* b_gate, int g0, int rl, int col, f32x4 v) {
;     ...
;   } else if (MODE == E_G) {
;     int gc = col - 5120;
;     float4 bg = *(GAS const float4*)(b_gate + gc);
;     f32x4 o;
;     o[0] = sigmoid_f(v[0] + bg.x); o[1] = sigmoid_f(v[1] + bg.y); o[2] = sigmoid_f(v[2] + bg.z); o[3] = sigmoid_f(v[3] + bg.w);
;     *(GAS uint2*)((u16*)(ws + W_G) + (size_t)rl * 2048 + gc) = pack4(o);
	v_cvt_pk_bf16_f32 v169, v170, v171
	global_store_dwordx2 v249, v[168:169], s[4:5]
	v_add_f32_e32 v172, v98, v148
	v_add_f32_e32 v173, v99, v149
	v_add_f32_e32 v174, v100, v150
	v_add_f32_e32 v175, v101, v151
	v_mul_f32_e32 v172, s18, v172
	v_mul_f32_e32 v173, s18, v173
	v_mul_f32_e32 v174, s18, v174
	v_mul_f32_e32 v175, s18, v175
	v_exp_f32_e32 v172, v172
	v_exp_f32_e32 v173, v173
	v_exp_f32_e32 v174, v174
	v_exp_f32_e32 v175, v175
	v_add_f32_e32 v172, 1.0, v172
	v_add_f32_e32 v173, 1.0, v173
	v_add_f32_e32 v174, 1.0, v174
	v_add_f32_e32 v175, 1.0, v175
	v_rcp_f32_e32 v172, v172
	v_rcp_f32_e32 v173, v173
	v_rcp_f32_e32 v174, v174
	v_rcp_f32_e32 v175, v175
	v_cvt_pk_bf16_f32 v172, v172, v173
	v_cvt_pk_bf16_f32 v173, v174, v175
	global_store_dwordx2 v249, v[172:173], s[4:5] offset:32
	v_add_f32_e32 v160, v94, v152
	v_add_f32_e32 v161, v95, v153
	v_add_f32_e32 v162, v96, v154
	v_add_f32_e32 v163, v97, v155
	v_mul_f32_e32 v160, s18, v160
	v_mul_f32_e32 v161, s18, v161
	v_mul_f32_e32 v162, s18, v162
	v_mul_f32_e32 v163, s18, v163
	v_exp_f32_e32 v160, v160
	v_exp_f32_e32 v161, v161
	v_exp_f32_e32 v162, v162
	v_exp_f32_e32 v163, v163
	v_add_f32_e32 v160, 1.0, v160
	v_add_f32_e32 v161, 1.0, v161
	v_add_f32_e32 v162, 1.0, v162
	v_add_f32_e32 v163, 1.0, v163
	v_rcp_f32_e32 v160, v160
	v_rcp_f32_e32 v161, v161
	v_rcp_f32_e32 v162, v162
	v_rcp_f32_e32 v163, v163
	v_cvt_pk_bf16_f32 v160, v160, v161
	v_cvt_pk_bf16_f32 v161, v162, v163
	global_store_dwordx2 v246, v[160:161], s[4:5] offset:256
	v_add_f32_e32 v164, v90, v156
	v_add_f32_e32 v165, v91, v157
	v_add_f32_e32 v166, v92, v158
	v_add_f32_e32 v167, v93, v159
	v_mul_f32_e32 v164, s18, v164
	v_mul_f32_e32 v165, s18, v165
	v_mul_f32_e32 v166, s18, v166
	v_mul_f32_e32 v167, s18, v167
	v_exp_f32_e32 v164, v164
	v_exp_f32_e32 v165, v165
	v_exp_f32_e32 v166, v166
	v_exp_f32_e32 v167, v167
	v_add_f32_e32 v164, 1.0, v164
	v_add_f32_e32 v165, 1.0, v165
	v_add_f32_e32 v166, 1.0, v166
	v_add_f32_e32 v167, 1.0, v167
	v_rcp_f32_e32 v164, v164
	v_rcp_f32_e32 v165, v165
	v_rcp_f32_e32 v166, v166
	v_rcp_f32_e32 v167, v167
	v_cvt_pk_bf16_f32 v164, v164, v165
	v_cvt_pk_bf16_f32 v165, v166, v167
	global_store_dwordx2 v246, v[164:165], s[4:5] offset:288
	v_add_f32_e32 v168, v86, v152
	v_add_f32_e32 v169, v87, v153
	v_add_f32_e32 v170, v88, v154
	v_add_f32_e32 v171, v89, v155
	v_mul_f32_e32 v168, s18, v168
	v_mul_f32_e32 v169, s18, v169
	v_mul_f32_e32 v170, s18, v170
	v_mul_f32_e32 v171, s18, v171
	v_exp_f32_e32 v168, v168
	v_exp_f32_e32 v169, v169
	v_exp_f32_e32 v170, v170
	v_exp_f32_e32 v171, v171
	v_add_f32_e32 v168, 1.0, v168
	v_add_f32_e32 v169, 1.0, v169
	v_add_f32_e32 v170, 1.0, v170
	v_add_f32_e32 v171, 1.0, v171
	v_rcp_f32_e32 v168, v168
	v_rcp_f32_e32 v169, v169
	v_rcp_f32_e32 v170, v170
	v_rcp_f32_e32 v171, v171
	v_cvt_pk_bf16_f32 v168, v168, v169
	v_cvt_pk_bf16_f32 v169, v170, v171
	global_store_dwordx2 v247, v[168:169], s[4:5] offset:256
	v_add_f32_e32 v172, v82, v156
	v_add_f32_e32 v173, v83, v157
	v_add_f32_e32 v174, v84, v158
	v_add_f32_e32 v175, v85, v159
	v_mul_f32_e32 v172, s18, v172
	v_mul_f32_e32 v173, s18, v173
	v_mul_f32_e32 v174, s18, v174
	v_mul_f32_e32 v175, s18, v175
	v_exp_f32_e32 v172, v172
	v_exp_f32_e32 v173, v173
	v_exp_f32_e32 v174, v174
	v_exp_f32_e32 v175, v175
	v_add_f32_e32 v172, 1.0, v172
	v_add_f32_e32 v173, 1.0, v173
	v_add_f32_e32 v174, 1.0, v174
	v_add_f32_e32 v175, 1.0, v175
	v_rcp_f32_e32 v172, v172
	v_rcp_f32_e32 v173, v173
	v_rcp_f32_e32 v174, v174
	v_rcp_f32_e32 v175, v175
	v_cvt_pk_bf16_f32 v172, v172, v173
	v_cvt_pk_bf16_f32 v173, v174, v175
	global_store_dwordx2 v247, v[172:173], s[4:5] offset:288
	v_add_f32_e32 v160, v78, v152
	v_add_f32_e32 v161, v79, v153
	v_add_f32_e32 v162, v80, v154
	v_add_f32_e32 v163, v81, v155
	v_mul_f32_e32 v160, s18, v160
	v_mul_f32_e32 v161, s18, v161
	v_mul_f32_e32 v162, s18, v162
	v_mul_f32_e32 v163, s18, v163
	v_exp_f32_e32 v160, v160
	v_exp_f32_e32 v161, v161
	v_exp_f32_e32 v162, v162
	v_exp_f32_e32 v163, v163
	v_add_f32_e32 v160, 1.0, v160
	v_add_f32_e32 v161, 1.0, v161
	v_add_f32_e32 v162, 1.0, v162
	v_add_f32_e32 v163, 1.0, v163
	v_rcp_f32_e32 v160, v160
	v_rcp_f32_e32 v161, v161
	v_rcp_f32_e32 v162, v162
	v_rcp_f32_e32 v163, v163
	v_cvt_pk_bf16_f32 v160, v160, v161
	v_cvt_pk_bf16_f32 v161, v162, v163
	global_store_dwordx2 v248, v[160:161], s[4:5] offset:256
	v_add_f32_e32 v164, v74, v156
	v_add_f32_e32 v165, v75, v157
	v_add_f32_e32 v166, v76, v158
	v_add_f32_e32 v167, v77, v159
	v_mul_f32_e32 v164, s18, v164
	v_mul_f32_e32 v165, s18, v165
	v_mul_f32_e32 v166, s18, v166
	v_mul_f32_e32 v167, s18, v167
	v_exp_f32_e32 v164, v164
	v_exp_f32_e32 v165, v165
	v_exp_f32_e32 v166, v166
	v_exp_f32_e32 v167, v167
	v_add_f32_e32 v164, 1.0, v164
	v_add_f32_e32 v165, 1.0, v165
	v_add_f32_e32 v166, 1.0, v166
	v_add_f32_e32 v167, 1.0, v167
	v_rcp_f32_e32 v164, v164
	v_rcp_f32_e32 v165, v165
	v_rcp_f32_e32 v166, v166
	v_rcp_f32_e32 v167, v167
	v_cvt_pk_bf16_f32 v164, v164, v165
	v_cvt_pk_bf16_f32 v165, v166, v167
	global_store_dwordx2 v248, v[164:165], s[4:5] offset:288
	v_add_f32_e32 v168, v70, v152
	v_add_f32_e32 v169, v71, v153
	v_add_f32_e32 v170, v72, v154
	v_add_f32_e32 v171, v73, v155
	v_mul_f32_e32 v168, s18, v168
	v_mul_f32_e32 v169, s18, v169
	v_mul_f32_e32 v170, s18, v170
	v_mul_f32_e32 v171, s18, v171
	v_exp_f32_e32 v168, v168
	v_exp_f32_e32 v169, v169
	v_exp_f32_e32 v170, v170
	v_exp_f32_e32 v171, v171
	v_add_f32_e32 v168, 1.0, v168
	v_add_f32_e32 v169, 1.0, v169
	v_add_f32_e32 v170, 1.0, v170
	v_add_f32_e32 v171, 1.0, v171
	v_rcp_f32_e32 v168, v168
	v_rcp_f32_e32 v169, v169
	v_rcp_f32_e32 v170, v170
	v_rcp_f32_e32 v171, v171
; #define GAS __attribute__((address_space(1)))
; __device__ __forceinline__ uint2 pack4(f32x4 v) { return make_uint2(pack2(v[0], v[1]), pack2(v[2], v[3])); }
; __device__ __forceinline__ float sigmoid_f(float x) { return __builtin_amdgcn_rcpf(1.0f + __builtin_amdgcn_exp2f(x * -1.4426950408889634f)); }
; template <int MODE>
; __device__ __forceinline__ void epi_elem(char* ws, float* outp, const float* b_gate, int g0, int rl, int col, f32x4 v) {
;     ...
;   } else if (MODE == E_G) {
;     int gc = col - 5120;
;     float4 bg = *(GAS const float4*)(b_gate + gc);
;     f32x4 o;
;     o[0] = sigmoid_f(v[0] + bg.x); o[1] = sigmoid_f(v[1] + bg.y); o[2] = sigmoid_f(v[2] + bg.z); o[3] = sigmoid_f(v[3] + bg.w);
;     *(GAS uint2*)((u16*)(ws + W_G) + (size_t)rl * 2048 + gc) = pack4(o);
	v_cvt_pk_bf16_f32 v168, v168, v169
	v_cvt_pk_bf16_f32 v169, v170, v171
	global_store_dwordx2 v249, v[168:169], s[4:5] offset:256
	v_add_f32_e32 v172, v66, v156
	v_add_f32_e32 v173, v67, v157
	v_add_f32_e32 v174, v68, v158
	v_add_f32_e32 v175, v69, v159
	v_mul_f32_e32 v172, s18, v172
	v_mul_f32_e32 v173, s18, v173
	v_mul_f32_e32 v174, s18, v174
	v_mul_f32_e32 v175, s18, v175
	v_exp_f32_e32 v172, v172
	v_exp_f32_e32 v173, v173
	v_exp_f32_e32 v174, v174
	v_exp_f32_e32 v175, v175
	v_add_f32_e32 v172, 1.0, v172
	v_add_f32_e32 v173, 1.0, v173
	v_add_f32_e32 v174, 1.0, v174
	v_add_f32_e32 v175, 1.0, v175
	v_rcp_f32_e32 v172, v172
	v_rcp_f32_e32 v173, v173
	v_rcp_f32_e32 v174, v174
	v_rcp_f32_e32 v175, v175
	v_cvt_pk_bf16_f32 v172, v172, v173
	v_cvt_pk_bf16_f32 v173, v174, v175
	global_store_dwordx2 v249, v[172:173], s[4:5] offset:288
	v_add_f32_e32 v160, v62, v144
	v_add_f32_e32 v161, v63, v145
	v_add_f32_e32 v162, v64, v146
	v_add_f32_e32 v163, v65, v147
	v_mul_f32_e32 v160, s18, v160
	v_mul_f32_e32 v161, s18, v161
	v_mul_f32_e32 v162, s18, v162
	v_mul_f32_e32 v163, s18, v163
	v_exp_f32_e32 v160, v160
	v_exp_f32_e32 v161, v161
	v_exp_f32_e32 v162, v162
	v_exp_f32_e32 v163, v163
	v_add_f32_e32 v160, 1.0, v160
	v_add_f32_e32 v161, 1.0, v161
	v_add_f32_e32 v162, 1.0, v162
	v_add_f32_e32 v163, 1.0, v163
	v_rcp_f32_e32 v160, v160
	v_rcp_f32_e32 v161, v161
	v_rcp_f32_e32 v162, v162
	v_rcp_f32_e32 v163, v163
	v_cvt_pk_bf16_f32 v160, v160, v161
	v_cvt_pk_bf16_f32 v161, v162, v163
	global_store_dwordx2 v246, v[160:161], s[6:7]
	v_add_f32_e32 v164, v58, v148
	v_add_f32_e32 v165, v59, v149
	v_add_f32_e32 v166, v60, v150
	v_add_f32_e32 v167, v61, v151
	v_mul_f32_e32 v164, s18, v164
	v_mul_f32_e32 v165, s18, v165
	v_mul_f32_e32 v166, s18, v166
	v_mul_f32_e32 v167, s18, v167
	v_exp_f32_e32 v164, v164
	v_exp_f32_e32 v165, v165
	v_exp_f32_e32 v166, v166
	v_exp_f32_e32 v167, v167
	v_add_f32_e32 v164, 1.0, v164
	v_add_f32_e32 v165, 1.0, v165
	v_add_f32_e32 v166, 1.0, v166
	v_add_f32_e32 v167, 1.0, v167
	v_rcp_f32_e32 v164, v164
	v_rcp_f32_e32 v165, v165
	v_rcp_f32_e32 v166, v166
	v_rcp_f32_e32 v167, v167
	v_cvt_pk_bf16_f32 v164, v164, v165
	v_cvt_pk_bf16_f32 v165, v166, v167
	global_store_dwordx2 v246, v[164:165], s[6:7] offset:32
	v_add_f32_e32 v168, v54, v144
	v_add_f32_e32 v169, v55, v145
	v_add_f32_e32 v170, v56, v146
	v_add_f32_e32 v171, v57, v147
	v_mul_f32_e32 v168, s18, v168
	v_mul_f32_e32 v169, s18, v169
	v_mul_f32_e32 v170, s18, v170
	v_mul_f32_e32 v171, s18, v171
	v_exp_f32_e32 v168, v168
	v_exp_f32_e32 v169, v169
	v_exp_f32_e32 v170, v170
	v_exp_f32_e32 v171, v171
	v_add_f32_e32 v168, 1.0, v168
	v_add_f32_e32 v169, 1.0, v169
	v_add_f32_e32 v170, 1.0, v170
	v_add_f32_e32 v171, 1.0, v171
	v_rcp_f32_e32 v168, v168
	v_rcp_f32_e32 v169, v169
	v_rcp_f32_e32 v170, v170
	v_rcp_f32_e32 v171, v171
	v_cvt_pk_bf16_f32 v168, v168, v169
	v_cvt_pk_bf16_f32 v169, v170, v171
	global_store_dwordx2 v247, v[168:169], s[6:7]
	v_add_f32_e32 v172, v50, v148
	v_add_f32_e32 v173, v51, v149
	v_add_f32_e32 v174, v52, v150
	v_add_f32_e32 v175, v53, v151
	v_mul_f32_e32 v172, s18, v172
	v_mul_f32_e32 v173, s18, v173
	v_mul_f32_e32 v174, s18, v174
	v_mul_f32_e32 v175, s18, v175
	v_exp_f32_e32 v172, v172
	v_exp_f32_e32 v173, v173
	v_exp_f32_e32 v174, v174
	v_exp_f32_e32 v175, v175
	v_add_f32_e32 v172, 1.0, v172
	v_add_f32_e32 v173, 1.0, v173
	v_add_f32_e32 v174, 1.0, v174
	v_add_f32_e32 v175, 1.0, v175
	v_rcp_f32_e32 v172, v172
	v_rcp_f32_e32 v173, v173
	v_rcp_f32_e32 v174, v174
	v_rcp_f32_e32 v175, v175
	v_cvt_pk_bf16_f32 v172, v172, v173
	v_cvt_pk_bf16_f32 v173, v174, v175
	global_store_dwordx2 v247, v[172:173], s[6:7] offset:32
	v_add_f32_e32 v160, v46, v144
	v_add_f32_e32 v161, v47, v145
	v_add_f32_e32 v162, v48, v146
	v_add_f32_e32 v163, v49, v147
	v_mul_f32_e32 v160, s18, v160
	v_mul_f32_e32 v161, s18, v161
	v_mul_f32_e32 v162, s18, v162
	v_mul_f32_e32 v163, s18, v163
	v_exp_f32_e32 v160, v160
	v_exp_f32_e32 v161, v161
	v_exp_f32_e32 v162, v162
	v_exp_f32_e32 v163, v163
	v_add_f32_e32 v160, 1.0, v160
	v_add_f32_e32 v161, 1.0, v161
	v_add_f32_e32 v162, 1.0, v162
	v_add_f32_e32 v163, 1.0, v163
	v_rcp_f32_e32 v160, v160
	v_rcp_f32_e32 v161, v161
	v_rcp_f32_e32 v162, v162
	v_rcp_f32_e32 v163, v163
	v_cvt_pk_bf16_f32 v160, v160, v161
	v_cvt_pk_bf16_f32 v161, v162, v163
	global_store_dwordx2 v248, v[160:161], s[6:7]
	v_add_f32_e32 v164, v42, v148
	v_add_f32_e32 v165, v43, v149
	v_add_f32_e32 v166, v44, v150
	v_add_f32_e32 v167, v45, v151
	v_mul_f32_e32 v164, s18, v164
	v_mul_f32_e32 v165, s18, v165
	v_mul_f32_e32 v166, s18, v166
	v_mul_f32_e32 v167, s18, v167
	v_exp_f32_e32 v164, v164
	v_exp_f32_e32 v165, v165
	v_exp_f32_e32 v166, v166
	v_exp_f32_e32 v167, v167
	v_add_f32_e32 v164, 1.0, v164
	v_add_f32_e32 v165, 1.0, v165
	v_add_f32_e32 v166, 1.0, v166
	v_add_f32_e32 v167, 1.0, v167
	v_rcp_f32_e32 v164, v164
	v_rcp_f32_e32 v165, v165
	v_rcp_f32_e32 v166, v166
	v_rcp_f32_e32 v167, v167
	v_cvt_pk_bf16_f32 v164, v164, v165
	v_cvt_pk_bf16_f32 v165, v166, v167
	global_store_dwordx2 v248, v[164:165], s[6:7] offset:32
	v_add_f32_e32 v168, v38, v144
	v_add_f32_e32 v169, v39, v145
	v_add_f32_e32 v170, v40, v146
	v_add_f32_e32 v171, v41, v147
	v_mul_f32_e32 v168, s18, v168
	v_mul_f32_e32 v169, s18, v169
	v_mul_f32_e32 v170, s18, v170
	v_mul_f32_e32 v171, s18, v171
	v_exp_f32_e32 v168, v168
	v_exp_f32_e32 v169, v169
	v_exp_f32_e32 v170, v170
	v_exp_f32_e32 v171, v171
	v_add_f32_e32 v168, 1.0, v168
	v_add_f32_e32 v169, 1.0, v169
	v_add_f32_e32 v170, 1.0, v170
	v_add_f32_e32 v171, 1.0, v171
	v_rcp_f32_e32 v168, v168
	v_rcp_f32_e32 v169, v169
	v_rcp_f32_e32 v170, v170
	v_rcp_f32_e32 v171, v171
; #define GAS __attribute__((address_space(1)))
; __device__ __forceinline__ uint2 pack4(f32x4 v) { return make_uint2(pack2(v[0], v[1]), pack2(v[2], v[3])); }
; __device__ __forceinline__ float sigmoid_f(float x) { return __builtin_amdgcn_rcpf(1.0f + __builtin_amdgcn_exp2f(x * -1.4426950408889634f)); }
; template <int MODE>
; __device__ __forceinline__ void epi_elem(char* ws, float* outp, const float* b_gate, int g0, int rl, int col, f32x4 v) {
;     ...
;   } else if (MODE == E_G) {
;     int gc = col - 5120;
;     float4 bg = *(GAS const float4*)(b_gate + gc);
;     f32x4 o;
;     o[0] = sigmoid_f(v[0] + bg.x); o[1] = sigmoid_f(v[1] + bg.y); o[2] = sigmoid_f(v[2] + bg.z); o[3] = sigmoid_f(v[3] + bg.w);
;     *(GAS uint2*)((u16*)(ws + W_G) + (size_t)rl * 2048 + gc) = pack4(o);
	v_cvt_pk_bf16_f32 v168, v168, v169
	v_cvt_pk_bf16_f32 v169, v170, v171
	global_store_dwordx2 v249, v[168:169], s[6:7]
	v_add_f32_e32 v172, v34, v148
	v_add_f32_e32 v173, v35, v149
	v_add_f32_e32 v174, v36, v150
	v_add_f32_e32 v175, v37, v151
	v_mul_f32_e32 v172, s18, v172
	v_mul_f32_e32 v173, s18, v173
	v_mul_f32_e32 v174, s18, v174
	v_mul_f32_e32 v175, s18, v175
	v_exp_f32_e32 v172, v172
	v_exp_f32_e32 v173, v173
	v_exp_f32_e32 v174, v174
	v_exp_f32_e32 v175, v175
	v_add_f32_e32 v172, 1.0, v172
	v_add_f32_e32 v173, 1.0, v173
	v_add_f32_e32 v174, 1.0, v174
	v_add_f32_e32 v175, 1.0, v175
	v_rcp_f32_e32 v172, v172
	v_rcp_f32_e32 v173, v173
	v_rcp_f32_e32 v174, v174
	v_rcp_f32_e32 v175, v175
	v_cvt_pk_bf16_f32 v172, v172, v173
	v_cvt_pk_bf16_f32 v173, v174, v175
	global_store_dwordx2 v249, v[172:173], s[6:7] offset:32
	v_add_f32_e32 v160, v30, v152
	v_add_f32_e32 v161, v31, v153
	v_add_f32_e32 v162, v32, v154
	v_add_f32_e32 v163, v33, v155
	v_mul_f32_e32 v160, s18, v160
	v_mul_f32_e32 v161, s18, v161
	v_mul_f32_e32 v162, s18, v162
	v_mul_f32_e32 v163, s18, v163
	v_exp_f32_e32 v160, v160
	v_exp_f32_e32 v161, v161
	v_exp_f32_e32 v162, v162
	v_exp_f32_e32 v163, v163
	v_add_f32_e32 v160, 1.0, v160
	v_add_f32_e32 v161, 1.0, v161
	v_add_f32_e32 v162, 1.0, v162
	v_add_f32_e32 v163, 1.0, v163
	v_rcp_f32_e32 v160, v160
	v_rcp_f32_e32 v161, v161
	v_rcp_f32_e32 v162, v162
	v_rcp_f32_e32 v163, v163
	v_cvt_pk_bf16_f32 v160, v160, v161
	v_cvt_pk_bf16_f32 v161, v162, v163
	global_store_dwordx2 v246, v[160:161], s[6:7] offset:256
	v_add_f32_e32 v164, v26, v156
	v_add_f32_e32 v165, v27, v157
	v_add_f32_e32 v166, v28, v158
	v_add_f32_e32 v167, v29, v159
	v_mul_f32_e32 v164, s18, v164
	v_mul_f32_e32 v165, s18, v165
	v_mul_f32_e32 v166, s18, v166
	v_mul_f32_e32 v167, s18, v167
	v_exp_f32_e32 v164, v164
	v_exp_f32_e32 v165, v165
	v_exp_f32_e32 v166, v166
	v_exp_f32_e32 v167, v167
	v_add_f32_e32 v164, 1.0, v164
	v_add_f32_e32 v165, 1.0, v165
	v_add_f32_e32 v166, 1.0, v166
	v_add_f32_e32 v167, 1.0, v167
	v_rcp_f32_e32 v164, v164
	v_rcp_f32_e32 v165, v165
	v_rcp_f32_e32 v166, v166
	v_rcp_f32_e32 v167, v167
	v_cvt_pk_bf16_f32 v164, v164, v165
	v_cvt_pk_bf16_f32 v165, v166, v167
	global_store_dwordx2 v246, v[164:165], s[6:7] offset:288
	v_add_f32_e32 v168, v22, v152
	v_add_f32_e32 v169, v23, v153
	v_add_f32_e32 v170, v24, v154
	v_add_f32_e32 v171, v25, v155
	v_mul_f32_e32 v168, s18, v168
	v_mul_f32_e32 v169, s18, v169
	v_mul_f32_e32 v170, s18, v170
	v_mul_f32_e32 v171, s18, v171
	v_exp_f32_e32 v168, v168
	v_exp_f32_e32 v169, v169
	v_exp_f32_e32 v170, v170
	v_exp_f32_e32 v171, v171
	v_add_f32_e32 v168, 1.0, v168
	v_add_f32_e32 v169, 1.0, v169
	v_add_f32_e32 v170, 1.0, v170
	v_add_f32_e32 v171, 1.0, v171
	v_rcp_f32_e32 v168, v168
	v_rcp_f32_e32 v169, v169
	v_rcp_f32_e32 v170, v170
	v_rcp_f32_e32 v171, v171
	v_cvt_pk_bf16_f32 v168, v168, v169
	v_cvt_pk_bf16_f32 v169, v170, v171
	global_store_dwordx2 v247, v[168:169], s[6:7] offset:256
	v_add_f32_e32 v172, v18, v156
	v_add_f32_e32 v173, v19, v157
	v_add_f32_e32 v174, v20, v158
	v_add_f32_e32 v175, v21, v159
	v_mul_f32_e32 v172, s18, v172
	v_mul_f32_e32 v173, s18, v173
	v_mul_f32_e32 v174, s18, v174
	v_mul_f32_e32 v175, s18, v175
	v_exp_f32_e32 v172, v172
	v_exp_f32_e32 v173, v173
	v_exp_f32_e32 v174, v174
	v_exp_f32_e32 v175, v175
	v_add_f32_e32 v172, 1.0, v172
	v_add_f32_e32 v173, 1.0, v173
	v_add_f32_e32 v174, 1.0, v174
	v_add_f32_e32 v175, 1.0, v175
	v_rcp_f32_e32 v172, v172
	v_rcp_f32_e32 v173, v173
	v_rcp_f32_e32 v174, v174
	v_rcp_f32_e32 v175, v175
	v_cvt_pk_bf16_f32 v172, v172, v173
	v_cvt_pk_bf16_f32 v173, v174, v175
	global_store_dwordx2 v247, v[172:173], s[6:7] offset:288
	v_add_f32_e32 v160, v14, v152
	v_add_f32_e32 v161, v15, v153
	v_add_f32_e32 v162, v16, v154
	v_add_f32_e32 v163, v17, v155
	v_mul_f32_e32 v160, s18, v160
	v_mul_f32_e32 v161, s18, v161
	v_mul_f32_e32 v162, s18, v162
	v_mul_f32_e32 v163, s18, v163
	v_exp_f32_e32 v160, v160
	v_exp_f32_e32 v161, v161
	v_exp_f32_e32 v162, v162
	v_exp_f32_e32 v163, v163
	v_add_f32_e32 v160, 1.0, v160
	v_add_f32_e32 v161, 1.0, v161
	v_add_f32_e32 v162, 1.0, v162
	v_add_f32_e32 v163, 1.0, v163
	v_rcp_f32_e32 v160, v160
	v_rcp_f32_e32 v161, v161
	v_rcp_f32_e32 v162, v162
	v_rcp_f32_e32 v163, v163
	v_cvt_pk_bf16_f32 v160, v160, v161
	v_cvt_pk_bf16_f32 v161, v162, v163
	global_store_dwordx2 v248, v[160:161], s[6:7] offset:256
	v_add_f32_e32 v164, v10, v156
	v_add_f32_e32 v165, v11, v157
	v_add_f32_e32 v166, v12, v158
	v_add_f32_e32 v167, v13, v159
	v_mul_f32_e32 v164, s18, v164
	v_mul_f32_e32 v165, s18, v165
	v_mul_f32_e32 v166, s18, v166
	v_mul_f32_e32 v167, s18, v167
	v_exp_f32_e32 v164, v164
	v_exp_f32_e32 v165, v165
	v_exp_f32_e32 v166, v166
	v_exp_f32_e32 v167, v167
	v_add_f32_e32 v164, 1.0, v164
	v_add_f32_e32 v165, 1.0, v165
	v_add_f32_e32 v166, 1.0, v166
	v_add_f32_e32 v167, 1.0, v167
	v_rcp_f32_e32 v164, v164
	v_rcp_f32_e32 v165, v165
	v_rcp_f32_e32 v166, v166
	v_rcp_f32_e32 v167, v167
	v_cvt_pk_bf16_f32 v164, v164, v165
	v_cvt_pk_bf16_f32 v165, v166, v167
	global_store_dwordx2 v248, v[164:165], s[6:7] offset:288
	v_add_f32_e32 v168, v6, v152
	v_add_f32_e32 v169, v7, v153
	v_add_f32_e32 v170, v8, v154
	v_add_f32_e32 v171, v9, v155
	v_mul_f32_e32 v168, s18, v168
	v_mul_f32_e32 v169, s18, v169
	v_mul_f32_e32 v170, s18, v170
	v_mul_f32_e32 v171, s18, v171
	v_exp_f32_e32 v168, v168
	v_exp_f32_e32 v169, v169
	v_exp_f32_e32 v170, v170
	v_exp_f32_e32 v171, v171
	v_add_f32_e32 v168, 1.0, v168
	v_add_f32_e32 v169, 1.0, v169
	v_add_f32_e32 v170, 1.0, v170
	v_add_f32_e32 v171, 1.0, v171
	v_rcp_f32_e32 v168, v168
	v_rcp_f32_e32 v169, v169
	v_rcp_f32_e32 v170, v170
	v_rcp_f32_e32 v171, v171
	v_cvt_pk_bf16_f32 v168, v168, v169
	v_cvt_pk_bf16_f32 v169, v170, v171
	global_store_dwordx2 v249, v[168:169], s[6:7] offset:256
	v_add_f32_e32 v172, v2, v156
	v_add_f32_e32 v173, v3, v157
	v_add_f32_e32 v174, v4, v158
	v_add_f32_e32 v175, v5, v159
	v_mul_f32_e32 v172, s18, v172
	v_mul_f32_e32 v173, s18, v173
	v_mul_f32_e32 v174, s18, v174
	v_mul_f32_e32 v175, s18, v175
	v_exp_f32_e32 v172, v172
	v_exp_f32_e32 v173, v173
	v_exp_f32_e32 v174, v174
	v_exp_f32_e32 v175, v175
	v_add_f32_e32 v172, 1.0, v172
	v_add_f32_e32 v173, 1.0, v173
	v_add_f32_e32 v174, 1.0, v174
	v_add_f32_e32 v175, 1.0, v175
	v_rcp_f32_e32 v172, v172
	v_rcp_f32_e32 v173, v173
	v_rcp_f32_e32 v174, v174
	v_rcp_f32_e32 v175, v175
	v_cvt_pk_bf16_f32 v172, v172, v173
	v_cvt_pk_bf16_f32 v173, v174, v175
	global_store_dwordx2 v249, v[172:173], s[6:7] offset:288
	s_branch .LBB0_996
; #define GAS __attribute__((address_space(1)))
; __device__ __forceinline__ u16 f2bf(float f) { return (u16)(pack2(f, 0.f) & 0xffffu); }
; template <int MODE>
; __device__ __forceinline__ void epi_elem(char* ws, float* outp, const float* b_gate, int g0, int rl, int col, f32x4 v) {
;     ...
;   } else if (MODE == E_V) {
;     int lc = col & 1023;
;     u16* vt = (u16*)(ws + W_VT);
; #pragma unroll
;     for (int i = 0; i < 4; ++i) vt[(size_t)(lc + i) * MAXR + rl] = f2bf(v[i]);
;     int rg = g0 + rl;
;     float* o = rg < NPROMPT ? outp + O_VP + (size_t)rg * 1024 : outp + O_VS + (size_t)(rg - NPROMPT) * 1024;
;     __builtin_nontemporal_store(v, (GAS f32x4*)(o + lc));
.LBB0_977:
	s_andn2_b64 vcc, exec, s[12:13]
	s_cbranch_vccnz .LBB0_979
	v_ashrrev_i32_e32 v143, 31, v142
	v_lshl_add_u64 v[144:145], v[142:143], 1, s[2:3]
	s_mov_b64 s[10:11], 0x169c0000
	v_lshl_add_u64 v[174:175], v[144:145], 0, s[10:11]
	v_readlane_b32 s10, v255, 18
	v_mov_b32_e32 v147, v0
	v_cvt_pk_bf16_f32 v148, v127, s0
	v_add_u32_e32 v141, s10, v142
	s_mov_b32 s10, 0x10000
	v_add_u32_e32 v143, 0xffff0000, v141
	v_ashrrev_i32_e32 v144, 31, v141
	v_cmp_gt_i32_e32 vcc, s10, v141
	s_mov_b32 s11, 0x20000
	v_cvt_pk_bf16_f32 v150, v128, s0
	v_cndmask_b32_e32 v145, 0, v144, vcc
	v_cndmask_b32_e32 v144, v143, v141, vcc
	v_cndmask_b32_e32 v146, v205, v206, vcc
	v_lshl_add_u64 v[146:147], s[6:7], 0, v[146:147]
	v_lshlrev_b64 v[144:145], 12, v[144:145]
	v_and_b32_e32 v143, 0x3ff, v140
	v_lshl_add_u64 v[188:189], v[146:147], 0, v[144:145]
	v_mul_u32_u24_e32 v144, 0x8200, v143
	v_lshlrev_b32_e32 v144, 1, v144
	v_mov_b32_e32 v145, v0
	v_cvt_pk_bf16_f32 v146, v126, s0
	v_lshl_add_u64 v[144:145], v[174:175], 0, v[144:145]
	global_store_short v[144:145], v146, off
	v_add_co_u32_e32 v146, vcc, s10, v144
	s_mov_b32 s12, 0x30000
	s_nop 0
	v_addc_co_u32_e32 v147, vcc, 0, v145, vcc
	global_store_short v[146:147], v148, off offset:1024
	v_add_co_u32_e32 v148, vcc, s11, v144
	v_cvt_pk_bf16_f32 v152, v129, s0
	s_nop 0
	v_addc_co_u32_e32 v149, vcc, 0, v145, vcc
	global_store_short v[148:149], v150, off offset:2048
	v_add_co_u32_e32 v150, vcc, s12, v144
	v_mov_b32_e32 v153, v0
	s_nop 0
	v_addc_co_u32_e32 v151, vcc, 0, v145, vcc
	global_store_short v[150:151], v152, off offset:3072
	v_lshlrev_b32_e32 v152, 2, v143
	v_add_u32_e32 v143, 16, v140
	v_lshl_add_u64 v[154:155], v[188:189], 0, v[152:153]
	v_and_b32_e32 v143, 0x3ff, v143
	global_store_dwordx4 v[154:155], v[126:129], off nt
	v_mul_u32_u24_e32 v154, 0x8200, v143
	v_lshlrev_b32_e32 v154, 1, v154
	v_mov_b32_e32 v155, v0
	v_cvt_pk_bf16_f32 v156, v122, s0
	v_lshl_add_u64 v[154:155], v[174:175], 0, v[154:155]
	global_store_short v[154:155], v156, off
	v_add_co_u32_e32 v156, vcc, s10, v154
	v_cvt_pk_bf16_f32 v158, v123, s0
	s_nop 0
	v_addc_co_u32_e32 v157, vcc, 0, v155, vcc
	global_store_short v[156:157], v158, off offset:1024
	v_add_co_u32_e32 v158, vcc, s11, v154
	v_cvt_pk_bf16_f32 v160, v124, s0
	s_nop 0
	v_addc_co_u32_e32 v159, vcc, 0, v155, vcc
	global_store_short v[158:159], v160, off offset:2048
	v_add_co_u32_e32 v160, vcc, s12, v154
	v_cvt_pk_bf16_f32 v162, v125, s0
	s_nop 0
	v_addc_co_u32_e32 v161, vcc, 0, v155, vcc
	global_store_short v[160:161], v162, off offset:3072
	v_lshlrev_b32_e32 v162, 2, v143
	v_mov_b32_e32 v163, v0
	v_lshl_add_u64 v[164:165], v[188:189], 0, v[162:163]
	v_add_u32_e32 v143, 16, v141
	global_store_dwordx4 v[164:165], v[122:125], off nt
	v_add_u32_e32 v164, 0xffff0010, v141
	v_cmp_gt_i32_e32 vcc, s10, v143
	v_ashrrev_i32_e32 v165, 31, v143
	v_mov_b32_e32 v167, v0
	v_cndmask_b32_e32 v164, v164, v143, vcc
	v_cvt_pk_bf16_f32 v143, v118, s0
	v_cndmask_b32_e32 v165, 0, v165, vcc
	v_cndmask_b32_e32 v166, v205, v206, vcc
	global_store_short v[144:145], v143, off offset:32
	v_cvt_pk_bf16_f32 v143, v119, s0
	v_lshl_add_u64 v[166:167], s[6:7], 0, v[166:167]
	v_lshlrev_b64 v[164:165], 12, v[164:165]
	global_store_short v[146:147], v143, off offset:1056
	v_cvt_pk_bf16_f32 v143, v120, s0
	v_lshl_add_u64 v[190:191], v[166:167], 0, v[164:165]
	global_store_short v[148:149], v143, off offset:2080
	v_cvt_pk_bf16_f32 v143, v121, s0
	global_store_short v[150:151], v143, off offset:3104
	v_lshl_add_u64 v[164:165], v[190:191], 0, v[152:153]
	v_cvt_pk_bf16_f32 v143, v114, s0
	global_store_dwordx4 v[164:165], v[118:121], off nt
	global_store_short v[154:155], v143, off offset:32
	v_cvt_pk_bf16_f32 v143, v115, s0
	global_store_short v[156:157], v143, off offset:1056
	v_cvt_pk_bf16_f32 v143, v116, s0
	global_store_short v[158:159], v143, off offset:2080
	v_cvt_pk_bf16_f32 v143, v117, s0
	v_lshl_add_u64 v[164:165], v[190:191], 0, v[162:163]
	global_store_short v[160:161], v143, off offset:3104
	global_store_dwordx4 v[164:165], v[114:117], off nt
	v_add_u32_e32 v143, 32, v141
	v_add_u32_e32 v164, 0xffff0020, v141
	v_cmp_gt_i32_e32 vcc, s10, v143
	v_ashrrev_i32_e32 v165, 31, v143
	v_mov_b32_e32 v167, v0
	v_cndmask_b32_e32 v164, v164, v143, vcc
	v_cvt_pk_bf16_f32 v143, v110, s0
	v_cndmask_b32_e32 v165, 0, v165, vcc
	v_cndmask_b32_e32 v166, v205, v206, vcc
	global_store_short v[144:145], v143, off offset:64
	v_cvt_pk_bf16_f32 v143, v111, s0
	v_lshl_add_u64 v[166:167], s[6:7], 0, v[166:167]
	v_lshlrev_b64 v[164:165], 12, v[164:165]
	global_store_short v[146:147], v143, off offset:1088
	v_cvt_pk_bf16_f32 v143, v112, s0
	v_lshl_add_u64 v[192:193], v[166:167], 0, v[164:165]
	global_store_short v[148:149], v143, off offset:2112
	v_cvt_pk_bf16_f32 v143, v113, s0
	global_store_short v[150:151], v143, off offset:3136
	v_lshl_add_u64 v[164:165], v[192:193], 0, v[152:153]
	v_cvt_pk_bf16_f32 v143, v106, s0
	global_store_dwordx4 v[164:165], v[110:113], off nt
	global_store_short v[154:155], v143, off offset:64
	v_cvt_pk_bf16_f32 v143, v107, s0
	global_store_short v[156:157], v143, off offset:1088
	v_cvt_pk_bf16_f32 v143, v108, s0
	global_store_short v[158:159], v143, off offset:2112
	v_cvt_pk_bf16_f32 v143, v109, s0
	global_store_short v[160:161], v143, off offset:3136
	v_lshl_add_u64 v[164:165], v[192:193], 0, v[162:163]
	v_add_u32_e32 v143, 48, v141
	global_store_dwordx4 v[164:165], v[106:109], off nt
	v_add_u32_e32 v164, 0xffff0030, v141
	v_cmp_gt_i32_e32 vcc, s10, v143
	v_ashrrev_i32_e32 v165, 31, v143
	v_mov_b32_e32 v167, v0
	v_cndmask_b32_e32 v164, v164, v143, vcc
	v_cvt_pk_bf16_f32 v143, v102, s0
; #define GAS __attribute__((address_space(1)))
; __device__ __forceinline__ u16 f2bf(float f) { return (u16)(pack2(f, 0.f) & 0xffffu); }
; template <int MODE>
; __device__ __forceinline__ void epi_elem(char* ws, float* outp, const float* b_gate, int g0, int rl, int col, f32x4 v) {
;     ...
;   } else if (MODE == E_V) {
;     int lc = col & 1023;
;     u16* vt = (u16*)(ws + W_VT);
; #pragma unroll
;     for (int i = 0; i < 4; ++i) vt[(size_t)(lc + i) * MAXR + rl] = f2bf(v[i]);
;     int rg = g0 + rl;
;     float* o = rg < NPROMPT ? outp + O_VP + (size_t)rg * 1024 : outp + O_VS + (size_t)(rg - NPROMPT) * 1024;
;     __builtin_nontemporal_store(v, (GAS f32x4*)(o + lc));
	v_cndmask_b32_e32 v165, 0, v165, vcc
	v_cndmask_b32_e32 v166, v205, v206, vcc
	global_store_short v[144:145], v143, off offset:96
	v_cvt_pk_bf16_f32 v143, v103, s0
	v_lshl_add_u64 v[166:167], s[6:7], 0, v[166:167]
	v_lshlrev_b64 v[164:165], 12, v[164:165]
	global_store_short v[146:147], v143, off offset:1120
	v_cvt_pk_bf16_f32 v143, v104, s0
	v_lshl_add_u64 v[194:195], v[166:167], 0, v[164:165]
	global_store_short v[148:149], v143, off offset:2144
	v_cvt_pk_bf16_f32 v143, v105, s0
	global_store_short v[150:151], v143, off offset:3168
	v_lshl_add_u64 v[164:165], v[194:195], 0, v[152:153]
	v_cvt_pk_bf16_f32 v143, v98, s0
	global_store_dwordx4 v[164:165], v[102:105], off nt
	global_store_short v[154:155], v143, off offset:96
	v_cvt_pk_bf16_f32 v143, v99, s0
	global_store_short v[156:157], v143, off offset:1120
	v_cvt_pk_bf16_f32 v143, v100, s0
	global_store_short v[158:159], v143, off offset:2144
	v_cvt_pk_bf16_f32 v143, v101, s0
	v_lshl_add_u64 v[164:165], v[194:195], 0, v[162:163]
	global_store_short v[160:161], v143, off offset:3168
	global_store_dwordx4 v[164:165], v[98:101], off nt
	v_add_u32_e32 v143, 0x80, v140
	v_and_b32_e32 v143, 0x3ff, v143
	v_mul_u32_u24_e32 v164, 0x8200, v143
	v_lshlrev_b32_e32 v164, 1, v164
	v_mov_b32_e32 v165, v0
	v_cvt_pk_bf16_f32 v166, v94, s0
	v_lshl_add_u64 v[164:165], v[174:175], 0, v[164:165]
	global_store_short v[164:165], v166, off
	v_add_co_u32_e32 v166, vcc, s10, v164
	v_cvt_pk_bf16_f32 v168, v95, s0
	s_nop 0
	v_addc_co_u32_e32 v167, vcc, 0, v165, vcc
	global_store_short v[166:167], v168, off offset:1024
	v_add_co_u32_e32 v168, vcc, s11, v164
	v_cvt_pk_bf16_f32 v170, v96, s0
	s_nop 0
	v_addc_co_u32_e32 v169, vcc, 0, v165, vcc
	global_store_short v[168:169], v170, off offset:2048
	v_add_co_u32_e32 v170, vcc, s12, v164
	v_cvt_pk_bf16_f32 v172, v97, s0
	s_nop 0
	v_addc_co_u32_e32 v171, vcc, 0, v165, vcc
	global_store_short v[170:171], v172, off offset:3072
	v_lshlrev_b32_e32 v172, 2, v143
	v_mov_b32_e32 v173, v0
	v_add_u32_e32 v143, 0x90, v140
	v_lshl_add_u64 v[176:177], v[188:189], 0, v[172:173]
	v_and_b32_e32 v143, 0x3ff, v143
	global_store_dwordx4 v[176:177], v[94:97], off nt
	v_mul_u32_u24_e32 v176, 0x8200, v143
	v_lshlrev_b32_e32 v176, 1, v176
	v_mov_b32_e32 v177, v0
	v_lshl_add_u64 v[174:175], v[174:175], 0, v[176:177]
	v_cvt_pk_bf16_f32 v178, v90, s0
	v_add_co_u32_e32 v176, vcc, s10, v174
	global_store_short v[174:175], v178, off
	v_cvt_pk_bf16_f32 v178, v91, s0
	v_addc_co_u32_e32 v177, vcc, 0, v175, vcc
	global_store_short v[176:177], v178, off offset:1024
	v_add_co_u32_e32 v178, vcc, s11, v174
	v_cvt_pk_bf16_f32 v180, v92, s0
	s_nop 0
	v_addc_co_u32_e32 v179, vcc, 0, v175, vcc
	global_store_short v[178:179], v180, off offset:2048
	v_add_co_u32_e32 v180, vcc, s12, v174
	v_cvt_pk_bf16_f32 v182, v93, s0
	s_nop 0
	v_addc_co_u32_e32 v181, vcc, 0, v175, vcc
	global_store_short v[180:181], v182, off offset:3072
	v_lshlrev_b32_e32 v182, 2, v143
	v_mov_b32_e32 v183, v0
	v_lshl_add_u64 v[188:189], v[188:189], 0, v[182:183]
	v_cvt_pk_bf16_f32 v143, v86, s0
	global_store_dwordx4 v[188:189], v[90:93], off nt
	global_store_short v[164:165], v143, off offset:32
	v_cvt_pk_bf16_f32 v143, v87, s0
	global_store_short v[166:167], v143, off offset:1056
	v_cvt_pk_bf16_f32 v143, v88, s0
	global_store_short v[168:169], v143, off offset:2080
	v_cvt_pk_bf16_f32 v143, v89, s0
	global_store_short v[170:171], v143, off offset:3104
	v_lshl_add_u64 v[188:189], v[190:191], 0, v[172:173]
	v_cvt_pk_bf16_f32 v143, v82, s0
	global_store_dwordx4 v[188:189], v[86:89], off nt
	global_store_short v[174:175], v143, off offset:32
	v_cvt_pk_bf16_f32 v143, v83, s0
	global_store_short v[176:177], v143, off offset:1056
	v_cvt_pk_bf16_f32 v143, v84, s0
	global_store_short v[178:179], v143, off offset:2080
	v_cvt_pk_bf16_f32 v143, v85, s0
	v_lshl_add_u64 v[188:189], v[190:191], 0, v[182:183]
	global_store_short v[180:181], v143, off offset:3104
	global_store_dwordx4 v[188:189], v[82:85], off nt
	v_cvt_pk_bf16_f32 v143, v78, s0
	global_store_short v[164:165], v143, off offset:64
	v_cvt_pk_bf16_f32 v143, v79, s0
	global_store_short v[166:167], v143, off offset:1088
	v_cvt_pk_bf16_f32 v143, v80, s0
	global_store_short v[168:169], v143, off offset:2112
	v_cvt_pk_bf16_f32 v143, v81, s0
	global_store_short v[170:171], v143, off offset:3136
	v_lshl_add_u64 v[188:189], v[192:193], 0, v[172:173]
	v_cvt_pk_bf16_f32 v143, v74, s0
	global_store_dwordx4 v[188:189], v[78:81], off nt
	global_store_short v[174:175], v143, off offset:64
	v_cvt_pk_bf16_f32 v143, v75, s0
	global_store_short v[176:177], v143, off offset:1088
	v_cvt_pk_bf16_f32 v143, v76, s0
	global_store_short v[178:179], v143, off offset:2112
	v_cvt_pk_bf16_f32 v143, v77, s0
	global_store_short v[180:181], v143, off offset:3136
	v_lshl_add_u64 v[188:189], v[192:193], 0, v[182:183]
	v_cvt_pk_bf16_f32 v143, v70, s0
	global_store_dwordx4 v[188:189], v[74:77], off nt
	global_store_short v[164:165], v143, off offset:96
	v_cvt_pk_bf16_f32 v143, v71, s0
	global_store_short v[166:167], v143, off offset:1120
	v_cvt_pk_bf16_f32 v143, v72, s0
	global_store_short v[168:169], v143, off offset:2144
	v_cvt_pk_bf16_f32 v143, v73, s0
	global_store_short v[170:171], v143, off offset:3168
	v_lshl_add_u64 v[188:189], v[194:195], 0, v[172:173]
	v_cvt_pk_bf16_f32 v143, v66, s0
	global_store_dwordx4 v[188:189], v[70:73], off nt
	global_store_short v[174:175], v143, off offset:96
	v_cvt_pk_bf16_f32 v143, v67, s0
	global_store_short v[176:177], v143, off offset:1120
	v_cvt_pk_bf16_f32 v143, v68, s0
	global_store_short v[178:179], v143, off offset:2144
	v_cvt_pk_bf16_f32 v143, v69, s0
	v_lshl_add_u64 v[188:189], v[194:195], 0, v[182:183]
; #define GAS __attribute__((address_space(1)))
; __device__ __forceinline__ u16 f2bf(float f) { return (u16)(pack2(f, 0.f) & 0xffffu); }
; template <int MODE>
; __device__ __forceinline__ void epi_elem(char* ws, float* outp, const float* b_gate, int g0, int rl, int col, f32x4 v) {
;     ...
;   } else if (MODE == E_V) {
;     int lc = col & 1023;
;     u16* vt = (u16*)(ws + W_VT);
; #pragma unroll
;     for (int i = 0; i < 4; ++i) vt[(size_t)(lc + i) * MAXR + rl] = f2bf(v[i]);
;     int rg = g0 + rl;
;     float* o = rg < NPROMPT ? outp + O_VP + (size_t)rg * 1024 : outp + O_VS + (size_t)(rg - NPROMPT) * 1024;
;     __builtin_nontemporal_store(v, (GAS f32x4*)(o + lc));
	global_store_short v[180:181], v143, off offset:3168
	global_store_dwordx4 v[188:189], v[66:69], off nt
	v_add_u32_e32 v143, 0x80, v141
	v_add_u32_e32 v187, 0xffff0080, v141
	v_ashrrev_i32_e32 v188, 31, v143
	v_cmp_gt_i32_e32 vcc, s10, v143
	v_mov_b32_e32 v191, v0
	v_mov_b32_e32 v193, v0
	v_cndmask_b32_e32 v189, 0, v188, vcc
	v_cndmask_b32_e32 v188, v187, v143, vcc
	v_cvt_pk_bf16_f32 v143, v62, s0
	v_cndmask_b32_e32 v190, v205, v206, vcc
	global_store_short v[144:145], v143, off offset:256
	v_cvt_pk_bf16_f32 v143, v63, s0
	v_lshl_add_u64 v[190:191], s[6:7], 0, v[190:191]
	v_lshlrev_b64 v[188:189], 12, v[188:189]
	global_store_short v[146:147], v143, off offset:1280
	v_cvt_pk_bf16_f32 v143, v64, s0
	v_lshl_add_u64 v[188:189], v[190:191], 0, v[188:189]
	global_store_short v[148:149], v143, off offset:2304
	v_cvt_pk_bf16_f32 v143, v65, s0
	global_store_short v[150:151], v143, off offset:3328
	v_lshl_add_u64 v[190:191], v[188:189], 0, v[152:153]
	v_cvt_pk_bf16_f32 v143, v58, s0
	global_store_dwordx4 v[190:191], v[62:65], off nt
	global_store_short v[154:155], v143, off offset:256
	v_cvt_pk_bf16_f32 v143, v59, s0
	global_store_short v[156:157], v143, off offset:1280
	v_cvt_pk_bf16_f32 v143, v60, s0
	global_store_short v[158:159], v143, off offset:2304
	v_cvt_pk_bf16_f32 v143, v61, s0
	global_store_short v[160:161], v143, off offset:3328
	v_lshl_add_u64 v[190:191], v[188:189], 0, v[162:163]
	v_add_u32_e32 v143, 0x90, v141
	global_store_dwordx4 v[190:191], v[58:61], off nt
	v_add_u32_e32 v187, 0xffff0090, v141
	v_ashrrev_i32_e32 v190, 31, v143
	v_cmp_gt_i32_e32 vcc, s10, v143
	s_nop 1
	v_cndmask_b32_e32 v191, 0, v190, vcc
	v_cndmask_b32_e32 v190, v187, v143, vcc
	v_cvt_pk_bf16_f32 v143, v54, s0
	v_cndmask_b32_e32 v192, v205, v206, vcc
	global_store_short v[144:145], v143, off offset:288
	v_cvt_pk_bf16_f32 v143, v55, s0
	v_lshl_add_u64 v[192:193], s[6:7], 0, v[192:193]
	v_lshlrev_b64 v[190:191], 12, v[190:191]
	global_store_short v[146:147], v143, off offset:1312
	v_cvt_pk_bf16_f32 v143, v56, s0
	v_lshl_add_u64 v[190:191], v[192:193], 0, v[190:191]
	global_store_short v[148:149], v143, off offset:2336
	v_cvt_pk_bf16_f32 v143, v57, s0
	global_store_short v[150:151], v143, off offset:3360
	v_lshl_add_u64 v[192:193], v[190:191], 0, v[152:153]
	v_cvt_pk_bf16_f32 v143, v50, s0
	global_store_dwordx4 v[192:193], v[54:57], off nt
	global_store_short v[154:155], v143, off offset:288
	v_cvt_pk_bf16_f32 v143, v51, s0
	global_store_short v[156:157], v143, off offset:1312
	v_cvt_pk_bf16_f32 v143, v52, s0
	global_store_short v[158:159], v143, off offset:2336
	v_cvt_pk_bf16_f32 v143, v53, s0
	v_lshl_add_u64 v[192:193], v[190:191], 0, v[162:163]
	global_store_short v[160:161], v143, off offset:3360
	global_store_dwordx4 v[192:193], v[50:53], off nt
	v_add_u32_e32 v143, 0xa0, v141
	v_add_u32_e32 v187, 0xffff00a0, v141
	v_ashrrev_i32_e32 v192, 31, v143
	v_cmp_gt_i32_e32 vcc, s10, v143
	v_mov_b32_e32 v195, v0
	v_mov_b32_e32 v197, v0
	v_cndmask_b32_e32 v193, 0, v192, vcc
	v_cndmask_b32_e32 v192, v187, v143, vcc
	v_cvt_pk_bf16_f32 v143, v46, s0
	v_cndmask_b32_e32 v194, v205, v206, vcc
	global_store_short v[144:145], v143, off offset:320
	v_cvt_pk_bf16_f32 v143, v47, s0
	v_lshl_add_u64 v[194:195], s[6:7], 0, v[194:195]
	v_lshlrev_b64 v[192:193], 12, v[192:193]
	global_store_short v[146:147], v143, off offset:1344
	v_cvt_pk_bf16_f32 v143, v48, s0
	v_lshl_add_u64 v[192:193], v[194:195], 0, v[192:193]
	global_store_short v[148:149], v143, off offset:2368
	v_cvt_pk_bf16_f32 v143, v49, s0
	global_store_short v[150:151], v143, off offset:3392
	v_lshl_add_u64 v[194:195], v[192:193], 0, v[152:153]
	v_cvt_pk_bf16_f32 v143, v42, s0
	global_store_dwordx4 v[194:195], v[46:49], off nt
	global_store_short v[154:155], v143, off offset:320
	v_cvt_pk_bf16_f32 v143, v43, s0
	global_store_short v[156:157], v143, off offset:1344
	v_cvt_pk_bf16_f32 v143, v44, s0
	global_store_short v[158:159], v143, off offset:2368
	v_cvt_pk_bf16_f32 v143, v45, s0
	global_store_short v[160:161], v143, off offset:3392
	v_add_u32_e32 v143, 0xb0, v141
	v_lshl_add_u64 v[194:195], v[192:193], 0, v[162:163]
	v_add_u32_e32 v141, 0xffff00b0, v141
	v_cmp_gt_i32_e32 vcc, s10, v143
	global_store_dwordx4 v[194:195], v[42:45], off nt
	v_ashrrev_i32_e32 v187, 31, v143
	v_cndmask_b32_e32 v194, v141, v143, vcc
	v_cvt_pk_bf16_f32 v141, v38, s0
	v_cndmask_b32_e32 v195, 0, v187, vcc
	v_cndmask_b32_e32 v196, v205, v206, vcc
	global_store_short v[144:145], v141, off offset:352
	v_cvt_pk_bf16_f32 v141, v39, s0
; #define GAS __attribute__((address_space(1)))
; __device__ __forceinline__ u16 f2bf(float f) { return (u16)(pack2(f, 0.f) & 0xffffu); }
; template <int MODE>
; __device__ __forceinline__ void epi_elem(char* ws, float* outp, const float* b_gate, int g0, int rl, int col, f32x4 v) {
;     ...
;   } else if (MODE == E_V) {
;     int lc = col & 1023;
;     u16* vt = (u16*)(ws + W_VT);
; #pragma unroll
;     for (int i = 0; i < 4; ++i) vt[(size_t)(lc + i) * MAXR + rl] = f2bf(v[i]);
;     int rg = g0 + rl;
;     float* o = rg < NPROMPT ? outp + O_VP + (size_t)rg * 1024 : outp + O_VS + (size_t)(rg - NPROMPT) * 1024;
;     __builtin_nontemporal_store(v, (GAS f32x4*)(o + lc));
	v_lshl_add_u64 v[196:197], s[6:7], 0, v[196:197]
	v_lshlrev_b64 v[194:195], 12, v[194:195]
	global_store_short v[146:147], v141, off offset:1376
	v_cvt_pk_bf16_f32 v141, v40, s0
	v_lshl_add_u64 v[194:195], v[196:197], 0, v[194:195]
	global_store_short v[148:149], v141, off offset:2400
	v_cvt_pk_bf16_f32 v141, v41, s0
	global_store_short v[150:151], v141, off offset:3424
	v_lshl_add_u64 v[144:145], v[194:195], 0, v[152:153]
	v_cvt_pk_bf16_f32 v141, v34, s0
	global_store_dwordx4 v[144:145], v[38:41], off nt
	global_store_short v[154:155], v141, off offset:352
	v_cvt_pk_bf16_f32 v141, v35, s0
	global_store_short v[156:157], v141, off offset:1376
	v_cvt_pk_bf16_f32 v141, v36, s0
	global_store_short v[158:159], v141, off offset:2400
	v_cvt_pk_bf16_f32 v141, v37, s0
	v_lshl_add_u64 v[144:145], v[194:195], 0, v[162:163]
	global_store_short v[160:161], v141, off offset:3424
	global_store_dwordx4 v[144:145], v[34:37], off nt
	v_cvt_pk_bf16_f32 v141, v30, s0
	global_store_short v[164:165], v141, off offset:256
	v_cvt_pk_bf16_f32 v141, v31, s0
	global_store_short v[166:167], v141, off offset:1280
	v_cvt_pk_bf16_f32 v141, v32, s0
	global_store_short v[168:169], v141, off offset:2304
	v_cvt_pk_bf16_f32 v141, v33, s0
	global_store_short v[170:171], v141, off offset:3328
	v_lshl_add_u64 v[144:145], v[188:189], 0, v[172:173]
	v_cvt_pk_bf16_f32 v141, v26, s0
	global_store_dwordx4 v[144:145], v[30:33], off nt
	global_store_short v[174:175], v141, off offset:256
	v_cvt_pk_bf16_f32 v141, v27, s0
	global_store_short v[176:177], v141, off offset:1280
	v_cvt_pk_bf16_f32 v141, v28, s0
	global_store_short v[178:179], v141, off offset:2304
	v_cvt_pk_bf16_f32 v141, v29, s0
	global_store_short v[180:181], v141, off offset:3328
	v_lshl_add_u64 v[144:145], v[188:189], 0, v[182:183]
	v_cvt_pk_bf16_f32 v141, v22, s0
	global_store_dwordx4 v[144:145], v[26:29], off nt
	global_store_short v[164:165], v141, off offset:288
	v_cvt_pk_bf16_f32 v141, v23, s0
	global_store_short v[166:167], v141, off offset:1312
	v_cvt_pk_bf16_f32 v141, v24, s0
	global_store_short v[168:169], v141, off offset:2336
	v_cvt_pk_bf16_f32 v141, v25, s0
	global_store_short v[170:171], v141, off offset:3360
	v_lshl_add_u64 v[144:145], v[190:191], 0, v[172:173]
	v_cvt_pk_bf16_f32 v141, v18, s0
	global_store_dwordx4 v[144:145], v[22:25], off nt
	global_store_short v[174:175], v141, off offset:288
	v_cvt_pk_bf16_f32 v141, v19, s0
	global_store_short v[176:177], v141, off offset:1312
	v_cvt_pk_bf16_f32 v141, v20, s0
	global_store_short v[178:179], v141, off offset:2336
	v_cvt_pk_bf16_f32 v141, v21, s0
	v_lshl_add_u64 v[144:145], v[190:191], 0, v[182:183]
	global_store_short v[180:181], v141, off offset:3360
	global_store_dwordx4 v[144:145], v[18:21], off nt
	v_cvt_pk_bf16_f32 v141, v14, s0
	global_store_short v[164:165], v141, off offset:320
	v_cvt_pk_bf16_f32 v141, v15, s0
	global_store_short v[166:167], v141, off offset:1344
	v_cvt_pk_bf16_f32 v141, v16, s0
	global_store_short v[168:169], v141, off offset:2368
	v_cvt_pk_bf16_f32 v141, v17, s0
	global_store_short v[170:171], v141, off offset:3392
	v_lshl_add_u64 v[144:145], v[192:193], 0, v[172:173]
	v_cvt_pk_bf16_f32 v141, v10, s0
	global_store_dwordx4 v[144:145], v[14:17], off nt
	global_store_short v[174:175], v141, off offset:320
	v_cvt_pk_bf16_f32 v141, v11, s0
	global_store_short v[176:177], v141, off offset:1344
	v_cvt_pk_bf16_f32 v141, v12, s0
	global_store_short v[178:179], v141, off offset:2368
	v_cvt_pk_bf16_f32 v141, v13, s0
	global_store_short v[180:181], v141, off offset:3392
	v_lshl_add_u64 v[144:145], v[192:193], 0, v[182:183]
	v_cvt_pk_bf16_f32 v141, v6, s0
	global_store_dwordx4 v[144:145], v[10:13], off nt
	global_store_short v[164:165], v141, off offset:352
	v_cvt_pk_bf16_f32 v141, v7, s0
	global_store_short v[166:167], v141, off offset:1376
	v_cvt_pk_bf16_f32 v141, v8, s0
	global_store_short v[168:169], v141, off offset:2400
	v_cvt_pk_bf16_f32 v141, v9, s0
	global_store_short v[170:171], v141, off offset:3424
	v_lshl_add_u64 v[144:145], v[194:195], 0, v[172:173]
	v_cvt_pk_bf16_f32 v141, v2, s0
	global_store_dwordx4 v[144:145], v[6:9], off nt
	global_store_short v[174:175], v141, off offset:352
	v_cvt_pk_bf16_f32 v141, v3, s0
	global_store_short v[176:177], v141, off offset:1376
	v_cvt_pk_bf16_f32 v141, v4, s0
	global_store_short v[178:179], v141, off offset:2400
	v_cvt_pk_bf16_f32 v141, v5, s0
	v_lshl_add_u64 v[144:145], v[194:195], 0, v[182:183]
	global_store_short v[180:181], v141, off offset:3424
	global_store_dwordx4 v[144:145], v[2:5], off nt

; #define GAS __attribute__((address_space(1)))
; __device__ __forceinline__ uint2 pack4(f32x4 v) { return make_uint2(pack2(v[0], v[1]), pack2(v[2], v[3])); }
; template <int MODE>
; __device__ __forceinline__ void epi_elem(char* ws, float* outp, const float* b_gate, int g0, int rl, int col, f32x4 v) {
;     ...
;   } else if (MODE == E_K) {
;     int lc = col & 1023;
;     *(GAS uint2*)((u16*)(ws + W_K) + (size_t)rl * 1024 + lc) = pack4(v);
;     int rg = g0 + rl;
;     float* o = rg < NPROMPT ? outp + O_KP + (size_t)rg * 1024 : outp + O_KS + (size_t)(rg - NPROMPT) * 1024;
;     __builtin_nontemporal_store(v, (GAS f32x4*)(o + lc));
.LBB0_980:
	s_and_b64 vcc, exec, s[12:13]
	s_cbranch_vccz .LBB0_992
	s_cmp_gt_i32 s16, 1
	s_mov_b64 s[8:9], -1
	s_cbranch_scc0 .LBB0_987
	s_cmp_gt_i32 s16, 2
	s_cbranch_scc0 .LBB0_984
	s_add_u32 s8, s2, 0x128c0000
	v_ashrrev_i32_e32 v143, 31, v142
	v_readlane_b32 s11, v255, 18
	s_addc_u32 s9, s3, 0
	v_lshlrev_b64 v[144:145], 11, v[142:143]
	v_add_u32_e32 v141, s11, v142
	s_mov_b32 s10, 0x10000
	v_lshl_add_u64 v[158:159], s[8:9], 0, v[144:145]
	v_add_u32_e32 v143, 0xffff0000, v141
	v_ashrrev_i32_e32 v144, 31, v141
	v_cmp_gt_i32_e32 vcc, s10, v141
	v_mov_b32_e32 v147, v0
	v_cvt_pk_bf16_f32 v150, v122, v123
	v_cndmask_b32_e32 v145, 0, v144, vcc
	v_cndmask_b32_e32 v144, v143, v141, vcc
	v_cndmask_b32_e32 v146, v207, v208, vcc
	v_lshl_add_u64 v[146:147], s[6:7], 0, v[146:147]
	v_lshlrev_b64 v[144:145], 12, v[144:145]
	v_and_b32_e32 v141, 0x3ff, v140
	v_lshl_add_u64 v[160:161], v[146:147], 0, v[144:145]
	v_lshlrev_b32_e32 v144, 1, v141
	v_mov_b32_e32 v145, v0
	v_cvt_pk_bf16_f32 v146, v126, v127
	v_cvt_pk_bf16_f32 v147, v128, v129
	v_lshl_add_u64 v[148:149], v[158:159], 0, v[144:145]
	global_store_dwordx2 v[148:149], v[146:147], off
	v_lshlrev_b32_e32 v146, 2, v141
	v_mov_b32_e32 v147, v0
	v_add_u32_e32 v141, 16, v140
	v_lshl_add_u64 v[148:149], v[160:161], 0, v[146:147]
	v_and_b32_e32 v141, 0x3ff, v141
	global_store_dwordx4 v[148:149], v[126:129], off nt
	v_lshlrev_b32_e32 v148, 1, v141
	v_mov_b32_e32 v149, v0
	v_cvt_pk_bf16_f32 v151, v124, v125
	v_lshl_add_u64 v[152:153], v[158:159], 0, v[148:149]
	global_store_dwordx2 v[152:153], v[150:151], off
	v_lshlrev_b32_e32 v150, 2, v141
	v_mov_b32_e32 v151, v0
	v_lshl_add_u64 v[152:153], v[160:161], 0, v[150:151]
	global_store_dwordx4 v[152:153], v[122:125], off nt
	v_add_u32_e32 v152, 16, v142
	v_ashrrev_i32_e32 v153, 31, v152
	v_add_u32_e32 v141, s11, v152
	v_lshlrev_b64 v[154:155], 11, v[152:153]
	v_add_u32_e32 v143, 0xffff0000, v141
	v_ashrrev_i32_e32 v152, 31, v141
	v_cmp_gt_i32_e32 vcc, s10, v141
	v_lshl_add_u64 v[162:163], s[8:9], 0, v[154:155]
	v_mov_b32_e32 v155, v0
	v_cndmask_b32_e32 v153, 0, v152, vcc
	v_cndmask_b32_e32 v152, v143, v141, vcc
	v_cndmask_b32_e32 v154, v207, v208, vcc
	v_lshl_add_u64 v[154:155], s[6:7], 0, v[154:155]
	v_lshlrev_b64 v[152:153], 12, v[152:153]
	v_lshl_add_u64 v[164:165], v[154:155], 0, v[152:153]
	v_cvt_pk_bf16_f32 v152, v118, v119
	v_cvt_pk_bf16_f32 v153, v120, v121
	v_lshl_add_u64 v[154:155], v[162:163], 0, v[144:145]
	global_store_dwordx2 v[154:155], v[152:153], off
	v_lshl_add_u64 v[152:153], v[164:165], 0, v[146:147]
	global_store_dwordx4 v[152:153], v[118:121], off nt
	v_cvt_pk_bf16_f32 v152, v114, v115
	v_cvt_pk_bf16_f32 v153, v116, v117
	v_lshl_add_u64 v[154:155], v[162:163], 0, v[148:149]
	global_store_dwordx2 v[154:155], v[152:153], off
	v_lshl_add_u64 v[152:153], v[164:165], 0, v[150:151]
	global_store_dwordx4 v[152:153], v[114:117], off nt
	v_add_u32_e32 v152, 32, v142
	v_ashrrev_i32_e32 v153, 31, v152
	v_add_u32_e32 v141, s11, v152
	v_lshlrev_b64 v[154:155], 11, v[152:153]
	v_add_u32_e32 v143, 0xffff0000, v141
	v_ashrrev_i32_e32 v152, 31, v141
	v_cmp_gt_i32_e32 vcc, s10, v141
	v_lshl_add_u64 v[166:167], s[8:9], 0, v[154:155]
	v_mov_b32_e32 v155, v0
	v_cndmask_b32_e32 v153, 0, v152, vcc
	v_cndmask_b32_e32 v152, v143, v141, vcc
	v_cndmask_b32_e32 v154, v207, v208, vcc
	v_lshl_add_u64 v[154:155], s[6:7], 0, v[154:155]
	v_lshlrev_b64 v[152:153], 12, v[152:153]
	v_lshl_add_u64 v[168:169], v[154:155], 0, v[152:153]
	v_cvt_pk_bf16_f32 v152, v110, v111
	v_cvt_pk_bf16_f32 v153, v112, v113
	v_lshl_add_u64 v[154:155], v[166:167], 0, v[144:145]
	global_store_dwordx2 v[154:155], v[152:153], off
	v_lshl_add_u64 v[152:153], v[168:169], 0, v[146:147]
	global_store_dwordx4 v[152:153], v[110:113], off nt
	v_cvt_pk_bf16_f32 v152, v106, v107
	v_cvt_pk_bf16_f32 v153, v108, v109
	v_lshl_add_u64 v[154:155], v[166:167], 0, v[148:149]
	global_store_dwordx2 v[154:155], v[152:153], off
	v_lshl_add_u64 v[152:153], v[168:169], 0, v[150:151]
	global_store_dwordx4 v[152:153], v[106:109], off nt
	v_add_u32_e32 v152, 48, v142
	v_ashrrev_i32_e32 v153, 31, v152
	v_add_u32_e32 v141, s11, v152
	v_lshlrev_b64 v[154:155], 11, v[152:153]
	v_add_u32_e32 v143, 0xffff0000, v141
	v_ashrrev_i32_e32 v152, 31, v141
	v_cmp_gt_i32_e32 vcc, s10, v141
	v_lshl_add_u64 v[170:171], s[8:9], 0, v[154:155]
	v_mov_b32_e32 v155, v0
	v_cndmask_b32_e32 v153, 0, v152, vcc
	v_cndmask_b32_e32 v152, v143, v141, vcc
	v_cndmask_b32_e32 v154, v207, v208, vcc
	v_lshl_add_u64 v[154:155], s[6:7], 0, v[154:155]
	v_lshlrev_b64 v[152:153], 12, v[152:153]
	v_lshl_add_u64 v[172:173], v[154:155], 0, v[152:153]
	v_cvt_pk_bf16_f32 v152, v102, v103
	v_cvt_pk_bf16_f32 v153, v104, v105
	v_lshl_add_u64 v[154:155], v[170:171], 0, v[144:145]
	global_store_dwordx2 v[154:155], v[152:153], off
	v_lshl_add_u64 v[152:153], v[172:173], 0, v[146:147]
	global_store_dwordx4 v[152:153], v[102:105], off nt
	v_cvt_pk_bf16_f32 v152, v98, v99
	v_cvt_pk_bf16_f32 v153, v100, v101
	v_lshl_add_u64 v[154:155], v[170:171], 0, v[148:149]
	global_store_dwordx2 v[154:155], v[152:153], off
	v_lshl_add_u64 v[152:153], v[172:173], 0, v[150:151]
	global_store_dwordx4 v[152:153], v[98:101], off nt
	v_add_u32_e32 v141, 0x80, v140
	v_and_b32_e32 v141, 0x3ff, v141
	v_lshlrev_b32_e32 v152, 1, v141
	v_mov_b32_e32 v153, v0
	v_cvt_pk_bf16_f32 v154, v94, v95
	v_cvt_pk_bf16_f32 v155, v96, v97
	v_lshl_add_u64 v[156:157], v[158:159], 0, v[152:153]
	global_store_dwordx2 v[156:157], v[154:155], off
	v_lshlrev_b32_e32 v154, 2, v141
	v_mov_b32_e32 v155, v0
	v_add_u32_e32 v141, 0x90, v140
	v_lshl_add_u64 v[156:157], v[160:161], 0, v[154:155]
	v_and_b32_e32 v141, 0x3ff, v141
; #define GAS __attribute__((address_space(1)))
; __device__ __forceinline__ uint2 pack4(f32x4 v) { return make_uint2(pack2(v[0], v[1]), pack2(v[2], v[3])); }
; template <int MODE>
; __device__ __forceinline__ void epi_elem(char* ws, float* outp, const float* b_gate, int g0, int rl, int col, f32x4 v) {
;     ...
;   } else if (MODE == E_K) {
;     int lc = col & 1023;
;     *(GAS uint2*)((u16*)(ws + W_K) + (size_t)rl * 1024 + lc) = pack4(v);
;     int rg = g0 + rl;
;     float* o = rg < NPROMPT ? outp + O_KP + (size_t)rg * 1024 : outp + O_KS + (size_t)(rg - NPROMPT) * 1024;
;     __builtin_nontemporal_store(v, (GAS f32x4*)(o + lc));
	global_store_dwordx4 v[156:157], v[94:97], off nt
	v_lshlrev_b32_e32 v156, 1, v141
	v_mov_b32_e32 v157, v0
	v_cvt_pk_bf16_f32 v174, v90, v91
	v_cvt_pk_bf16_f32 v175, v92, v93
	v_lshl_add_u64 v[158:159], v[158:159], 0, v[156:157]
	global_store_dwordx2 v[158:159], v[174:175], off
	v_lshlrev_b32_e32 v158, 2, v141
	v_mov_b32_e32 v159, v0
	v_lshl_add_u64 v[160:161], v[160:161], 0, v[158:159]
	global_store_dwordx4 v[160:161], v[90:93], off nt
	v_cvt_pk_bf16_f32 v160, v86, v87
	v_cvt_pk_bf16_f32 v161, v88, v89
	v_lshl_add_u64 v[174:175], v[162:163], 0, v[152:153]
	global_store_dwordx2 v[174:175], v[160:161], off
	v_lshl_add_u64 v[160:161], v[164:165], 0, v[154:155]
	global_store_dwordx4 v[160:161], v[86:89], off nt
	v_cvt_pk_bf16_f32 v160, v82, v83
	v_cvt_pk_bf16_f32 v161, v84, v85
	v_lshl_add_u64 v[162:163], v[162:163], 0, v[156:157]
	global_store_dwordx2 v[162:163], v[160:161], off
	v_lshl_add_u64 v[160:161], v[164:165], 0, v[158:159]
	global_store_dwordx4 v[160:161], v[82:85], off nt
	v_cvt_pk_bf16_f32 v160, v78, v79
	v_cvt_pk_bf16_f32 v161, v80, v81
	v_lshl_add_u64 v[162:163], v[166:167], 0, v[152:153]
	global_store_dwordx2 v[162:163], v[160:161], off
	v_lshl_add_u64 v[160:161], v[168:169], 0, v[154:155]
	global_store_dwordx4 v[160:161], v[78:81], off nt
	v_cvt_pk_bf16_f32 v160, v74, v75
	v_cvt_pk_bf16_f32 v161, v76, v77
	v_lshl_add_u64 v[162:163], v[166:167], 0, v[156:157]
	global_store_dwordx2 v[162:163], v[160:161], off
	v_lshl_add_u64 v[160:161], v[168:169], 0, v[158:159]
	global_store_dwordx4 v[160:161], v[74:77], off nt
	v_cvt_pk_bf16_f32 v160, v70, v71
	v_cvt_pk_bf16_f32 v161, v72, v73
	v_lshl_add_u64 v[162:163], v[170:171], 0, v[152:153]
	global_store_dwordx2 v[162:163], v[160:161], off
	v_lshl_add_u64 v[160:161], v[172:173], 0, v[154:155]
	global_store_dwordx4 v[160:161], v[70:73], off nt
	v_cvt_pk_bf16_f32 v160, v66, v67
	v_cvt_pk_bf16_f32 v161, v68, v69
	v_lshl_add_u64 v[162:163], v[170:171], 0, v[156:157]
	global_store_dwordx2 v[162:163], v[160:161], off
	v_lshl_add_u64 v[160:161], v[172:173], 0, v[158:159]
	global_store_dwordx4 v[160:161], v[66:69], off nt
	v_add_u32_e32 v160, 0x80, v142
	v_ashrrev_i32_e32 v161, 31, v160
	v_add_u32_e32 v141, s11, v160
	v_lshlrev_b64 v[162:163], 11, v[160:161]
	v_add_u32_e32 v143, 0xffff0000, v141
	v_ashrrev_i32_e32 v160, 31, v141
	v_cmp_gt_i32_e32 vcc, s10, v141
	v_mov_b32_e32 v165, v0
	v_lshl_add_u64 v[162:163], s[8:9], 0, v[162:163]
	v_cndmask_b32_e32 v161, 0, v160, vcc
	v_cndmask_b32_e32 v160, v143, v141, vcc
	v_cndmask_b32_e32 v164, v207, v208, vcc
	v_lshl_add_u64 v[164:165], s[6:7], 0, v[164:165]
	v_lshlrev_b64 v[160:161], 12, v[160:161]
	v_lshl_add_u64 v[160:161], v[164:165], 0, v[160:161]
	v_cvt_pk_bf16_f32 v164, v62, v63
	v_cvt_pk_bf16_f32 v165, v64, v65
	v_lshl_add_u64 v[166:167], v[162:163], 0, v[144:145]
	global_store_dwordx2 v[166:167], v[164:165], off
	v_lshl_add_u64 v[164:165], v[160:161], 0, v[146:147]
	global_store_dwordx4 v[164:165], v[62:65], off nt
	v_cvt_pk_bf16_f32 v164, v58, v59
	v_cvt_pk_bf16_f32 v165, v60, v61
	v_lshl_add_u64 v[166:167], v[162:163], 0, v[148:149]
	global_store_dwordx2 v[166:167], v[164:165], off
	v_lshl_add_u64 v[164:165], v[160:161], 0, v[150:151]
	global_store_dwordx4 v[164:165], v[58:61], off nt
	v_add_u32_e32 v164, 0x90, v142
	v_ashrrev_i32_e32 v165, 31, v164
	v_add_u32_e32 v141, s11, v164
	v_lshlrev_b64 v[166:167], 11, v[164:165]
	v_add_u32_e32 v143, 0xffff0000, v141
	v_ashrrev_i32_e32 v164, 31, v141
	v_cmp_gt_i32_e32 vcc, s10, v141
	v_mov_b32_e32 v169, v0
	v_lshl_add_u64 v[166:167], s[8:9], 0, v[166:167]
	v_cndmask_b32_e32 v165, 0, v164, vcc
	v_cndmask_b32_e32 v164, v143, v141, vcc
	v_cndmask_b32_e32 v168, v207, v208, vcc
	v_lshl_add_u64 v[168:169], s[6:7], 0, v[168:169]
	v_lshlrev_b64 v[164:165], 12, v[164:165]
	v_lshl_add_u64 v[164:165], v[168:169], 0, v[164:165]
	v_cvt_pk_bf16_f32 v168, v54, v55
	v_cvt_pk_bf16_f32 v169, v56, v57
	v_lshl_add_u64 v[170:171], v[166:167], 0, v[144:145]
	global_store_dwordx2 v[170:171], v[168:169], off
	v_lshl_add_u64 v[168:169], v[164:165], 0, v[146:147]
	global_store_dwordx4 v[168:169], v[54:57], off nt
	v_cvt_pk_bf16_f32 v168, v50, v51
	v_cvt_pk_bf16_f32 v169, v52, v53
	v_lshl_add_u64 v[170:171], v[166:167], 0, v[148:149]
	global_store_dwordx2 v[170:171], v[168:169], off
	v_lshl_add_u64 v[168:169], v[164:165], 0, v[150:151]
	global_store_dwordx4 v[168:169], v[50:53], off nt
	v_add_u32_e32 v168, 0xa0, v142
	v_ashrrev_i32_e32 v169, 31, v168
	v_add_u32_e32 v141, s11, v168
	v_lshlrev_b64 v[170:171], 11, v[168:169]
	v_add_u32_e32 v143, 0xffff0000, v141
	v_ashrrev_i32_e32 v168, 31, v141
	v_cmp_gt_i32_e32 vcc, s10, v141
	v_mov_b32_e32 v173, v0
	v_lshl_add_u64 v[170:171], s[8:9], 0, v[170:171]
	v_cndmask_b32_e32 v169, 0, v168, vcc
	v_cndmask_b32_e32 v168, v143, v141, vcc
	v_cndmask_b32_e32 v172, v207, v208, vcc
	v_lshl_add_u64 v[172:173], s[6:7], 0, v[172:173]
	v_lshlrev_b64 v[168:169], 12, v[168:169]
	v_lshl_add_u64 v[168:169], v[172:173], 0, v[168:169]
	v_cvt_pk_bf16_f32 v172, v46, v47
	v_cvt_pk_bf16_f32 v173, v48, v49
	v_lshl_add_u64 v[174:175], v[170:171], 0, v[144:145]
	global_store_dwordx2 v[174:175], v[172:173], off
	v_lshl_add_u64 v[172:173], v[168:169], 0, v[146:147]
	global_store_dwordx4 v[172:173], v[46:49], off nt
	v_cvt_pk_bf16_f32 v172, v42, v43
	v_cvt_pk_bf16_f32 v173, v44, v45
	v_lshl_add_u64 v[174:175], v[170:171], 0, v[148:149]
	global_store_dwordx2 v[174:175], v[172:173], off
	v_lshl_add_u64 v[172:173], v[168:169], 0, v[150:151]
	global_store_dwordx4 v[172:173], v[42:45], off nt
	v_add_u32_e32 v172, 0xb0, v142
	v_ashrrev_i32_e32 v173, 31, v172
	v_add_u32_e32 v141, s11, v172
	v_lshlrev_b64 v[174:175], 11, v[172:173]
; #define GAS __attribute__((address_space(1)))
; __device__ __forceinline__ uint2 pack4(f32x4 v) { return make_uint2(pack2(v[0], v[1]), pack2(v[2], v[3])); }
; template <int MODE>
; __device__ __forceinline__ void epi_elem(char* ws, float* outp, const float* b_gate, int g0, int rl, int col, f32x4 v) {
;     ...
;   } else if (MODE == E_Q) {
;     int lc = col & 1023;
;     f32x4 o = v * 0.18033688011112042f;
;     *(GAS uint2*)((u16*)(ws + W_Q) + (size_t)rl * 1024 + lc) = pack4(o);
;   } else if (MODE == E_K) {
;     int lc = col & 1023;
;     *(GAS uint2*)((u16*)(ws + W_K) + (size_t)rl * 1024 + lc) = pack4(v);
;     int rg = g0 + rl;
;     float* o = rg < NPROMPT ? outp + O_KP + (size_t)rg * 1024 : outp + O_KS + (size_t)(rg - NPROMPT) * 1024;
;     __builtin_nontemporal_store(v, (GAS f32x4*)(o + lc));
	v_add_u32_e32 v143, 0xffff0000, v141
	v_ashrrev_i32_e32 v172, 31, v141
	v_cmp_gt_i32_e32 vcc, s10, v141
	v_mov_b32_e32 v177, v0
	v_lshl_add_u64 v[174:175], s[8:9], 0, v[174:175]
	v_cndmask_b32_e32 v173, 0, v172, vcc
	v_cndmask_b32_e32 v172, v143, v141, vcc
	v_cndmask_b32_e32 v176, v207, v208, vcc
	v_lshl_add_u64 v[176:177], s[6:7], 0, v[176:177]
	v_lshlrev_b64 v[172:173], 12, v[172:173]
	v_lshl_add_u64 v[172:173], v[176:177], 0, v[172:173]
	v_cvt_pk_bf16_f32 v176, v38, v39
	v_cvt_pk_bf16_f32 v177, v40, v41
	v_lshl_add_u64 v[144:145], v[174:175], 0, v[144:145]
	global_store_dwordx2 v[144:145], v[176:177], off
	v_lshl_add_u64 v[144:145], v[172:173], 0, v[146:147]
	global_store_dwordx4 v[144:145], v[38:41], off nt
	v_cvt_pk_bf16_f32 v144, v34, v35
	v_cvt_pk_bf16_f32 v145, v36, v37
	v_lshl_add_u64 v[146:147], v[174:175], 0, v[148:149]
	global_store_dwordx2 v[146:147], v[144:145], off
	v_lshl_add_u64 v[144:145], v[172:173], 0, v[150:151]
	global_store_dwordx4 v[144:145], v[34:37], off nt
	v_cvt_pk_bf16_f32 v144, v30, v31
	v_cvt_pk_bf16_f32 v145, v32, v33
	v_lshl_add_u64 v[146:147], v[162:163], 0, v[152:153]
	global_store_dwordx2 v[146:147], v[144:145], off
	v_lshl_add_u64 v[144:145], v[160:161], 0, v[154:155]
	global_store_dwordx4 v[144:145], v[30:33], off nt
	v_cvt_pk_bf16_f32 v144, v26, v27
	v_cvt_pk_bf16_f32 v145, v28, v29
	v_lshl_add_u64 v[146:147], v[162:163], 0, v[156:157]
	global_store_dwordx2 v[146:147], v[144:145], off
	v_lshl_add_u64 v[144:145], v[160:161], 0, v[158:159]
	global_store_dwordx4 v[144:145], v[26:29], off nt
	v_cvt_pk_bf16_f32 v144, v22, v23
	v_cvt_pk_bf16_f32 v145, v24, v25
	v_lshl_add_u64 v[146:147], v[166:167], 0, v[152:153]
	global_store_dwordx2 v[146:147], v[144:145], off
	v_lshl_add_u64 v[144:145], v[164:165], 0, v[154:155]
	global_store_dwordx4 v[144:145], v[22:25], off nt
	v_cvt_pk_bf16_f32 v144, v18, v19
	v_cvt_pk_bf16_f32 v145, v20, v21
	v_lshl_add_u64 v[146:147], v[166:167], 0, v[156:157]
	global_store_dwordx2 v[146:147], v[144:145], off
	v_lshl_add_u64 v[144:145], v[164:165], 0, v[158:159]
	global_store_dwordx4 v[144:145], v[18:21], off nt
	v_cvt_pk_bf16_f32 v144, v14, v15
	v_cvt_pk_bf16_f32 v145, v16, v17
	v_lshl_add_u64 v[146:147], v[170:171], 0, v[152:153]
	global_store_dwordx2 v[146:147], v[144:145], off
	v_lshl_add_u64 v[144:145], v[168:169], 0, v[154:155]
	global_store_dwordx4 v[144:145], v[14:17], off nt
	v_cvt_pk_bf16_f32 v144, v10, v11
	v_cvt_pk_bf16_f32 v145, v12, v13
	v_lshl_add_u64 v[146:147], v[170:171], 0, v[156:157]
	global_store_dwordx2 v[146:147], v[144:145], off
	v_lshl_add_u64 v[144:145], v[168:169], 0, v[158:159]
	global_store_dwordx4 v[144:145], v[10:13], off nt
	v_cvt_pk_bf16_f32 v144, v6, v7
	v_cvt_pk_bf16_f32 v145, v8, v9
	v_lshl_add_u64 v[146:147], v[174:175], 0, v[152:153]
	global_store_dwordx2 v[146:147], v[144:145], off
	v_lshl_add_u64 v[144:145], v[172:173], 0, v[154:155]
	global_store_dwordx4 v[144:145], v[6:9], off nt
	v_cvt_pk_bf16_f32 v144, v2, v3
	v_cvt_pk_bf16_f32 v145, v4, v5
	v_lshl_add_u64 v[146:147], v[174:175], 0, v[156:157]
	global_store_dwordx2 v[146:147], v[144:145], off
	v_lshl_add_u64 v[144:145], v[172:173], 0, v[158:159]
	global_store_dwordx4 v[144:145], v[2:5], off nt
	s_mov_b64 s[8:9], 0
.LBB0_984:
	s_andn2_b64 vcc, exec, s[8:9]
	s_cbranch_vccnz .LBB0_986
	v_ashrrev_i32_e32 v143, 31, v142
	v_lshlrev_b64 v[144:145], 11, v[142:143]
	v_lshl_add_u64 v[144:145], s[2:3], 0, v[144:145]
	s_mov_b64 s[6:7], 0xe7c0000
	v_lshl_add_u64 v[148:149], v[144:145], 0, s[6:7]
	s_mov_b32 s6, 0x3e38aa3b
	v_and_b32_e32 v141, 0x3ff, v140
	v_pk_mul_f32 v[146:147], v[128:129], s[6:7] op_sel_hi:[1,0]
	v_pk_mul_f32 v[150:151], v[126:127], s[6:7] op_sel_hi:[1,0]
	s_mov_b64 s[8:9], 0xe7c8000
	v_cvt_pk_bf16_f32 v150, v150, v151
	v_cvt_pk_bf16_f32 v151, v146, v147
	v_lshlrev_b32_e32 v146, 1, v141
	v_mov_b32_e32 v147, v0
	v_lshl_add_u64 v[152:153], v[148:149], 0, v[146:147]
	v_add_u32_e32 v141, 16, v140
	global_store_dwordx2 v[152:153], v[150:151], off
	v_and_b32_e32 v141, 0x3ff, v141
	v_pk_mul_f32 v[150:151], v[124:125], s[6:7] op_sel_hi:[1,0]
	v_pk_mul_f32 v[152:153], v[122:123], s[6:7] op_sel_hi:[1,0]
	v_pk_mul_f32 v[156:157], v[118:119], s[6:7] op_sel_hi:[1,0]
	v_cvt_pk_bf16_f32 v152, v152, v153
	v_cvt_pk_bf16_f32 v153, v150, v151
	v_lshlrev_b32_e32 v150, 1, v141
	v_mov_b32_e32 v151, v0
	v_lshl_add_u64 v[154:155], v[148:149], 0, v[150:151]
	global_store_dwordx2 v[154:155], v[152:153], off
	v_lshl_add_u64 v[152:153], v[144:145], 0, s[8:9]
	v_pk_mul_f32 v[154:155], v[120:121], s[6:7] op_sel_hi:[1,0]
	v_cvt_pk_bf16_f32 v156, v156, v157
	v_cvt_pk_bf16_f32 v157, v154, v155
	v_lshl_add_u64 v[154:155], v[152:153], 0, v[146:147]
	global_store_dwordx2 v[154:155], v[156:157], off
	v_pk_mul_f32 v[154:155], v[116:117], s[6:7] op_sel_hi:[1,0]
	v_pk_mul_f32 v[156:157], v[114:115], s[6:7] op_sel_hi:[1,0]
	s_nop 0
	v_cvt_pk_bf16_f32 v156, v156, v157
	v_cvt_pk_bf16_f32 v157, v154, v155
	v_lshl_add_u64 v[154:155], v[152:153], 0, v[150:151]
	global_store_dwordx2 v[154:155], v[156:157], off
	s_mov_b64 s[8:9], 0xe7d0000
	v_lshl_add_u64 v[154:155], v[144:145], 0, s[8:9]
	v_pk_mul_f32 v[156:157], v[112:113], s[6:7] op_sel_hi:[1,0]
	v_pk_mul_f32 v[158:159], v[110:111], s[6:7] op_sel_hi:[1,0]
	s_mov_b64 s[8:9], 0xe7d8000
	v_cvt_pk_bf16_f32 v158, v158, v159
	v_cvt_pk_bf16_f32 v159, v156, v157
	v_lshl_add_u64 v[156:157], v[154:155], 0, v[146:147]
	global_store_dwordx2 v[156:157], v[158:159], off
	v_pk_mul_f32 v[156:157], v[108:109], s[6:7] op_sel_hi:[1,0]
	v_pk_mul_f32 v[158:159], v[106:107], s[6:7] op_sel_hi:[1,0]
	v_pk_mul_f32 v[160:161], v[102:103], s[6:7] op_sel_hi:[1,0]
	v_cvt_pk_bf16_f32 v158, v158, v159
; #define GAS __attribute__((address_space(1)))
; __device__ __forceinline__ uint2 pack4(f32x4 v) { return make_uint2(pack2(v[0], v[1]), pack2(v[2], v[3])); }
; template <int MODE>
; __device__ __forceinline__ void epi_elem(char* ws, float* outp, const float* b_gate, int g0, int rl, int col, f32x4 v) {
;     ...
;   } else if (MODE == E_Q) {
;     int lc = col & 1023;
;     f32x4 o = v * 0.18033688011112042f;
;     *(GAS uint2*)((u16*)(ws + W_Q) + (size_t)rl * 1024 + lc) = pack4(o);
; template <int MODE>
; __device__ __forceinline__ void epi_store(char* ws, float* outp, const float* b_gate, int g0, const f32x4 (&acc)[2][2][4][2], int rbase, int cbase) {
; #pragma unroll
;   for (int ai = 0; ai < 2; ++ai)
; #pragma unroll
;     for (int bj = 0; bj < 2; ++bj)
; #pragma unroll
;       for (int m = 0; m < 4; ++m) {
; #pragma unroll
;         for (int n = 0; n < 2; ++n)
;           epi_elem<MODE>(ws, outp, b_gate, g0, rbase + ai * HALF + m * 16, cbase + bj * HALF + n * 16, acc[ai][bj][m][n]);
;         if ((m & 1) && (MODE != E_M1 && MODE != E_MG)) __builtin_amdgcn_sched_barrier(0);
;         if (m == 3 && (MODE == E_M1 || MODE == E_MG)) __builtin_amdgcn_sched_barrier(0);
	v_cvt_pk_bf16_f32 v159, v156, v157
	v_lshl_add_u64 v[156:157], v[154:155], 0, v[150:151]
	global_store_dwordx2 v[156:157], v[158:159], off
	v_lshl_add_u64 v[156:157], v[144:145], 0, s[8:9]
	v_pk_mul_f32 v[158:159], v[104:105], s[6:7] op_sel_hi:[1,0]
	v_cvt_pk_bf16_f32 v160, v160, v161
	v_cvt_pk_bf16_f32 v161, v158, v159
	v_lshl_add_u64 v[158:159], v[156:157], 0, v[146:147]
	global_store_dwordx2 v[158:159], v[160:161], off
	v_pk_mul_f32 v[158:159], v[100:101], s[6:7] op_sel_hi:[1,0]
	v_pk_mul_f32 v[160:161], v[98:99], s[6:7] op_sel_hi:[1,0]
	s_nop 0
	v_cvt_pk_bf16_f32 v160, v160, v161
	v_cvt_pk_bf16_f32 v161, v158, v159
	v_lshl_add_u64 v[158:159], v[156:157], 0, v[150:151]
	global_store_dwordx2 v[158:159], v[160:161], off
	v_add_u32_e32 v141, 0x80, v140
	v_and_b32_e32 v141, 0x3ff, v141
	v_pk_mul_f32 v[158:159], v[96:97], s[6:7] op_sel_hi:[1,0]
	v_pk_mul_f32 v[160:161], v[94:95], s[6:7] op_sel_hi:[1,0]
	s_nop 0
	v_cvt_pk_bf16_f32 v160, v160, v161
	v_cvt_pk_bf16_f32 v161, v158, v159
	v_lshlrev_b32_e32 v158, 1, v141
	v_mov_b32_e32 v159, v0
	v_lshl_add_u64 v[162:163], v[148:149], 0, v[158:159]
	v_add_u32_e32 v141, 0x90, v140
	global_store_dwordx2 v[162:163], v[160:161], off
	v_and_b32_e32 v141, 0x3ff, v141
	v_pk_mul_f32 v[160:161], v[92:93], s[6:7] op_sel_hi:[1,0]
	v_pk_mul_f32 v[162:163], v[90:91], s[6:7] op_sel_hi:[1,0]
	s_nop 0
	v_cvt_pk_bf16_f32 v162, v162, v163
	v_cvt_pk_bf16_f32 v163, v160, v161
	v_lshlrev_b32_e32 v160, 1, v141
	v_mov_b32_e32 v161, v0
	v_lshl_add_u64 v[148:149], v[148:149], 0, v[160:161]
	global_store_dwordx2 v[148:149], v[162:163], off
	v_pk_mul_f32 v[148:149], v[88:89], s[6:7] op_sel_hi:[1,0]
	v_pk_mul_f32 v[162:163], v[86:87], s[6:7] op_sel_hi:[1,0]
	s_nop 0
	v_cvt_pk_bf16_f32 v162, v162, v163
	v_cvt_pk_bf16_f32 v163, v148, v149
	v_lshl_add_u64 v[148:149], v[152:153], 0, v[158:159]
	global_store_dwordx2 v[148:149], v[162:163], off
	v_pk_mul_f32 v[148:149], v[84:85], s[6:7] op_sel_hi:[1,0]
	v_pk_mul_f32 v[162:163], v[82:83], s[6:7] op_sel_hi:[1,0]
	s_nop 0
	v_cvt_pk_bf16_f32 v162, v162, v163
	v_cvt_pk_bf16_f32 v163, v148, v149
	v_lshl_add_u64 v[148:149], v[152:153], 0, v[160:161]
	global_store_dwordx2 v[148:149], v[162:163], off
	v_pk_mul_f32 v[148:149], v[80:81], s[6:7] op_sel_hi:[1,0]
	v_pk_mul_f32 v[152:153], v[78:79], s[6:7] op_sel_hi:[1,0]
	s_nop 0
	v_cvt_pk_bf16_f32 v152, v152, v153
	v_cvt_pk_bf16_f32 v153, v148, v149
	v_lshl_add_u64 v[148:149], v[154:155], 0, v[158:159]
	global_store_dwordx2 v[148:149], v[152:153], off
	v_pk_mul_f32 v[148:149], v[76:77], s[6:7] op_sel_hi:[1,0]
	v_pk_mul_f32 v[152:153], v[74:75], s[6:7] op_sel_hi:[1,0]
	s_nop 0
	v_cvt_pk_bf16_f32 v152, v152, v153
	v_cvt_pk_bf16_f32 v153, v148, v149
	v_lshl_add_u64 v[148:149], v[154:155], 0, v[160:161]
	global_store_dwordx2 v[148:149], v[152:153], off
	v_pk_mul_f32 v[148:149], v[72:73], s[6:7] op_sel_hi:[1,0]
	v_pk_mul_f32 v[152:153], v[70:71], s[6:7] op_sel_hi:[1,0]
	s_nop 0
	v_cvt_pk_bf16_f32 v152, v152, v153
	v_cvt_pk_bf16_f32 v153, v148, v149
	v_lshl_add_u64 v[148:149], v[156:157], 0, v[158:159]
	global_store_dwordx2 v[148:149], v[152:153], off
	v_pk_mul_f32 v[148:149], v[68:69], s[6:7] op_sel_hi:[1,0]
	v_pk_mul_f32 v[152:153], v[66:67], s[6:7] op_sel_hi:[1,0]
	s_nop 0
	v_cvt_pk_bf16_f32 v152, v152, v153
	v_cvt_pk_bf16_f32 v153, v148, v149
	v_lshl_add_u64 v[148:149], v[156:157], 0, v[160:161]
	global_store_dwordx2 v[148:149], v[152:153], off
	s_mov_b64 s[8:9], 0xe800000
	v_lshl_add_u64 v[148:149], v[144:145], 0, s[8:9]
	v_pk_mul_f32 v[152:153], v[64:65], s[6:7] op_sel_hi:[1,0]
	v_pk_mul_f32 v[154:155], v[62:63], s[6:7] op_sel_hi:[1,0]
	s_mov_b64 s[8:9], 0xe808000
	v_cvt_pk_bf16_f32 v154, v154, v155
	v_cvt_pk_bf16_f32 v155, v152, v153
	v_lshl_add_u64 v[152:153], v[148:149], 0, v[146:147]
	global_store_dwordx2 v[152:153], v[154:155], off
	v_pk_mul_f32 v[152:153], v[60:61], s[6:7] op_sel_hi:[1,0]
	v_pk_mul_f32 v[154:155], v[58:59], s[6:7] op_sel_hi:[1,0]
	v_pk_mul_f32 v[156:157], v[54:55], s[6:7] op_sel_hi:[1,0]
	v_cvt_pk_bf16_f32 v154, v154, v155
	v_cvt_pk_bf16_f32 v155, v152, v153
	v_lshl_add_u64 v[152:153], v[148:149], 0, v[150:151]
	global_store_dwordx2 v[152:153], v[154:155], off
	v_lshl_add_u64 v[152:153], v[144:145], 0, s[8:9]
	v_pk_mul_f32 v[154:155], v[56:57], s[6:7] op_sel_hi:[1,0]
; #define GAS __attribute__((address_space(1)))
; __device__ __forceinline__ uint2 pack4(f32x4 v) { return make_uint2(pack2(v[0], v[1]), pack2(v[2], v[3])); }
; template <int MODE>
; __device__ __forceinline__ void epi_elem(char* ws, float* outp, const float* b_gate, int g0, int rl, int col, f32x4 v) {
;     ...
;   } else if (MODE == E_Q) {
;     int lc = col & 1023;
;     f32x4 o = v * 0.18033688011112042f;
;     *(GAS uint2*)((u16*)(ws + W_Q) + (size_t)rl * 1024 + lc) = pack4(o);
; template <int MODE>
; __device__ __forceinline__ void epi_store(char* ws, float* outp, const float* b_gate, int g0, const f32x4 (&acc)[2][2][4][2], int rbase, int cbase) {
; #pragma unroll
;   for (int ai = 0; ai < 2; ++ai)
; #pragma unroll
;     for (int bj = 0; bj < 2; ++bj)
; #pragma unroll
;       for (int m = 0; m < 4; ++m) {
; #pragma unroll
;         for (int n = 0; n < 2; ++n)
;           epi_elem<MODE>(ws, outp, b_gate, g0, rbase + ai * HALF + m * 16, cbase + bj * HALF + n * 16, acc[ai][bj][m][n]);
;         if ((m & 1) && (MODE != E_M1 && MODE != E_MG)) __builtin_amdgcn_sched_barrier(0);
;         if (m == 3 && (MODE == E_M1 || MODE == E_MG)) __builtin_amdgcn_sched_barrier(0);
	v_cvt_pk_bf16_f32 v156, v156, v157
	v_cvt_pk_bf16_f32 v157, v154, v155
	v_lshl_add_u64 v[154:155], v[152:153], 0, v[146:147]
	global_store_dwordx2 v[154:155], v[156:157], off
	v_pk_mul_f32 v[154:155], v[52:53], s[6:7] op_sel_hi:[1,0]
	v_pk_mul_f32 v[156:157], v[50:51], s[6:7] op_sel_hi:[1,0]
	s_nop 0
	v_cvt_pk_bf16_f32 v156, v156, v157
	v_cvt_pk_bf16_f32 v157, v154, v155
	v_lshl_add_u64 v[154:155], v[152:153], 0, v[150:151]
	global_store_dwordx2 v[154:155], v[156:157], off
	s_mov_b64 s[8:9], 0xe810000
	v_lshl_add_u64 v[154:155], v[144:145], 0, s[8:9]
	v_pk_mul_f32 v[156:157], v[48:49], s[6:7] op_sel_hi:[1,0]
	v_pk_mul_f32 v[162:163], v[46:47], s[6:7] op_sel_hi:[1,0]
	s_mov_b64 s[8:9], 0xe818000
	v_cvt_pk_bf16_f32 v162, v162, v163
	v_cvt_pk_bf16_f32 v163, v156, v157
	v_lshl_add_u64 v[156:157], v[154:155], 0, v[146:147]
	global_store_dwordx2 v[156:157], v[162:163], off
	v_pk_mul_f32 v[156:157], v[44:45], s[6:7] op_sel_hi:[1,0]
	v_pk_mul_f32 v[162:163], v[42:43], s[6:7] op_sel_hi:[1,0]
	v_lshl_add_u64 v[144:145], v[144:145], 0, s[8:9]
	v_cvt_pk_bf16_f32 v162, v162, v163
	v_cvt_pk_bf16_f32 v163, v156, v157
	v_lshl_add_u64 v[156:157], v[154:155], 0, v[150:151]
	global_store_dwordx2 v[156:157], v[162:163], off
	v_pk_mul_f32 v[156:157], v[40:41], s[6:7] op_sel_hi:[1,0]
	v_pk_mul_f32 v[162:163], v[38:39], s[6:7] op_sel_hi:[1,0]
	v_lshl_add_u64 v[146:147], v[144:145], 0, v[146:147]
	v_cvt_pk_bf16_f32 v162, v162, v163
	v_cvt_pk_bf16_f32 v163, v156, v157
	global_store_dwordx2 v[146:147], v[162:163], off
	v_pk_mul_f32 v[146:147], v[36:37], s[6:7] op_sel_hi:[1,0]
	v_pk_mul_f32 v[156:157], v[34:35], s[6:7] op_sel_hi:[1,0]
	s_nop 0
	v_cvt_pk_bf16_f32 v156, v156, v157
	v_cvt_pk_bf16_f32 v157, v146, v147
	v_lshl_add_u64 v[146:147], v[144:145], 0, v[150:151]
	global_store_dwordx2 v[146:147], v[156:157], off
	v_pk_mul_f32 v[146:147], v[32:33], s[6:7] op_sel_hi:[1,0]
	v_pk_mul_f32 v[150:151], v[30:31], s[6:7] op_sel_hi:[1,0]
	s_nop 0
	v_cvt_pk_bf16_f32 v150, v150, v151
	v_cvt_pk_bf16_f32 v151, v146, v147
	v_lshl_add_u64 v[146:147], v[148:149], 0, v[158:159]
	global_store_dwordx2 v[146:147], v[150:151], off
	v_pk_mul_f32 v[146:147], v[28:29], s[6:7] op_sel_hi:[1,0]
	v_pk_mul_f32 v[150:151], v[26:27], s[6:7] op_sel_hi:[1,0]
	s_nop 0
	v_cvt_pk_bf16_f32 v150, v150, v151
	v_cvt_pk_bf16_f32 v151, v146, v147
	v_lshl_add_u64 v[146:147], v[148:149], 0, v[160:161]
	global_store_dwordx2 v[146:147], v[150:151], off
	v_pk_mul_f32 v[146:147], v[24:25], s[6:7] op_sel_hi:[1,0]
	v_pk_mul_f32 v[148:149], v[22:23], s[6:7] op_sel_hi:[1,0]
	s_nop 0
	v_cvt_pk_bf16_f32 v148, v148, v149
	v_cvt_pk_bf16_f32 v149, v146, v147
	v_lshl_add_u64 v[146:147], v[152:153], 0, v[158:159]
	global_store_dwordx2 v[146:147], v[148:149], off
	v_pk_mul_f32 v[146:147], v[20:21], s[6:7] op_sel_hi:[1,0]
	v_pk_mul_f32 v[148:149], v[18:19], s[6:7] op_sel_hi:[1,0]
	s_nop 0
	v_cvt_pk_bf16_f32 v148, v148, v149
	v_cvt_pk_bf16_f32 v149, v146, v147
	v_lshl_add_u64 v[146:147], v[152:153], 0, v[160:161]
	global_store_dwordx2 v[146:147], v[148:149], off
	v_pk_mul_f32 v[146:147], v[16:17], s[6:7] op_sel_hi:[1,0]
	v_pk_mul_f32 v[148:149], v[14:15], s[6:7] op_sel_hi:[1,0]
	s_nop 0
	v_cvt_pk_bf16_f32 v148, v148, v149
	v_cvt_pk_bf16_f32 v149, v146, v147
	v_lshl_add_u64 v[146:147], v[154:155], 0, v[158:159]
	global_store_dwordx2 v[146:147], v[148:149], off
	v_pk_mul_f32 v[146:147], v[12:13], s[6:7] op_sel_hi:[1,0]
	v_pk_mul_f32 v[148:149], v[10:11], s[6:7] op_sel_hi:[1,0]
	s_nop 0
	v_cvt_pk_bf16_f32 v148, v148, v149
	v_cvt_pk_bf16_f32 v149, v146, v147
	v_lshl_add_u64 v[146:147], v[154:155], 0, v[160:161]
	global_store_dwordx2 v[146:147], v[148:149], off
	v_pk_mul_f32 v[146:147], v[8:9], s[6:7] op_sel_hi:[1,0]
	v_pk_mul_f32 v[148:149], v[6:7], s[6:7] op_sel_hi:[1,0]
	s_nop 0
	v_cvt_pk_bf16_f32 v148, v148, v149
	v_cvt_pk_bf16_f32 v149, v146, v147
	v_lshl_add_u64 v[146:147], v[144:145], 0, v[158:159]
	global_store_dwordx2 v[146:147], v[148:149], off
	v_pk_mul_f32 v[146:147], v[4:5], s[6:7] op_sel_hi:[1,0]
	v_pk_mul_f32 v[148:149], v[2:3], s[6:7] op_sel_hi:[1,0]
	v_lshl_add_u64 v[144:145], v[144:145], 0, v[160:161]
	v_cvt_pk_bf16_f32 v148, v148, v149
	v_cvt_pk_bf16_f32 v149, v146, v147
	global_store_dwordx2 v[144:145], v[148:149], off

; #define GAS __attribute__((address_space(1)))
; __device__ __forceinline__ uint2 pack4(f32x4 v) { return make_uint2(pack2(v[0], v[1]), pack2(v[2], v[3])); }
; __device__ __forceinline__ float gelu_f(float x) {
;   const float c1 = -1.5957691216057308f * 1.4426950408889634f, c2 = c1 * 0.044715f;
;   float u = x * __builtin_fmaf(x * x, c2, c1);
;   return x * __builtin_amdgcn_rcpf(1.0f + __builtin_amdgcn_exp2f(u));
; }
; template <int MODE>
; __device__ __forceinline__ void epi_elem(char* ws, float* outp, const float* b_gate, int g0, int rl, int col, f32x4 v) {
;   if (MODE == E_U || MODE == E_GV) {
;     int lc = col & 1023;
;     f32x4 o; for (int i = 0; i < 4; ++i) o[i] = gelu_f(v[i]);
;     u16* dst = (u16*)(ws + (MODE == E_U ? W_U : W_GV));
;     *(GAS uint2*)(dst + (size_t)rl * 1024 + lc) = pack4(o);
.LBB0_987:
	s_andn2_b64 vcc, exec, s[8:9]
	s_mov_b64 s[8:9], 0
	s_cbranch_vccnz .LBB0_992
	s_cmp_gt_i32 s16, 0
	s_mov_b64 s[6:7], -1
	s_cbranch_scc0 .LBB0_990
	v_mul_f32_e32 v141, v126, v126
	v_fmamk_f32 v141, v141, 0xbdd2d3e7, v198
	v_mul_f32_e32 v141, v126, v141
	v_exp_f32_e32 v141, v141
	v_ashrrev_i32_e32 v143, 31, v142
	v_lshlrev_b64 v[144:145], 11, v[142:143]
	v_mul_f32_e32 v143, v122, v122
	v_add_f32_e32 v141, 1.0, v141
	v_rcp_f32_e32 v146, v141
	v_mul_f32_e32 v141, v127, v127
	v_fmamk_f32 v141, v141, 0xbdd2d3e7, v198
	v_mul_f32_e32 v141, v127, v141
	v_exp_f32_e32 v141, v141
	v_fmamk_f32 v143, v143, 0xbdd2d3e7, v198
	v_mul_f32_e32 v143, v122, v143
	v_exp_f32_e32 v143, v143
	v_add_f32_e32 v141, 1.0, v141
	v_rcp_f32_e32 v147, v141
	v_mul_f32_e32 v141, v128, v128
	v_fmamk_f32 v141, v141, 0xbdd2d3e7, v198
	v_mul_f32_e32 v141, v128, v141
	v_exp_f32_e32 v141, v141
	v_lshl_add_u64 v[144:145], s[2:3], 0, v[144:145]
	s_mov_b64 s[6:7], 0xa6c0000
	v_pk_mul_f32 v[146:147], v[126:127], v[146:147]
	v_add_f32_e32 v141, 1.0, v141
	v_rcp_f32_e32 v148, v141
	v_mul_f32_e32 v141, v129, v129
	v_fmamk_f32 v141, v141, 0xbdd2d3e7, v198
	v_mul_f32_e32 v141, v129, v141
	v_exp_f32_e32 v141, v141
	v_lshl_add_u64 v[154:155], v[144:145], 0, s[6:7]
	v_cvt_pk_bf16_f32 v150, v146, v147
	v_mov_b32_e32 v147, v0
	v_add_f32_e32 v141, 1.0, v141
	v_rcp_f32_e32 v149, v141
	v_and_b32_e32 v141, 0x3ff, v140
	v_lshlrev_b32_e32 v146, 1, v141
	v_add_f32_e32 v143, 1.0, v143
	v_pk_mul_f32 v[148:149], v[128:129], v[148:149]
	v_add_u32_e32 v141, 16, v140
	v_cvt_pk_bf16_f32 v151, v148, v149
	v_lshl_add_u64 v[148:149], v[154:155], 0, v[146:147]
	global_store_dwordx2 v[148:149], v[150:151], off
	v_rcp_f32_e32 v148, v143
	v_mul_f32_e32 v143, v123, v123
	v_fmamk_f32 v143, v143, 0xbdd2d3e7, v198
	v_mul_f32_e32 v143, v123, v143
	v_exp_f32_e32 v143, v143
	v_and_b32_e32 v141, 0x3ff, v141
	s_mov_b64 s[6:7], 0xa6c8000
	v_lshl_add_u64 v[156:157], v[144:145], 0, s[6:7]
	v_add_f32_e32 v143, 1.0, v143
	v_rcp_f32_e32 v149, v143
	v_mul_f32_e32 v143, v124, v124
	v_fmamk_f32 v143, v143, 0xbdd2d3e7, v198
	v_mul_f32_e32 v143, v124, v143
	v_exp_f32_e32 v143, v143
	v_pk_mul_f32 v[148:149], v[122:123], v[148:149]
	v_add_f32_e32 v143, 1.0, v143
	v_rcp_f32_e32 v150, v143
	v_mul_f32_e32 v143, v125, v125
	v_fmamk_f32 v143, v143, 0xbdd2d3e7, v198
	v_mul_f32_e32 v143, v125, v143
	v_exp_f32_e32 v143, v143
	v_cvt_pk_bf16_f32 v152, v148, v149
	v_lshlrev_b32_e32 v148, 1, v141
	v_mul_f32_e32 v141, v118, v118
	v_add_f32_e32 v143, 1.0, v143
	v_fmamk_f32 v141, v141, 0xbdd2d3e7, v198
	v_rcp_f32_e32 v151, v143
	v_mul_f32_e32 v141, v118, v141
	v_exp_f32_e32 v141, v141
	v_mov_b32_e32 v149, v0
	v_pk_mul_f32 v[150:151], v[124:125], v[150:151]
	v_add_f32_e32 v141, 1.0, v141
	v_cvt_pk_bf16_f32 v153, v150, v151
	v_lshl_add_u64 v[150:151], v[154:155], 0, v[148:149]
	global_store_dwordx2 v[150:151], v[152:153], off
	v_rcp_f32_e32 v150, v141
	v_mul_f32_e32 v141, v119, v119
	v_fmamk_f32 v141, v141, 0xbdd2d3e7, v198
	v_mul_f32_e32 v141, v119, v141
	v_exp_f32_e32 v141, v141
	s_nop 0
	v_add_f32_e32 v141, 1.0, v141
	v_rcp_f32_e32 v151, v141
	v_mul_f32_e32 v141, v120, v120
	v_fmamk_f32 v141, v141, 0xbdd2d3e7, v198
	v_mul_f32_e32 v141, v120, v141
	v_exp_f32_e32 v141, v141
	v_pk_mul_f32 v[150:151], v[118:119], v[150:151]
	v_add_f32_e32 v141, 1.0, v141
	v_rcp_f32_e32 v152, v141
	v_mul_f32_e32 v141, v121, v121
	v_fmamk_f32 v141, v141, 0xbdd2d3e7, v198
	v_mul_f32_e32 v141, v121, v141
	v_exp_f32_e32 v141, v141
	v_cvt_pk_bf16_f32 v150, v150, v151
	v_add_f32_e32 v141, 1.0, v141
	v_rcp_f32_e32 v153, v141
	v_mul_f32_e32 v141, v114, v114
	v_fmamk_f32 v141, v141, 0xbdd2d3e7, v198
	v_mul_f32_e32 v141, v114, v141
	v_exp_f32_e32 v141, v141
	v_pk_mul_f32 v[152:153], v[120:121], v[152:153]
	v_add_f32_e32 v141, 1.0, v141
	v_cvt_pk_bf16_f32 v151, v152, v153
	v_lshl_add_u64 v[152:153], v[156:157], 0, v[146:147]
	global_store_dwordx2 v[152:153], v[150:151], off
	v_rcp_f32_e32 v150, v141
	v_mul_f32_e32 v141, v115, v115
	v_fmamk_f32 v141, v141, 0xbdd2d3e7, v198
	v_mul_f32_e32 v141, v115, v141
	v_exp_f32_e32 v141, v141
	s_nop 0
	v_add_f32_e32 v141, 1.0, v141
	v_rcp_f32_e32 v151, v141
	v_mul_f32_e32 v141, v116, v116
	v_fmamk_f32 v141, v141, 0xbdd2d3e7, v198
	v_mul_f32_e32 v141, v116, v141
	v_exp_f32_e32 v141, v141
	v_pk_mul_f32 v[150:151], v[114:115], v[150:151]
	v_add_f32_e32 v141, 1.0, v141
	v_rcp_f32_e32 v152, v141
	v_mul_f32_e32 v141, v117, v117
	v_fmamk_f32 v141, v141, 0xbdd2d3e7, v198
	v_mul_f32_e32 v141, v117, v141
	v_exp_f32_e32 v141, v141
	v_cvt_pk_bf16_f32 v150, v150, v151
	v_add_f32_e32 v141, 1.0, v141
	v_rcp_f32_e32 v153, v141
	s_nop 0
	v_pk_mul_f32 v[152:153], v[116:117], v[152:153]
	s_nop 0
	v_cvt_pk_bf16_f32 v151, v152, v153
	v_lshl_add_u64 v[152:153], v[156:157], 0, v[148:149]
	global_store_dwordx2 v[152:153], v[150:151], off
	v_mul_f32_e32 v141, v110, v110
	v_fmamk_f32 v141, v141, 0xbdd2d3e7, v198
	v_mul_f32_e32 v141, v110, v141
	v_exp_f32_e32 v141, v141
	s_mov_b64 s[6:7], 0xa6d0000
	v_lshl_add_u64 v[160:161], v[144:145], 0, s[6:7]
	s_mov_b64 s[6:7], 0xa6d8000
	v_add_f32_e32 v141, 1.0, v141
	v_rcp_f32_e32 v150, v141
	v_mul_f32_e32 v141, v111, v111
	v_fmamk_f32 v141, v141, 0xbdd2d3e7, v198
	v_mul_f32_e32 v141, v111, v141
	v_exp_f32_e32 v141, v141
	v_lshl_add_u64 v[158:159], v[144:145], 0, s[6:7]
	v_add_f32_e32 v141, 1.0, v141
	v_rcp_f32_e32 v151, v141
	v_mul_f32_e32 v141, v112, v112
	v_fmamk_f32 v141, v141, 0xbdd2d3e7, v198
	v_mul_f32_e32 v141, v112, v141
	v_exp_f32_e32 v141, v141
	v_pk_mul_f32 v[150:151], v[110:111], v[150:151]
	v_add_f32_e32 v141, 1.0, v141
	v_rcp_f32_e32 v152, v141
	v_mul_f32_e32 v141, v113, v113
	v_fmamk_f32 v141, v141, 0xbdd2d3e7, v198
; #define GAS __attribute__((address_space(1)))
; __device__ __forceinline__ uint2 pack4(f32x4 v) { return make_uint2(pack2(v[0], v[1]), pack2(v[2], v[3])); }
; __device__ __forceinline__ float gelu_f(float x) {
;   const float c1 = -1.5957691216057308f * 1.4426950408889634f, c2 = c1 * 0.044715f;
;   float u = x * __builtin_fmaf(x * x, c2, c1);
;   return x * __builtin_amdgcn_rcpf(1.0f + __builtin_amdgcn_exp2f(u));
; }
; template <int MODE>
; __device__ __forceinline__ void epi_elem(char* ws, float* outp, const float* b_gate, int g0, int rl, int col, f32x4 v) {
;   if (MODE == E_U || MODE == E_GV) {
;     int lc = col & 1023;
;     f32x4 o; for (int i = 0; i < 4; ++i) o[i] = gelu_f(v[i]);
;     u16* dst = (u16*)(ws + (MODE == E_U ? W_U : W_GV));
;     *(GAS uint2*)(dst + (size_t)rl * 1024 + lc) = pack4(o);
	v_mul_f32_e32 v141, v113, v141
	v_exp_f32_e32 v141, v141
	v_cvt_pk_bf16_f32 v150, v150, v151
	v_add_f32_e32 v141, 1.0, v141
	v_rcp_f32_e32 v153, v141
	v_mul_f32_e32 v141, v106, v106
	v_fmamk_f32 v141, v141, 0xbdd2d3e7, v198
	v_mul_f32_e32 v141, v106, v141
	v_exp_f32_e32 v141, v141
	v_pk_mul_f32 v[152:153], v[112:113], v[152:153]
	v_add_f32_e32 v141, 1.0, v141
	v_cvt_pk_bf16_f32 v151, v152, v153
	v_lshl_add_u64 v[152:153], v[160:161], 0, v[146:147]
	global_store_dwordx2 v[152:153], v[150:151], off
	v_rcp_f32_e32 v150, v141
	v_mul_f32_e32 v141, v107, v107
	v_fmamk_f32 v141, v141, 0xbdd2d3e7, v198
	v_mul_f32_e32 v141, v107, v141
	v_exp_f32_e32 v141, v141
	s_nop 0
	v_add_f32_e32 v141, 1.0, v141
	v_rcp_f32_e32 v151, v141
	v_mul_f32_e32 v141, v108, v108
	v_fmamk_f32 v141, v141, 0xbdd2d3e7, v198
	v_mul_f32_e32 v141, v108, v141
	v_exp_f32_e32 v141, v141
	v_pk_mul_f32 v[150:151], v[106:107], v[150:151]
	v_add_f32_e32 v141, 1.0, v141
	v_rcp_f32_e32 v152, v141
	v_mul_f32_e32 v141, v109, v109
	v_fmamk_f32 v141, v141, 0xbdd2d3e7, v198
	v_mul_f32_e32 v141, v109, v141
	v_exp_f32_e32 v141, v141
	v_cvt_pk_bf16_f32 v150, v150, v151
	v_add_f32_e32 v141, 1.0, v141
	v_rcp_f32_e32 v153, v141
	v_mul_f32_e32 v141, v102, v102
	v_fmamk_f32 v141, v141, 0xbdd2d3e7, v198
	v_mul_f32_e32 v141, v102, v141
	v_exp_f32_e32 v141, v141
	v_pk_mul_f32 v[152:153], v[108:109], v[152:153]
	v_add_f32_e32 v141, 1.0, v141
	v_cvt_pk_bf16_f32 v151, v152, v153
	v_lshl_add_u64 v[152:153], v[160:161], 0, v[148:149]
	global_store_dwordx2 v[152:153], v[150:151], off
	v_rcp_f32_e32 v150, v141
	v_mul_f32_e32 v141, v103, v103
	v_fmamk_f32 v141, v141, 0xbdd2d3e7, v198
	v_mul_f32_e32 v141, v103, v141
	v_exp_f32_e32 v141, v141
	s_nop 0
	v_add_f32_e32 v141, 1.0, v141
	v_rcp_f32_e32 v151, v141
	v_mul_f32_e32 v141, v104, v104
	v_fmamk_f32 v141, v141, 0xbdd2d3e7, v198
	v_mul_f32_e32 v141, v104, v141
	v_exp_f32_e32 v141, v141
	v_pk_mul_f32 v[150:151], v[102:103], v[150:151]
	v_add_f32_e32 v141, 1.0, v141
	v_rcp_f32_e32 v152, v141
	v_mul_f32_e32 v141, v105, v105
	v_fmamk_f32 v141, v141, 0xbdd2d3e7, v198
	v_mul_f32_e32 v141, v105, v141
	v_exp_f32_e32 v141, v141
	v_cvt_pk_bf16_f32 v150, v150, v151
	v_add_f32_e32 v141, 1.0, v141
	v_rcp_f32_e32 v153, v141
	v_mul_f32_e32 v141, v98, v98
	v_fmamk_f32 v141, v141, 0xbdd2d3e7, v198
	v_mul_f32_e32 v141, v98, v141
	v_exp_f32_e32 v141, v141
	v_pk_mul_f32 v[152:153], v[104:105], v[152:153]
	v_add_f32_e32 v141, 1.0, v141
	v_cvt_pk_bf16_f32 v151, v152, v153
	v_lshl_add_u64 v[152:153], v[158:159], 0, v[146:147]
	global_store_dwordx2 v[152:153], v[150:151], off
	v_rcp_f32_e32 v150, v141
	v_mul_f32_e32 v141, v99, v99
	v_fmamk_f32 v141, v141, 0xbdd2d3e7, v198
	v_mul_f32_e32 v141, v99, v141
	v_exp_f32_e32 v141, v141
	s_nop 0
	v_add_f32_e32 v141, 1.0, v141
	v_rcp_f32_e32 v151, v141
	v_mul_f32_e32 v141, v100, v100
	v_fmamk_f32 v141, v141, 0xbdd2d3e7, v198
	v_mul_f32_e32 v141, v100, v141
	v_exp_f32_e32 v141, v141
	v_pk_mul_f32 v[150:151], v[98:99], v[150:151]
	v_add_f32_e32 v141, 1.0, v141
	v_rcp_f32_e32 v152, v141
	v_mul_f32_e32 v141, v101, v101
	v_fmamk_f32 v141, v141, 0xbdd2d3e7, v198
	v_mul_f32_e32 v141, v101, v141
	v_exp_f32_e32 v141, v141
	v_cvt_pk_bf16_f32 v150, v150, v151
	v_add_f32_e32 v141, 1.0, v141
	v_rcp_f32_e32 v153, v141
	s_nop 0
	v_pk_mul_f32 v[152:153], v[100:101], v[152:153]
	s_nop 0
	v_cvt_pk_bf16_f32 v151, v152, v153
	v_lshl_add_u64 v[152:153], v[158:159], 0, v[148:149]
	global_store_dwordx2 v[152:153], v[150:151], off
	v_mul_f32_e32 v143, v94, v94
	v_fmamk_f32 v143, v143, 0xbdd2d3e7, v198
	v_mul_f32_e32 v143, v94, v143
	v_exp_f32_e32 v143, v143
	v_add_u32_e32 v141, 0x80, v140
	v_and_b32_e32 v141, 0x3ff, v141
	v_add_f32_e32 v143, 1.0, v143
	v_rcp_f32_e32 v150, v143
	v_mul_f32_e32 v143, v95, v95
	v_fmamk_f32 v143, v143, 0xbdd2d3e7, v198
	v_mul_f32_e32 v143, v95, v143
	v_exp_f32_e32 v143, v143
	s_nop 0
	v_add_f32_e32 v143, 1.0, v143
	v_rcp_f32_e32 v151, v143
	v_mul_f32_e32 v143, v96, v96
	v_fmamk_f32 v143, v143, 0xbdd2d3e7, v198
	v_mul_f32_e32 v143, v96, v143
	v_exp_f32_e32 v143, v143
	v_pk_mul_f32 v[150:151], v[94:95], v[150:151]
	v_add_f32_e32 v143, 1.0, v143
	v_rcp_f32_e32 v152, v143
	v_mul_f32_e32 v143, v97, v97
	v_fmamk_f32 v143, v143, 0xbdd2d3e7, v198
	v_mul_f32_e32 v143, v97, v143
	v_exp_f32_e32 v143, v143
	v_cvt_pk_bf16_f32 v162, v150, v151
	v_lshlrev_b32_e32 v150, 1, v141
	v_mov_b32_e32 v151, v0
	v_add_f32_e32 v143, 1.0, v143
	v_rcp_f32_e32 v153, v143
	v_mul_f32_e32 v143, v90, v90
	v_fmamk_f32 v143, v143, 0xbdd2d3e7, v198
	v_mul_f32_e32 v143, v90, v143
	v_exp_f32_e32 v143, v143
	v_pk_mul_f32 v[152:153], v[96:97], v[152:153]
	v_add_u32_e32 v141, 0x90, v140
	v_cvt_pk_bf16_f32 v163, v152, v153
	v_lshl_add_u64 v[152:153], v[154:155], 0, v[150:151]
	v_add_f32_e32 v143, 1.0, v143
	global_store_dwordx2 v[152:153], v[162:163], off
	v_rcp_f32_e32 v152, v143
	v_mul_f32_e32 v143, v91, v91
	v_fmamk_f32 v143, v143, 0xbdd2d3e7, v198
	v_mul_f32_e32 v143, v91, v143
	v_exp_f32_e32 v143, v143
	v_and_b32_e32 v141, 0x3ff, v141
	v_add_f32_e32 v143, 1.0, v143
	v_rcp_f32_e32 v153, v143
	v_mul_f32_e32 v143, v92, v92
	v_fmamk_f32 v143, v143, 0xbdd2d3e7, v198
	v_mul_f32_e32 v143, v92, v143
	v_exp_f32_e32 v143, v143
	v_pk_mul_f32 v[152:153], v[90:91], v[152:153]
	v_add_f32_e32 v143, 1.0, v143
	v_rcp_f32_e32 v162, v143
	v_mul_f32_e32 v143, v93, v93
	v_fmamk_f32 v143, v143, 0xbdd2d3e7, v198
	v_mul_f32_e32 v143, v93, v143
	v_exp_f32_e32 v143, v143
	v_cvt_pk_bf16_f32 v164, v152, v153
	v_lshlrev_b32_e32 v152, 1, v141
	v_mul_f32_e32 v141, v86, v86
	v_add_f32_e32 v143, 1.0, v143
	v_fmamk_f32 v141, v141, 0xbdd2d3e7, v198
	v_rcp_f32_e32 v163, v143
	v_mul_f32_e32 v141, v86, v141
; #define GAS __attribute__((address_space(1)))
; __device__ __forceinline__ uint2 pack4(f32x4 v) { return make_uint2(pack2(v[0], v[1]), pack2(v[2], v[3])); }
; __device__ __forceinline__ float gelu_f(float x) {
;   const float c1 = -1.5957691216057308f * 1.4426950408889634f, c2 = c1 * 0.044715f;
;   float u = x * __builtin_fmaf(x * x, c2, c1);
;   return x * __builtin_amdgcn_rcpf(1.0f + __builtin_amdgcn_exp2f(u));
; }
; template <int MODE>
; __device__ __forceinline__ void epi_elem(char* ws, float* outp, const float* b_gate, int g0, int rl, int col, f32x4 v) {
;   if (MODE == E_U || MODE == E_GV) {
;     int lc = col & 1023;
;     f32x4 o; for (int i = 0; i < 4; ++i) o[i] = gelu_f(v[i]);
;     u16* dst = (u16*)(ws + (MODE == E_U ? W_U : W_GV));
;     *(GAS uint2*)(dst + (size_t)rl * 1024 + lc) = pack4(o);
	v_exp_f32_e32 v141, v141
	v_mov_b32_e32 v153, v0
	v_pk_mul_f32 v[162:163], v[92:93], v[162:163]
	v_lshl_add_u64 v[154:155], v[154:155], 0, v[152:153]
	v_cvt_pk_bf16_f32 v165, v162, v163
	v_add_f32_e32 v141, 1.0, v141
	global_store_dwordx2 v[154:155], v[164:165], off
	v_rcp_f32_e32 v154, v141
	v_mul_f32_e32 v141, v87, v87
	v_fmamk_f32 v141, v141, 0xbdd2d3e7, v198
	v_mul_f32_e32 v141, v87, v141
	v_exp_f32_e32 v141, v141
	s_nop 0
	v_add_f32_e32 v141, 1.0, v141
	v_rcp_f32_e32 v155, v141
	v_mul_f32_e32 v141, v88, v88
	v_fmamk_f32 v141, v141, 0xbdd2d3e7, v198
	v_mul_f32_e32 v141, v88, v141
	v_exp_f32_e32 v141, v141
	v_pk_mul_f32 v[154:155], v[86:87], v[154:155]
	v_add_f32_e32 v141, 1.0, v141
	v_rcp_f32_e32 v162, v141
	v_mul_f32_e32 v141, v89, v89
	v_fmamk_f32 v141, v141, 0xbdd2d3e7, v198
	v_mul_f32_e32 v141, v89, v141
	v_exp_f32_e32 v141, v141
	v_cvt_pk_bf16_f32 v154, v154, v155
	v_add_f32_e32 v141, 1.0, v141
	v_rcp_f32_e32 v163, v141
	v_mul_f32_e32 v141, v82, v82
	v_fmamk_f32 v141, v141, 0xbdd2d3e7, v198
	v_mul_f32_e32 v141, v82, v141
	v_exp_f32_e32 v141, v141
	v_pk_mul_f32 v[162:163], v[88:89], v[162:163]
	v_add_f32_e32 v141, 1.0, v141
	v_cvt_pk_bf16_f32 v155, v162, v163
	v_lshl_add_u64 v[162:163], v[156:157], 0, v[150:151]
	global_store_dwordx2 v[162:163], v[154:155], off
	v_rcp_f32_e32 v154, v141
	v_mul_f32_e32 v141, v83, v83
	v_fmamk_f32 v141, v141, 0xbdd2d3e7, v198
	v_mul_f32_e32 v141, v83, v141
	v_exp_f32_e32 v141, v141
	v_lshl_add_u64 v[156:157], v[156:157], 0, v[152:153]
	v_add_f32_e32 v141, 1.0, v141
	v_rcp_f32_e32 v155, v141
	v_mul_f32_e32 v141, v84, v84
	v_fmamk_f32 v141, v141, 0xbdd2d3e7, v198
	v_mul_f32_e32 v141, v84, v141
	v_exp_f32_e32 v141, v141
	v_pk_mul_f32 v[154:155], v[82:83], v[154:155]
	v_add_f32_e32 v141, 1.0, v141
	v_rcp_f32_e32 v162, v141
	v_mul_f32_e32 v141, v85, v85
	v_fmamk_f32 v141, v141, 0xbdd2d3e7, v198
	v_mul_f32_e32 v141, v85, v141
	v_exp_f32_e32 v141, v141
	v_cvt_pk_bf16_f32 v154, v154, v155
	v_add_f32_e32 v141, 1.0, v141
	v_rcp_f32_e32 v163, v141
	s_nop 0
	v_pk_mul_f32 v[162:163], v[84:85], v[162:163]
	s_nop 0
	v_cvt_pk_bf16_f32 v155, v162, v163
	global_store_dwordx2 v[156:157], v[154:155], off
	v_mul_f32_e32 v141, v78, v78
	v_fmamk_f32 v141, v141, 0xbdd2d3e7, v198
	v_mul_f32_e32 v141, v78, v141
	v_exp_f32_e32 v141, v141
	s_nop 0
	v_add_f32_e32 v141, 1.0, v141
	v_rcp_f32_e32 v154, v141
	v_mul_f32_e32 v141, v79, v79
	v_fmamk_f32 v141, v141, 0xbdd2d3e7, v198
	v_mul_f32_e32 v141, v79, v141
	v_exp_f32_e32 v141, v141
	s_nop 0
	v_add_f32_e32 v141, 1.0, v141
	v_rcp_f32_e32 v155, v141
	v_mul_f32_e32 v141, v80, v80
	v_fmamk_f32 v141, v141, 0xbdd2d3e7, v198
	v_mul_f32_e32 v141, v80, v141
	v_exp_f32_e32 v141, v141
	v_pk_mul_f32 v[154:155], v[78:79], v[154:155]
	v_add_f32_e32 v141, 1.0, v141
	v_rcp_f32_e32 v156, v141
	v_mul_f32_e32 v141, v81, v81
	v_fmamk_f32 v141, v141, 0xbdd2d3e7, v198
	v_mul_f32_e32 v141, v81, v141
	v_exp_f32_e32 v141, v141
	v_cvt_pk_bf16_f32 v154, v154, v155
	v_add_f32_e32 v141, 1.0, v141
	v_rcp_f32_e32 v157, v141
	v_mul_f32_e32 v141, v74, v74
	v_fmamk_f32 v141, v141, 0xbdd2d3e7, v198
	v_mul_f32_e32 v141, v74, v141
	v_exp_f32_e32 v141, v141
	v_pk_mul_f32 v[156:157], v[80:81], v[156:157]
	v_add_f32_e32 v141, 1.0, v141
	v_cvt_pk_bf16_f32 v155, v156, v157
	v_lshl_add_u64 v[156:157], v[160:161], 0, v[150:151]
	global_store_dwordx2 v[156:157], v[154:155], off
	v_rcp_f32_e32 v154, v141
	v_mul_f32_e32 v141, v75, v75
	v_fmamk_f32 v141, v141, 0xbdd2d3e7, v198
	v_mul_f32_e32 v141, v75, v141
	v_exp_f32_e32 v141, v141
	s_nop 0
	v_add_f32_e32 v141, 1.0, v141
	v_rcp_f32_e32 v155, v141
	v_mul_f32_e32 v141, v76, v76
	v_fmamk_f32 v141, v141, 0xbdd2d3e7, v198
	v_mul_f32_e32 v141, v76, v141
	v_exp_f32_e32 v141, v141
	v_pk_mul_f32 v[154:155], v[74:75], v[154:155]
	v_add_f32_e32 v141, 1.0, v141
	v_rcp_f32_e32 v156, v141
	v_mul_f32_e32 v141, v77, v77
	v_fmamk_f32 v141, v141, 0xbdd2d3e7, v198
	v_mul_f32_e32 v141, v77, v141
	v_exp_f32_e32 v141, v141
	v_cvt_pk_bf16_f32 v154, v154, v155
	v_add_f32_e32 v141, 1.0, v141
	v_rcp_f32_e32 v157, v141
	v_mul_f32_e32 v141, v70, v70
	v_fmamk_f32 v141, v141, 0xbdd2d3e7, v198
	v_mul_f32_e32 v141, v70, v141
	v_exp_f32_e32 v141, v141
	v_pk_mul_f32 v[156:157], v[76:77], v[156:157]
	v_add_f32_e32 v141, 1.0, v141
	v_cvt_pk_bf16_f32 v155, v156, v157
	v_lshl_add_u64 v[156:157], v[160:161], 0, v[152:153]
	global_store_dwordx2 v[156:157], v[154:155], off
	v_rcp_f32_e32 v154, v141
	v_mul_f32_e32 v141, v71, v71
	v_fmamk_f32 v141, v141, 0xbdd2d3e7, v198
	v_mul_f32_e32 v141, v71, v141
	v_exp_f32_e32 v141, v141
	s_nop 0
	v_add_f32_e32 v141, 1.0, v141
	v_rcp_f32_e32 v155, v141
	v_mul_f32_e32 v141, v72, v72
	v_fmamk_f32 v141, v141, 0xbdd2d3e7, v198
	v_mul_f32_e32 v141, v72, v141
	v_exp_f32_e32 v141, v141
	v_pk_mul_f32 v[154:155], v[70:71], v[154:155]
	v_add_f32_e32 v141, 1.0, v141
	v_rcp_f32_e32 v156, v141
	v_mul_f32_e32 v141, v73, v73
	v_fmamk_f32 v141, v141, 0xbdd2d3e7, v198
	v_mul_f32_e32 v141, v73, v141
	v_exp_f32_e32 v141, v141
	v_cvt_pk_bf16_f32 v154, v154, v155
	v_add_f32_e32 v141, 1.0, v141
	v_rcp_f32_e32 v157, v141
	v_mul_f32_e32 v141, v66, v66
	v_fmamk_f32 v141, v141, 0xbdd2d3e7, v198
	v_mul_f32_e32 v141, v66, v141
	v_exp_f32_e32 v141, v141
	v_pk_mul_f32 v[156:157], v[72:73], v[156:157]
	v_add_f32_e32 v141, 1.0, v141
	v_cvt_pk_bf16_f32 v155, v156, v157
	v_lshl_add_u64 v[156:157], v[158:159], 0, v[150:151]
	global_store_dwordx2 v[156:157], v[154:155], off
	v_rcp_f32_e32 v154, v141
	v_mul_f32_e32 v141, v67, v67
	v_fmamk_f32 v141, v141, 0xbdd2d3e7, v198
	v_mul_f32_e32 v141, v67, v141
	v_exp_f32_e32 v141, v141
	s_nop 0
	v_add_f32_e32 v141, 1.0, v141
	v_rcp_f32_e32 v155, v141
	v_mul_f32_e32 v141, v68, v68
; #define GAS __attribute__((address_space(1)))
; __device__ __forceinline__ uint2 pack4(f32x4 v) { return make_uint2(pack2(v[0], v[1]), pack2(v[2], v[3])); }
; __device__ __forceinline__ float gelu_f(float x) {
;   const float c1 = -1.5957691216057308f * 1.4426950408889634f, c2 = c1 * 0.044715f;
;   float u = x * __builtin_fmaf(x * x, c2, c1);
;   return x * __builtin_amdgcn_rcpf(1.0f + __builtin_amdgcn_exp2f(u));
; }
; template <int MODE>
; __device__ __forceinline__ void epi_elem(char* ws, float* outp, const float* b_gate, int g0, int rl, int col, f32x4 v) {
;   if (MODE == E_U || MODE == E_GV) {
;     int lc = col & 1023;
;     f32x4 o; for (int i = 0; i < 4; ++i) o[i] = gelu_f(v[i]);
;     u16* dst = (u16*)(ws + (MODE == E_U ? W_U : W_GV));
;     *(GAS uint2*)(dst + (size_t)rl * 1024 + lc) = pack4(o);
	v_fmamk_f32 v141, v141, 0xbdd2d3e7, v198
	v_mul_f32_e32 v141, v68, v141
	v_exp_f32_e32 v141, v141
	v_pk_mul_f32 v[154:155], v[66:67], v[154:155]
	v_add_f32_e32 v141, 1.0, v141
	v_rcp_f32_e32 v156, v141
	v_mul_f32_e32 v141, v69, v69
	v_fmamk_f32 v141, v141, 0xbdd2d3e7, v198
	v_mul_f32_e32 v141, v69, v141
	v_exp_f32_e32 v141, v141
	v_cvt_pk_bf16_f32 v154, v154, v155
	v_add_f32_e32 v141, 1.0, v141
	v_rcp_f32_e32 v157, v141
	s_nop 0
	v_pk_mul_f32 v[156:157], v[68:69], v[156:157]
	s_nop 0
	v_cvt_pk_bf16_f32 v155, v156, v157
	v_lshl_add_u64 v[156:157], v[158:159], 0, v[152:153]
	global_store_dwordx2 v[156:157], v[154:155], off
	v_mul_f32_e32 v141, v62, v62
	v_fmamk_f32 v141, v141, 0xbdd2d3e7, v198
	v_mul_f32_e32 v141, v62, v141
	v_exp_f32_e32 v141, v141
	s_mov_b64 s[6:7], 0xa700000
	v_lshl_add_u64 v[156:157], v[144:145], 0, s[6:7]
	s_mov_b64 s[6:7], 0xa708000
	v_add_f32_e32 v141, 1.0, v141
	v_rcp_f32_e32 v154, v141
	v_mul_f32_e32 v141, v63, v63
	v_fmamk_f32 v141, v141, 0xbdd2d3e7, v198
	v_mul_f32_e32 v141, v63, v141
	v_exp_f32_e32 v141, v141
	s_nop 0
	v_add_f32_e32 v141, 1.0, v141
	v_rcp_f32_e32 v155, v141
	v_mul_f32_e32 v141, v64, v64
	v_fmamk_f32 v141, v141, 0xbdd2d3e7, v198
	v_mul_f32_e32 v141, v64, v141
	v_exp_f32_e32 v141, v141
	v_pk_mul_f32 v[154:155], v[62:63], v[154:155]
	v_add_f32_e32 v141, 1.0, v141
	v_rcp_f32_e32 v158, v141
	v_mul_f32_e32 v141, v65, v65
	v_fmamk_f32 v141, v141, 0xbdd2d3e7, v198
	v_mul_f32_e32 v141, v65, v141
	v_exp_f32_e32 v141, v141
	v_cvt_pk_bf16_f32 v154, v154, v155
	v_add_f32_e32 v141, 1.0, v141
	v_rcp_f32_e32 v159, v141
	v_mul_f32_e32 v141, v58, v58
	v_fmamk_f32 v141, v141, 0xbdd2d3e7, v198
	v_mul_f32_e32 v141, v58, v141
	v_exp_f32_e32 v141, v141
	v_pk_mul_f32 v[158:159], v[64:65], v[158:159]
	v_add_f32_e32 v141, 1.0, v141
	v_cvt_pk_bf16_f32 v155, v158, v159
	v_lshl_add_u64 v[158:159], v[156:157], 0, v[146:147]
	global_store_dwordx2 v[158:159], v[154:155], off
	v_rcp_f32_e32 v154, v141
	v_mul_f32_e32 v141, v59, v59
	v_fmamk_f32 v141, v141, 0xbdd2d3e7, v198
	v_mul_f32_e32 v141, v59, v141
	v_exp_f32_e32 v141, v141
	s_nop 0
	v_add_f32_e32 v141, 1.0, v141
	v_rcp_f32_e32 v155, v141
	v_mul_f32_e32 v141, v60, v60
	v_fmamk_f32 v141, v141, 0xbdd2d3e7, v198
	v_mul_f32_e32 v141, v60, v141
	v_exp_f32_e32 v141, v141
	v_pk_mul_f32 v[154:155], v[58:59], v[154:155]
	v_add_f32_e32 v141, 1.0, v141
	v_rcp_f32_e32 v158, v141
	v_mul_f32_e32 v141, v61, v61
	v_fmamk_f32 v141, v141, 0xbdd2d3e7, v198
	v_mul_f32_e32 v141, v61, v141
	v_exp_f32_e32 v141, v141
	v_cvt_pk_bf16_f32 v154, v154, v155
	v_add_f32_e32 v141, 1.0, v141
	v_rcp_f32_e32 v159, v141
	v_mul_f32_e32 v141, v54, v54
	v_fmamk_f32 v141, v141, 0xbdd2d3e7, v198
	v_mul_f32_e32 v141, v54, v141
	v_exp_f32_e32 v141, v141
	v_pk_mul_f32 v[158:159], v[60:61], v[158:159]
	v_add_f32_e32 v141, 1.0, v141
	v_cvt_pk_bf16_f32 v155, v158, v159
	v_lshl_add_u64 v[158:159], v[156:157], 0, v[148:149]
	global_store_dwordx2 v[158:159], v[154:155], off
	v_rcp_f32_e32 v158, v141
	v_mul_f32_e32 v141, v55, v55
	v_fmamk_f32 v141, v141, 0xbdd2d3e7, v198
	v_mul_f32_e32 v141, v55, v141
	v_exp_f32_e32 v141, v141
	v_lshl_add_u64 v[154:155], v[144:145], 0, s[6:7]
	v_add_f32_e32 v141, 1.0, v141
	v_rcp_f32_e32 v159, v141
	v_mul_f32_e32 v141, v56, v56
	v_fmamk_f32 v141, v141, 0xbdd2d3e7, v198
	v_mul_f32_e32 v141, v56, v141
	v_exp_f32_e32 v141, v141
	v_pk_mul_f32 v[158:159], v[54:55], v[158:159]
	v_add_f32_e32 v141, 1.0, v141
	v_rcp_f32_e32 v160, v141
	v_mul_f32_e32 v141, v57, v57
	v_fmamk_f32 v141, v141, 0xbdd2d3e7, v198
	v_mul_f32_e32 v141, v57, v141
	v_exp_f32_e32 v141, v141
	v_cvt_pk_bf16_f32 v158, v158, v159
	v_add_f32_e32 v141, 1.0, v141
	v_rcp_f32_e32 v161, v141
	v_mul_f32_e32 v141, v50, v50
	v_fmamk_f32 v141, v141, 0xbdd2d3e7, v198
	v_mul_f32_e32 v141, v50, v141
	v_exp_f32_e32 v141, v141
	v_pk_mul_f32 v[160:161], v[56:57], v[160:161]
	v_add_f32_e32 v141, 1.0, v141
	v_cvt_pk_bf16_f32 v159, v160, v161
	v_lshl_add_u64 v[160:161], v[154:155], 0, v[146:147]
	global_store_dwordx2 v[160:161], v[158:159], off
	v_rcp_f32_e32 v158, v141
	v_mul_f32_e32 v141, v51, v51
	v_fmamk_f32 v141, v141, 0xbdd2d3e7, v198
	v_mul_f32_e32 v141, v51, v141
	v_exp_f32_e32 v141, v141
	s_nop 0
	v_add_f32_e32 v141, 1.0, v141
	v_rcp_f32_e32 v159, v141
	v_mul_f32_e32 v141, v52, v52
	v_fmamk_f32 v141, v141, 0xbdd2d3e7, v198
	v_mul_f32_e32 v141, v52, v141
	v_exp_f32_e32 v141, v141
	v_pk_mul_f32 v[158:159], v[50:51], v[158:159]
	v_add_f32_e32 v141, 1.0, v141
	v_rcp_f32_e32 v160, v141
	v_mul_f32_e32 v141, v53, v53
	v_fmamk_f32 v141, v141, 0xbdd2d3e7, v198
	v_mul_f32_e32 v141, v53, v141
	v_exp_f32_e32 v141, v141
	v_cvt_pk_bf16_f32 v158, v158, v159
	v_add_f32_e32 v141, 1.0, v141
	v_rcp_f32_e32 v161, v141
	s_nop 0
	v_pk_mul_f32 v[160:161], v[52:53], v[160:161]
	s_nop 0
	v_cvt_pk_bf16_f32 v159, v160, v161
	v_lshl_add_u64 v[160:161], v[154:155], 0, v[148:149]
	global_store_dwordx2 v[160:161], v[158:159], off
	v_mul_f32_e32 v141, v46, v46
	v_fmamk_f32 v141, v141, 0xbdd2d3e7, v198
	v_mul_f32_e32 v141, v46, v141
	v_exp_f32_e32 v141, v141
	s_mov_b64 s[6:7], 0xa710000
	v_lshl_add_u64 v[158:159], v[144:145], 0, s[6:7]
	s_mov_b64 s[6:7], 0xa718000
	v_add_f32_e32 v141, 1.0, v141
	v_rcp_f32_e32 v160, v141
	v_mul_f32_e32 v141, v47, v47
	v_fmamk_f32 v141, v141, 0xbdd2d3e7, v198
	v_mul_f32_e32 v141, v47, v141
	v_exp_f32_e32 v141, v141
	v_lshl_add_u64 v[144:145], v[144:145], 0, s[6:7]
	v_add_f32_e32 v141, 1.0, v141
	v_rcp_f32_e32 v161, v141
	v_mul_f32_e32 v141, v48, v48
	v_fmamk_f32 v141, v141, 0xbdd2d3e7, v198
	v_mul_f32_e32 v141, v48, v141
	v_exp_f32_e32 v141, v141
	v_pk_mul_f32 v[160:161], v[46:47], v[160:161]
	v_add_f32_e32 v141, 1.0, v141
	v_rcp_f32_e32 v162, v141
; #define GAS __attribute__((address_space(1)))
; __device__ __forceinline__ uint2 pack4(f32x4 v) { return make_uint2(pack2(v[0], v[1]), pack2(v[2], v[3])); }
; __device__ __forceinline__ float gelu_f(float x) {
;   const float c1 = -1.5957691216057308f * 1.4426950408889634f, c2 = c1 * 0.044715f;
;   float u = x * __builtin_fmaf(x * x, c2, c1);
;   return x * __builtin_amdgcn_rcpf(1.0f + __builtin_amdgcn_exp2f(u));
; }
; template <int MODE>
; __device__ __forceinline__ void epi_elem(char* ws, float* outp, const float* b_gate, int g0, int rl, int col, f32x4 v) {
;   if (MODE == E_U || MODE == E_GV) {
;     int lc = col & 1023;
;     f32x4 o; for (int i = 0; i < 4; ++i) o[i] = gelu_f(v[i]);
;     u16* dst = (u16*)(ws + (MODE == E_U ? W_U : W_GV));
;     *(GAS uint2*)(dst + (size_t)rl * 1024 + lc) = pack4(o);
	v_mul_f32_e32 v141, v49, v49
	v_fmamk_f32 v141, v141, 0xbdd2d3e7, v198
	v_mul_f32_e32 v141, v49, v141
	v_exp_f32_e32 v141, v141
	v_cvt_pk_bf16_f32 v160, v160, v161
	v_add_f32_e32 v141, 1.0, v141
	v_rcp_f32_e32 v163, v141
	v_mul_f32_e32 v141, v42, v42
	v_fmamk_f32 v141, v141, 0xbdd2d3e7, v198
	v_mul_f32_e32 v141, v42, v141
	v_exp_f32_e32 v141, v141
	v_pk_mul_f32 v[162:163], v[48:49], v[162:163]
	v_add_f32_e32 v141, 1.0, v141
	v_cvt_pk_bf16_f32 v161, v162, v163
	v_lshl_add_u64 v[162:163], v[158:159], 0, v[146:147]
	global_store_dwordx2 v[162:163], v[160:161], off
	v_rcp_f32_e32 v160, v141
	v_mul_f32_e32 v141, v43, v43
	v_fmamk_f32 v141, v141, 0xbdd2d3e7, v198
	v_mul_f32_e32 v141, v43, v141
	v_exp_f32_e32 v141, v141
	v_lshl_add_u64 v[146:147], v[144:145], 0, v[146:147]
	v_add_f32_e32 v141, 1.0, v141
	v_rcp_f32_e32 v161, v141
	v_mul_f32_e32 v141, v44, v44
	v_fmamk_f32 v141, v141, 0xbdd2d3e7, v198
	v_mul_f32_e32 v141, v44, v141
	v_exp_f32_e32 v141, v141
	v_pk_mul_f32 v[160:161], v[42:43], v[160:161]
	v_add_f32_e32 v141, 1.0, v141
	v_rcp_f32_e32 v162, v141
	v_mul_f32_e32 v141, v45, v45
	v_fmamk_f32 v141, v141, 0xbdd2d3e7, v198
	v_mul_f32_e32 v141, v45, v141
	v_exp_f32_e32 v141, v141
	v_cvt_pk_bf16_f32 v160, v160, v161
	v_add_f32_e32 v141, 1.0, v141
	v_rcp_f32_e32 v163, v141
	v_mul_f32_e32 v141, v38, v38
	v_fmamk_f32 v141, v141, 0xbdd2d3e7, v198
	v_mul_f32_e32 v141, v38, v141
	v_exp_f32_e32 v141, v141
	v_pk_mul_f32 v[162:163], v[44:45], v[162:163]
	v_add_f32_e32 v141, 1.0, v141
	v_cvt_pk_bf16_f32 v161, v162, v163
	v_lshl_add_u64 v[162:163], v[158:159], 0, v[148:149]
	global_store_dwordx2 v[162:163], v[160:161], off
	v_rcp_f32_e32 v160, v141
	v_mul_f32_e32 v141, v39, v39
	v_fmamk_f32 v141, v141, 0xbdd2d3e7, v198
	v_mul_f32_e32 v141, v39, v141
	v_exp_f32_e32 v141, v141
	v_lshl_add_u64 v[148:149], v[144:145], 0, v[148:149]
	v_add_f32_e32 v141, 1.0, v141
	v_rcp_f32_e32 v161, v141
	v_mul_f32_e32 v141, v40, v40
	v_fmamk_f32 v141, v141, 0xbdd2d3e7, v198
	v_mul_f32_e32 v141, v40, v141
	v_exp_f32_e32 v141, v141
	v_pk_mul_f32 v[160:161], v[38:39], v[160:161]
	v_add_f32_e32 v141, 1.0, v141
	v_rcp_f32_e32 v162, v141
	v_mul_f32_e32 v141, v41, v41
	v_fmamk_f32 v141, v141, 0xbdd2d3e7, v198
	v_mul_f32_e32 v141, v41, v141
	v_exp_f32_e32 v141, v141
	v_cvt_pk_bf16_f32 v160, v160, v161
	v_add_f32_e32 v141, 1.0, v141
	v_rcp_f32_e32 v163, v141
	v_mul_f32_e32 v141, v34, v34
	v_fmamk_f32 v141, v141, 0xbdd2d3e7, v198
	v_mul_f32_e32 v141, v34, v141
	v_exp_f32_e32 v141, v141
	v_pk_mul_f32 v[162:163], v[40:41], v[162:163]
	v_add_f32_e32 v141, 1.0, v141
	v_cvt_pk_bf16_f32 v161, v162, v163
	global_store_dwordx2 v[146:147], v[160:161], off
	v_rcp_f32_e32 v146, v141
	v_mul_f32_e32 v141, v35, v35
	v_fmamk_f32 v141, v141, 0xbdd2d3e7, v198
	v_mul_f32_e32 v141, v35, v141
	v_exp_f32_e32 v141, v141
	s_nop 0
	v_add_f32_e32 v141, 1.0, v141
	v_rcp_f32_e32 v147, v141
	v_mul_f32_e32 v141, v36, v36
	v_fmamk_f32 v141, v141, 0xbdd2d3e7, v198
	v_mul_f32_e32 v141, v36, v141
	v_exp_f32_e32 v141, v141
	v_pk_mul_f32 v[146:147], v[34:35], v[146:147]
	v_add_f32_e32 v141, 1.0, v141
	v_rcp_f32_e32 v160, v141
	v_mul_f32_e32 v141, v37, v37
	v_fmamk_f32 v141, v141, 0xbdd2d3e7, v198
	v_mul_f32_e32 v141, v37, v141
	v_exp_f32_e32 v141, v141
	v_cvt_pk_bf16_f32 v146, v146, v147
	v_add_f32_e32 v141, 1.0, v141
	v_rcp_f32_e32 v161, v141
	s_nop 0
	v_pk_mul_f32 v[160:161], v[36:37], v[160:161]
	s_nop 0
	v_cvt_pk_bf16_f32 v147, v160, v161
	global_store_dwordx2 v[148:149], v[146:147], off
	v_mul_f32_e32 v141, v30, v30
	v_fmamk_f32 v141, v141, 0xbdd2d3e7, v198
	v_mul_f32_e32 v141, v30, v141
	v_exp_f32_e32 v141, v141
	s_nop 0
	v_add_f32_e32 v141, 1.0, v141
	v_rcp_f32_e32 v146, v141
	v_mul_f32_e32 v141, v31, v31
	v_fmamk_f32 v141, v141, 0xbdd2d3e7, v198
	v_mul_f32_e32 v141, v31, v141
	v_exp_f32_e32 v141, v141
	s_nop 0
	v_add_f32_e32 v141, 1.0, v141
	v_rcp_f32_e32 v147, v141
	v_mul_f32_e32 v141, v32, v32
	v_fmamk_f32 v141, v141, 0xbdd2d3e7, v198
	v_mul_f32_e32 v141, v32, v141
	v_exp_f32_e32 v141, v141
	v_pk_mul_f32 v[146:147], v[30:31], v[146:147]
	v_add_f32_e32 v141, 1.0, v141
	v_rcp_f32_e32 v148, v141
	v_mul_f32_e32 v141, v33, v33
	v_fmamk_f32 v141, v141, 0xbdd2d3e7, v198
	v_mul_f32_e32 v141, v33, v141
	v_exp_f32_e32 v141, v141
	v_cvt_pk_bf16_f32 v146, v146, v147
	v_add_f32_e32 v141, 1.0, v141
	v_rcp_f32_e32 v149, v141
	v_mul_f32_e32 v141, v26, v26
	v_fmamk_f32 v141, v141, 0xbdd2d3e7, v198
	v_mul_f32_e32 v141, v26, v141
	v_exp_f32_e32 v141, v141
	v_pk_mul_f32 v[148:149], v[32:33], v[148:149]
	v_add_f32_e32 v141, 1.0, v141
	v_cvt_pk_bf16_f32 v147, v148, v149
	v_lshl_add_u64 v[148:149], v[156:157], 0, v[150:151]
	global_store_dwordx2 v[148:149], v[146:147], off
	v_rcp_f32_e32 v146, v141
	v_mul_f32_e32 v141, v27, v27
	v_fmamk_f32 v141, v141, 0xbdd2d3e7, v198
	v_mul_f32_e32 v141, v27, v141
	v_exp_f32_e32 v141, v141
	s_nop 0
	v_add_f32_e32 v141, 1.0, v141
	v_rcp_f32_e32 v147, v141
	v_mul_f32_e32 v141, v28, v28
	v_fmamk_f32 v141, v141, 0xbdd2d3e7, v198
	v_mul_f32_e32 v141, v28, v141
	v_exp_f32_e32 v141, v141
	v_pk_mul_f32 v[146:147], v[26:27], v[146:147]
	v_add_f32_e32 v141, 1.0, v141
	v_rcp_f32_e32 v148, v141
	v_mul_f32_e32 v141, v29, v29
	v_fmamk_f32 v141, v141, 0xbdd2d3e7, v198
	v_mul_f32_e32 v141, v29, v141
	v_exp_f32_e32 v141, v141
	v_cvt_pk_bf16_f32 v146, v146, v147
	v_add_f32_e32 v141, 1.0, v141
	v_rcp_f32_e32 v149, v141
	v_mul_f32_e32 v141, v22, v22
	v_fmamk_f32 v141, v141, 0xbdd2d3e7, v198
	v_mul_f32_e32 v141, v22, v141
	v_exp_f32_e32 v141, v141
	v_pk_mul_f32 v[148:149], v[28:29], v[148:149]
	v_add_f32_e32 v141, 1.0, v141
	v_cvt_pk_bf16_f32 v147, v148, v149
	v_lshl_add_u64 v[148:149], v[156:157], 0, v[152:153]
; #define GAS __attribute__((address_space(1)))
; __device__ __forceinline__ uint2 pack4(f32x4 v) { return make_uint2(pack2(v[0], v[1]), pack2(v[2], v[3])); }
; __device__ __forceinline__ float gelu_f(float x) {
;   const float c1 = -1.5957691216057308f * 1.4426950408889634f, c2 = c1 * 0.044715f;
;   float u = x * __builtin_fmaf(x * x, c2, c1);
;   return x * __builtin_amdgcn_rcpf(1.0f + __builtin_amdgcn_exp2f(u));
; }
; template <int MODE>
; __device__ __forceinline__ void epi_elem(char* ws, float* outp, const float* b_gate, int g0, int rl, int col, f32x4 v) {
;   if (MODE == E_U || MODE == E_GV) {
;     int lc = col & 1023;
;     f32x4 o; for (int i = 0; i < 4; ++i) o[i] = gelu_f(v[i]);
;     u16* dst = (u16*)(ws + (MODE == E_U ? W_U : W_GV));
;     *(GAS uint2*)(dst + (size_t)rl * 1024 + lc) = pack4(o);
	global_store_dwordx2 v[148:149], v[146:147], off
	v_rcp_f32_e32 v146, v141
	v_mul_f32_e32 v141, v23, v23
	v_fmamk_f32 v141, v141, 0xbdd2d3e7, v198
	v_mul_f32_e32 v141, v23, v141
	v_exp_f32_e32 v141, v141
	s_nop 0
	v_add_f32_e32 v141, 1.0, v141
	v_rcp_f32_e32 v147, v141
	v_mul_f32_e32 v141, v24, v24
	v_fmamk_f32 v141, v141, 0xbdd2d3e7, v198
	v_mul_f32_e32 v141, v24, v141
	v_exp_f32_e32 v141, v141
	v_pk_mul_f32 v[146:147], v[22:23], v[146:147]
	v_add_f32_e32 v141, 1.0, v141
	v_rcp_f32_e32 v148, v141
	v_mul_f32_e32 v141, v25, v25
	v_fmamk_f32 v141, v141, 0xbdd2d3e7, v198
	v_mul_f32_e32 v141, v25, v141
	v_exp_f32_e32 v141, v141
	v_cvt_pk_bf16_f32 v146, v146, v147
	v_add_f32_e32 v141, 1.0, v141
	v_rcp_f32_e32 v149, v141
	v_mul_f32_e32 v141, v18, v18
	v_fmamk_f32 v141, v141, 0xbdd2d3e7, v198
	v_mul_f32_e32 v141, v18, v141
	v_exp_f32_e32 v141, v141
	v_pk_mul_f32 v[148:149], v[24:25], v[148:149]
	v_add_f32_e32 v141, 1.0, v141
	v_cvt_pk_bf16_f32 v147, v148, v149
	v_lshl_add_u64 v[148:149], v[154:155], 0, v[150:151]
	global_store_dwordx2 v[148:149], v[146:147], off
	v_rcp_f32_e32 v146, v141
	v_mul_f32_e32 v141, v19, v19
	v_fmamk_f32 v141, v141, 0xbdd2d3e7, v198
	v_mul_f32_e32 v141, v19, v141
	v_exp_f32_e32 v141, v141
	s_nop 0
	v_add_f32_e32 v141, 1.0, v141
	v_rcp_f32_e32 v147, v141
	v_mul_f32_e32 v141, v20, v20
	v_fmamk_f32 v141, v141, 0xbdd2d3e7, v198
	v_mul_f32_e32 v141, v20, v141
	v_exp_f32_e32 v141, v141
	v_pk_mul_f32 v[146:147], v[18:19], v[146:147]
	v_add_f32_e32 v141, 1.0, v141
	v_rcp_f32_e32 v148, v141
	v_mul_f32_e32 v141, v21, v21
	v_fmamk_f32 v141, v141, 0xbdd2d3e7, v198
	v_mul_f32_e32 v141, v21, v141
	v_exp_f32_e32 v141, v141
	v_cvt_pk_bf16_f32 v146, v146, v147
	v_add_f32_e32 v141, 1.0, v141
	v_rcp_f32_e32 v149, v141
	s_nop 0
	v_pk_mul_f32 v[148:149], v[20:21], v[148:149]
	s_nop 0
	v_cvt_pk_bf16_f32 v147, v148, v149
	v_lshl_add_u64 v[148:149], v[154:155], 0, v[152:153]
	global_store_dwordx2 v[148:149], v[146:147], off
	v_mul_f32_e32 v141, v14, v14
	v_fmamk_f32 v141, v141, 0xbdd2d3e7, v198
	v_mul_f32_e32 v141, v14, v141
	v_exp_f32_e32 v141, v141
	s_nop 0
	v_add_f32_e32 v141, 1.0, v141
	v_rcp_f32_e32 v146, v141
	v_mul_f32_e32 v141, v15, v15
	v_fmamk_f32 v141, v141, 0xbdd2d3e7, v198
	v_mul_f32_e32 v141, v15, v141
	v_exp_f32_e32 v141, v141
	s_nop 0
	v_add_f32_e32 v141, 1.0, v141
	v_rcp_f32_e32 v147, v141
	v_mul_f32_e32 v141, v16, v16
	v_fmamk_f32 v141, v141, 0xbdd2d3e7, v198
	v_mul_f32_e32 v141, v16, v141
	v_exp_f32_e32 v141, v141
	v_pk_mul_f32 v[146:147], v[14:15], v[146:147]
	v_add_f32_e32 v141, 1.0, v141
	v_rcp_f32_e32 v148, v141
	v_mul_f32_e32 v141, v17, v17
	v_fmamk_f32 v141, v141, 0xbdd2d3e7, v198
	v_mul_f32_e32 v141, v17, v141
	v_exp_f32_e32 v141, v141
	v_cvt_pk_bf16_f32 v146, v146, v147
	v_add_f32_e32 v141, 1.0, v141
	v_rcp_f32_e32 v149, v141
	v_mul_f32_e32 v141, v10, v10
	v_fmamk_f32 v141, v141, 0xbdd2d3e7, v198
	v_mul_f32_e32 v141, v10, v141
	v_exp_f32_e32 v141, v141
	v_pk_mul_f32 v[148:149], v[16:17], v[148:149]
	v_add_f32_e32 v141, 1.0, v141
	v_cvt_pk_bf16_f32 v147, v148, v149
	v_lshl_add_u64 v[148:149], v[158:159], 0, v[150:151]
	global_store_dwordx2 v[148:149], v[146:147], off
	v_rcp_f32_e32 v146, v141
	v_mul_f32_e32 v141, v11, v11
	v_fmamk_f32 v141, v141, 0xbdd2d3e7, v198
	v_mul_f32_e32 v141, v11, v141
	v_exp_f32_e32 v141, v141
	s_nop 0
	v_add_f32_e32 v141, 1.0, v141
	v_rcp_f32_e32 v147, v141
	v_mul_f32_e32 v141, v12, v12
	v_fmamk_f32 v141, v141, 0xbdd2d3e7, v198
	v_mul_f32_e32 v141, v12, v141
	v_exp_f32_e32 v141, v141
	v_pk_mul_f32 v[146:147], v[10:11], v[146:147]
	v_add_f32_e32 v141, 1.0, v141
	v_rcp_f32_e32 v148, v141
	v_mul_f32_e32 v141, v13, v13
	v_fmamk_f32 v141, v141, 0xbdd2d3e7, v198
	v_mul_f32_e32 v141, v13, v141
	v_exp_f32_e32 v141, v141
	v_cvt_pk_bf16_f32 v146, v146, v147
	v_add_f32_e32 v141, 1.0, v141
	v_rcp_f32_e32 v149, v141
	v_mul_f32_e32 v141, v6, v6
	v_fmamk_f32 v141, v141, 0xbdd2d3e7, v198
	v_mul_f32_e32 v141, v6, v141
	v_exp_f32_e32 v141, v141
	v_pk_mul_f32 v[148:149], v[12:13], v[148:149]
	v_add_f32_e32 v141, 1.0, v141
	v_cvt_pk_bf16_f32 v147, v148, v149
	v_lshl_add_u64 v[148:149], v[158:159], 0, v[152:153]
	global_store_dwordx2 v[148:149], v[146:147], off
	v_rcp_f32_e32 v146, v141
	v_mul_f32_e32 v141, v7, v7
	v_fmamk_f32 v141, v141, 0xbdd2d3e7, v198
	v_mul_f32_e32 v141, v7, v141
	v_exp_f32_e32 v141, v141
	s_nop 0
	v_add_f32_e32 v141, 1.0, v141
	v_rcp_f32_e32 v147, v141
	v_mul_f32_e32 v141, v8, v8
	v_fmamk_f32 v141, v141, 0xbdd2d3e7, v198
	v_mul_f32_e32 v141, v8, v141
	v_exp_f32_e32 v141, v141
	v_pk_mul_f32 v[146:147], v[6:7], v[146:147]
	v_add_f32_e32 v141, 1.0, v141
	v_rcp_f32_e32 v148, v141
	v_mul_f32_e32 v141, v9, v9
	v_fmamk_f32 v141, v141, 0xbdd2d3e7, v198
	v_mul_f32_e32 v141, v9, v141
	v_exp_f32_e32 v141, v141
	v_cvt_pk_bf16_f32 v146, v146, v147
	v_add_f32_e32 v141, 1.0, v141
	v_rcp_f32_e32 v149, v141
	v_mul_f32_e32 v141, v2, v2
	v_fmamk_f32 v141, v141, 0xbdd2d3e7, v198
	v_mul_f32_e32 v141, v2, v141
	v_exp_f32_e32 v141, v141
	v_pk_mul_f32 v[148:149], v[8:9], v[148:149]
	v_add_f32_e32 v141, 1.0, v141
	v_cvt_pk_bf16_f32 v147, v148, v149
	v_lshl_add_u64 v[148:149], v[144:145], 0, v[150:151]
	global_store_dwordx2 v[148:149], v[146:147], off
	v_rcp_f32_e32 v146, v141
	v_mul_f32_e32 v141, v3, v3
	v_fmamk_f32 v141, v141, 0xbdd2d3e7, v198
	v_mul_f32_e32 v141, v3, v141
	v_exp_f32_e32 v141, v141
	v_lshl_add_u64 v[144:145], v[144:145], 0, v[152:153]
	v_add_f32_e32 v141, 1.0, v141
	v_rcp_f32_e32 v147, v141
	v_mul_f32_e32 v141, v4, v4
	v_fmamk_f32 v141, v141, 0xbdd2d3e7, v198
	v_mul_f32_e32 v141, v4, v141
	v_exp_f32_e32 v141, v141
	v_pk_mul_f32 v[146:147], v[2:3], v[146:147]
	v_add_f32_e32 v141, 1.0, v141
	v_rcp_f32_e32 v148, v141
	v_mul_f32_e32 v141, v5, v5
	v_fmamk_f32 v141, v141, 0xbdd2d3e7, v198
	v_mul_f32_e32 v141, v5, v141
	v_exp_f32_e32 v141, v141
	v_cvt_pk_bf16_f32 v146, v146, v147
	v_add_f32_e32 v141, 1.0, v141
	v_rcp_f32_e32 v149, v141
	s_nop 0
	v_pk_mul_f32 v[148:149], v[4:5], v[148:149]
	s_nop 0
	v_cvt_pk_bf16_f32 v147, v148, v149
	global_store_dwordx2 v[144:145], v[146:147], off
	s_mov_b64 s[6:7], 0

; #define GAS __attribute__((address_space(1)))
; __device__ __forceinline__ uint2 pack4(f32x4 v) { return make_uint2(pack2(v[0], v[1]), pack2(v[2], v[3])); }
; template <int MODE>
; __device__ __forceinline__ void epi_elem(char* ws, float* outp, const float* b_gate, int g0, int rl, int col, f32x4 v) {
;     ...
;   } else if (MODE == E_T || MODE == E_FF) {
;     *(GAS uint2*)((u16*)(ws + (MODE == E_T ? W_T : W_FF)) + (size_t)rl * 1024 + col) = pack4(v);
; template <int MODE>
; __device__ __forceinline__ void epi_store(char* ws, float* outp, const float* b_gate, int g0, const f32x4 (&acc)[2][2][4][2], int rbase, int cbase) {
; #pragma unroll
;   for (int ai = 0; ai < 2; ++ai)
; #pragma unroll
;     for (int bj = 0; bj < 2; ++bj)
; #pragma unroll
;       for (int m = 0; m < 4; ++m) {
; #pragma unroll
;         for (int n = 0; n < 2; ++n)
;           epi_elem<MODE>(ws, outp, b_gate, g0, rbase + ai * HALF + m * 16, cbase + bj * HALF + n * 16, acc[ai][bj][m][n]);
;         if ((m & 1) && (MODE != E_M1 && MODE != E_MG)) __builtin_amdgcn_sched_barrier(0);
;         if (m == 3 && (MODE == E_M1 || MODE == E_MG)) __builtin_amdgcn_sched_barrier(0);
.LBB0_992:
	s_and_b64 vcc, exec, s[4:5]
	v_ashrrev_i32_e32 v143, 31, v142
	s_cbranch_vccz .LBB0_994
	v_lshlrev_b64 v[144:145], 11, v[142:143]
	v_lshl_add_u64 v[144:145], s[2:3], 0, v[144:145]
	v_ashrrev_i32_e32 v141, 31, v140
	v_lshl_add_u64 v[144:145], v[140:141], 1, v[144:145]
	s_mov_b64 s[4:5], 0x26dc0000
	v_add_co_u32_e32 v150, vcc, 0x26dc0000, v144
	v_cvt_pk_bf16_f32 v146, v126, v127
	v_cvt_pk_bf16_f32 v147, v128, v129
	v_lshl_add_u64 v[148:149], v[144:145], 0, s[4:5]
	v_addc_co_u32_e32 v151, vcc, 0, v145, vcc
	s_mov_b64 s[4:5], 0x26dc8000
	global_store_dwordx2 v[150:151], v[146:147], off
	v_lshl_add_u64 v[150:151], v[144:145], 0, s[4:5]
	s_mov_b32 s4, 0x26dc8000
	v_cvt_pk_bf16_f32 v146, v122, v123
	v_cvt_pk_bf16_f32 v147, v124, v125
	v_add_co_u32_e32 v152, vcc, s4, v144
	global_store_dwordx2 v[148:149], v[146:147], off offset:32
	v_cvt_pk_bf16_f32 v146, v118, v119
	v_cvt_pk_bf16_f32 v147, v120, v121
	v_addc_co_u32_e32 v153, vcc, 0, v145, vcc
	global_store_dwordx2 v[152:153], v[146:147], off
	v_cvt_pk_bf16_f32 v146, v114, v115
	v_cvt_pk_bf16_f32 v147, v116, v117
	global_store_dwordx2 v[150:151], v[146:147], off offset:32
	s_mov_b64 s[4:5], 0x26dd0000
	v_lshl_add_u64 v[152:153], v[144:145], 0, s[4:5]
	s_mov_b32 s4, 0x26dd0000
	v_add_co_u32_e32 v154, vcc, s4, v144
	v_cvt_pk_bf16_f32 v146, v110, v111
	v_cvt_pk_bf16_f32 v147, v112, v113
	v_addc_co_u32_e32 v155, vcc, 0, v145, vcc
	s_mov_b64 s[4:5], 0x26dd8000
	global_store_dwordx2 v[154:155], v[146:147], off
	v_lshl_add_u64 v[154:155], v[144:145], 0, s[4:5]
	s_mov_b32 s4, 0x26dd8000
	v_cvt_pk_bf16_f32 v146, v106, v107
	v_cvt_pk_bf16_f32 v147, v108, v109
	v_add_co_u32_e32 v156, vcc, s4, v144
	global_store_dwordx2 v[152:153], v[146:147], off offset:32
	v_cvt_pk_bf16_f32 v146, v102, v103
	v_cvt_pk_bf16_f32 v147, v104, v105
	v_addc_co_u32_e32 v157, vcc, 0, v145, vcc
	global_store_dwordx2 v[156:157], v[146:147], off
	v_cvt_pk_bf16_f32 v146, v98, v99
	v_cvt_pk_bf16_f32 v147, v100, v101
	global_store_dwordx2 v[154:155], v[146:147], off offset:32
	v_cvt_pk_bf16_f32 v146, v94, v95
	v_cvt_pk_bf16_f32 v147, v96, v97
	global_store_dwordx2 v[148:149], v[146:147], off offset:256
	v_cvt_pk_bf16_f32 v146, v90, v91
	v_cvt_pk_bf16_f32 v147, v92, v93
	global_store_dwordx2 v[148:149], v[146:147], off offset:288
	v_cvt_pk_bf16_f32 v146, v86, v87
	v_cvt_pk_bf16_f32 v147, v88, v89
	global_store_dwordx2 v[150:151], v[146:147], off offset:256
	v_cvt_pk_bf16_f32 v146, v82, v83
	v_cvt_pk_bf16_f32 v147, v84, v85
	global_store_dwordx2 v[150:151], v[146:147], off offset:288
	v_cvt_pk_bf16_f32 v146, v78, v79
	v_cvt_pk_bf16_f32 v147, v80, v81
	global_store_dwordx2 v[152:153], v[146:147], off offset:256
	v_cvt_pk_bf16_f32 v146, v74, v75
	v_cvt_pk_bf16_f32 v147, v76, v77
	global_store_dwordx2 v[152:153], v[146:147], off offset:288
	v_cvt_pk_bf16_f32 v146, v70, v71
	v_cvt_pk_bf16_f32 v147, v72, v73
	global_store_dwordx2 v[154:155], v[146:147], off offset:256
	v_cvt_pk_bf16_f32 v146, v66, v67
	v_cvt_pk_bf16_f32 v147, v68, v69
	global_store_dwordx2 v[154:155], v[146:147], off offset:288
	s_mov_b64 s[4:5], 0x26e00000
	v_lshl_add_u64 v[148:149], v[144:145], 0, s[4:5]
	s_mov_b32 s4, 0x26e00000
	v_add_co_u32_e32 v150, vcc, s4, v144
	v_cvt_pk_bf16_f32 v146, v62, v63
	v_cvt_pk_bf16_f32 v147, v64, v65
	v_addc_co_u32_e32 v151, vcc, 0, v145, vcc
	s_mov_b64 s[4:5], 0x26e08000
	global_store_dwordx2 v[150:151], v[146:147], off
	v_lshl_add_u64 v[150:151], v[144:145], 0, s[4:5]
	s_mov_b32 s4, 0x26e08000
	v_cvt_pk_bf16_f32 v146, v58, v59
	v_cvt_pk_bf16_f32 v147, v60, v61
	v_add_co_u32_e32 v152, vcc, s4, v144
	global_store_dwordx2 v[148:149], v[146:147], off offset:32
	v_cvt_pk_bf16_f32 v146, v54, v55
	v_cvt_pk_bf16_f32 v147, v56, v57
	v_addc_co_u32_e32 v153, vcc, 0, v145, vcc
	global_store_dwordx2 v[152:153], v[146:147], off
	v_cvt_pk_bf16_f32 v146, v50, v51
	v_cvt_pk_bf16_f32 v147, v52, v53
	global_store_dwordx2 v[150:151], v[146:147], off offset:32
	s_mov_b64 s[4:5], 0x26e10000
	v_lshl_add_u64 v[152:153], v[144:145], 0, s[4:5]
	s_mov_b32 s4, 0x26e10000
	v_add_co_u32_e32 v154, vcc, s4, v144
	v_cvt_pk_bf16_f32 v146, v46, v47
	v_cvt_pk_bf16_f32 v147, v48, v49
	v_addc_co_u32_e32 v155, vcc, 0, v145, vcc
	s_mov_b64 s[4:5], 0x26e18000
	global_store_dwordx2 v[154:155], v[146:147], off
	v_lshl_add_u64 v[154:155], v[144:145], 0, s[4:5]
	s_mov_b32 s4, 0x26e18000
	v_cvt_pk_bf16_f32 v146, v42, v43
	v_cvt_pk_bf16_f32 v147, v44, v45
	v_add_co_u32_e32 v144, vcc, s4, v144
	global_store_dwordx2 v[152:153], v[146:147], off offset:32
	v_cvt_pk_bf16_f32 v146, v38, v39
	v_cvt_pk_bf16_f32 v147, v40, v41
	v_addc_co_u32_e32 v145, vcc, 0, v145, vcc
	global_store_dwordx2 v[144:145], v[146:147], off
	v_cvt_pk_bf16_f32 v144, v34, v35
	v_cvt_pk_bf16_f32 v145, v36, v37
	global_store_dwordx2 v[154:155], v[144:145], off offset:32
	v_cvt_pk_bf16_f32 v144, v30, v31
	v_cvt_pk_bf16_f32 v145, v32, v33
	global_store_dwordx2 v[148:149], v[144:145], off offset:256
	v_cvt_pk_bf16_f32 v144, v26, v27
	v_cvt_pk_bf16_f32 v145, v28, v29
	global_store_dwordx2 v[148:149], v[144:145], off offset:288
	v_cvt_pk_bf16_f32 v144, v22, v23
	v_cvt_pk_bf16_f32 v145, v24, v25
	global_store_dwordx2 v[150:151], v[144:145], off offset:256
	v_cvt_pk_bf16_f32 v144, v18, v19
	v_cvt_pk_bf16_f32 v145, v20, v21
	global_store_dwordx2 v[150:151], v[144:145], off offset:288
	v_cvt_pk_bf16_f32 v144, v14, v15
	v_cvt_pk_bf16_f32 v145, v16, v17
	global_store_dwordx2 v[152:153], v[144:145], off offset:256
	v_cvt_pk_bf16_f32 v144, v10, v11
	v_cvt_pk_bf16_f32 v145, v12, v13
	global_store_dwordx2 v[152:153], v[144:145], off offset:288
	v_cvt_pk_bf16_f32 v144, v6, v7
	v_cvt_pk_bf16_f32 v145, v8, v9
	global_store_dwordx2 v[154:155], v[144:145], off offset:256
	v_cvt_pk_bf16_f32 v144, v2, v3
	v_cvt_pk_bf16_f32 v145, v4, v5
	global_store_dwordx2 v[154:155], v[144:145], off offset:288
	s_mov_b64 s[8:9], 0
; #define GAS __attribute__((address_space(1)))
; __device__ __forceinline__ uint2 pack4(f32x4 v) { return make_uint2(pack2(v[0], v[1]), pack2(v[2], v[3])); }
; __device__ __forceinline__ float gelu_f(float x) {
;   const float c1 = -1.5957691216057308f * 1.4426950408889634f, c2 = c1 * 0.044715f;
;   float u = x * __builtin_fmaf(x * x, c2, c1);
;   return x * __builtin_amdgcn_rcpf(1.0f + __builtin_amdgcn_exp2f(u));
; }
; template <int MODE>
; __device__ __forceinline__ void epi_elem(char* ws, float* outp, const float* b_gate, int g0, int rl, int col, f32x4 v) {
;   if (MODE == E_U || MODE == E_GV) {
;     int lc = col & 1023;
;     f32x4 o; for (int i = 0; i < 4; ++i) o[i] = gelu_f(v[i]);
;     u16* dst = (u16*)(ws + (MODE == E_U ? W_U : W_GV));
;     *(GAS uint2*)(dst + (size_t)rl * 1024 + lc) = pack4(o);
.LBB0_994:
	s_andn2_b64 vcc, exec, s[8:9]
	s_cbranch_vccnz .LBB0_996
	v_mul_f32_e32 v141, v126, v126
	v_fmamk_f32 v141, v141, 0xbdd2d3e7, v198
	v_mul_f32_e32 v141, v126, v141
	v_exp_f32_e32 v141, v141
	v_lshlrev_b64 v[142:143], 11, v[142:143]
	v_lshl_add_u64 v[142:143], s[2:3], 0, v[142:143]
	s_mov_b64 s[2:3], 0x65c0000
	v_add_f32_e32 v141, 1.0, v141
	v_rcp_f32_e32 v144, v141
	v_mul_f32_e32 v141, v127, v127
	v_fmamk_f32 v141, v141, 0xbdd2d3e7, v198
	v_mul_f32_e32 v141, v127, v141
	v_exp_f32_e32 v141, v141
	v_lshl_add_u64 v[150:151], v[142:143], 0, s[2:3]
	s_mov_b64 s[2:3], 0x65c8000
	v_add_f32_e32 v141, 1.0, v141
	v_rcp_f32_e32 v145, v141
	v_mul_f32_e32 v141, v128, v128
	v_fmamk_f32 v141, v141, 0xbdd2d3e7, v198
	v_mul_f32_e32 v141, v128, v141
	v_exp_f32_e32 v141, v141
	v_pk_mul_f32 v[144:145], v[126:127], v[144:145]
	v_add_f32_e32 v141, 1.0, v141
	v_rcp_f32_e32 v146, v141
	v_mul_f32_e32 v141, v129, v129
	v_fmamk_f32 v141, v141, 0xbdd2d3e7, v198
	v_mul_f32_e32 v141, v129, v141
	v_exp_f32_e32 v141, v141
	v_cvt_pk_bf16_f32 v148, v144, v145
	v_mov_b32_e32 v145, v0
	v_add_f32_e32 v141, 1.0, v141
	v_rcp_f32_e32 v147, v141
	v_and_b32_e32 v141, 0x3ff, v140
	v_lshlrev_b32_e32 v144, 1, v141
	v_add_u32_e32 v141, 16, v140
	v_pk_mul_f32 v[146:147], v[128:129], v[146:147]
	v_and_b32_e32 v141, 0x3ff, v141
	v_cvt_pk_bf16_f32 v149, v146, v147
	v_lshl_add_u64 v[146:147], v[150:151], 0, v[144:145]
	global_store_dwordx2 v[146:147], v[148:149], off
	v_mul_f32_e32 v146, v122, v122
	v_mul_f32_e32 v147, v123, v123
	v_fmamk_f32 v146, v146, 0xbdd2d3e7, v198
	v_fmamk_f32 v147, v147, 0xbdd2d3e7, v198
	v_mul_f32_e32 v146, v122, v146
	v_mul_f32_e32 v147, v123, v147
	v_exp_f32_e32 v146, v146
	v_exp_f32_e32 v147, v147
	v_mul_f32_e32 v148, v124, v124
	v_mul_f32_e32 v149, v125, v125
	v_add_f32_e32 v146, 1.0, v146
	v_add_f32_e32 v147, 1.0, v147
	v_rcp_f32_e32 v146, v146
	v_rcp_f32_e32 v147, v147
	v_fmamk_f32 v148, v148, 0xbdd2d3e7, v198
	v_fmamk_f32 v149, v149, 0xbdd2d3e7, v198
	v_mul_f32_e32 v148, v124, v148
	v_mul_f32_e32 v149, v125, v149
	v_exp_f32_e32 v148, v148
	v_exp_f32_e32 v149, v149
	v_pk_mul_f32 v[146:147], v[122:123], v[146:147]
	v_add_f32_e32 v148, 1.0, v148
	v_cvt_pk_bf16_f32 v152, v146, v147
	v_lshlrev_b32_e32 v146, 1, v141
	v_mul_f32_e32 v141, v118, v118
	v_add_f32_e32 v149, 1.0, v149
	v_fmamk_f32 v141, v141, 0xbdd2d3e7, v198
	v_rcp_f32_e32 v148, v148
	v_rcp_f32_e32 v149, v149
	v_mul_f32_e32 v141, v118, v141
	v_exp_f32_e32 v141, v141
	v_mov_b32_e32 v147, v0
	v_pk_mul_f32 v[148:149], v[124:125], v[148:149]
	v_add_f32_e32 v141, 1.0, v141
	v_cvt_pk_bf16_f32 v153, v148, v149
	v_lshl_add_u64 v[148:149], v[150:151], 0, v[146:147]
	global_store_dwordx2 v[148:149], v[152:153], off
	v_rcp_f32_e32 v148, v141
	v_mul_f32_e32 v141, v119, v119
	v_fmamk_f32 v141, v141, 0xbdd2d3e7, v198
	v_mul_f32_e32 v141, v119, v141
	v_exp_f32_e32 v141, v141
	v_lshl_add_u64 v[152:153], v[142:143], 0, s[2:3]
	v_add_f32_e32 v141, 1.0, v141
	v_rcp_f32_e32 v149, v141
	v_mul_f32_e32 v141, v120, v120
	v_fmamk_f32 v141, v141, 0xbdd2d3e7, v198
	v_mul_f32_e32 v141, v120, v141
	v_exp_f32_e32 v141, v141
	v_pk_mul_f32 v[148:149], v[118:119], v[148:149]
	v_add_f32_e32 v141, 1.0, v141
	v_rcp_f32_e32 v154, v141
	v_mul_f32_e32 v141, v121, v121
	v_fmamk_f32 v141, v141, 0xbdd2d3e7, v198
	v_mul_f32_e32 v141, v121, v141
	v_exp_f32_e32 v141, v141
	v_cvt_pk_bf16_f32 v148, v148, v149
	v_add_f32_e32 v141, 1.0, v141
	v_rcp_f32_e32 v155, v141
	v_mul_f32_e32 v141, v114, v114
	v_fmamk_f32 v141, v141, 0xbdd2d3e7, v198
	v_mul_f32_e32 v141, v114, v141
	v_exp_f32_e32 v141, v141
	v_pk_mul_f32 v[154:155], v[120:121], v[154:155]
	v_add_f32_e32 v141, 1.0, v141
	v_cvt_pk_bf16_f32 v149, v154, v155
	v_lshl_add_u64 v[154:155], v[152:153], 0, v[144:145]
	global_store_dwordx2 v[154:155], v[148:149], off
	v_rcp_f32_e32 v148, v141
	v_mul_f32_e32 v141, v115, v115
	v_fmamk_f32 v141, v141, 0xbdd2d3e7, v198
	v_mul_f32_e32 v141, v115, v141
	v_exp_f32_e32 v141, v141
	s_nop 0
	v_add_f32_e32 v141, 1.0, v141
	v_rcp_f32_e32 v149, v141
	v_mul_f32_e32 v141, v116, v116
	v_fmamk_f32 v141, v141, 0xbdd2d3e7, v198
	v_mul_f32_e32 v141, v116, v141
	v_exp_f32_e32 v141, v141
	v_pk_mul_f32 v[148:149], v[114:115], v[148:149]
	v_add_f32_e32 v141, 1.0, v141
	v_rcp_f32_e32 v154, v141
	v_mul_f32_e32 v141, v117, v117
	v_fmamk_f32 v141, v141, 0xbdd2d3e7, v198
	v_mul_f32_e32 v141, v117, v141
	v_exp_f32_e32 v141, v141
	v_cvt_pk_bf16_f32 v148, v148, v149
	v_add_f32_e32 v141, 1.0, v141
	v_rcp_f32_e32 v155, v141
	s_nop 0
	v_pk_mul_f32 v[154:155], v[116:117], v[154:155]
	s_nop 0
	v_cvt_pk_bf16_f32 v149, v154, v155
	v_lshl_add_u64 v[154:155], v[152:153], 0, v[146:147]
	global_store_dwordx2 v[154:155], v[148:149], off
	v_mul_f32_e32 v141, v110, v110
	v_fmamk_f32 v141, v141, 0xbdd2d3e7, v198
	v_mul_f32_e32 v141, v110, v141
	v_exp_f32_e32 v141, v141
	s_mov_b64 s[2:3], 0x65d0000
	v_lshl_add_u64 v[156:157], v[142:143], 0, s[2:3]
	s_mov_b64 s[2:3], 0x65d8000
	v_add_f32_e32 v141, 1.0, v141
	v_rcp_f32_e32 v148, v141
	v_mul_f32_e32 v141, v111, v111
	v_fmamk_f32 v141, v141, 0xbdd2d3e7, v198
	v_mul_f32_e32 v141, v111, v141
	v_exp_f32_e32 v141, v141
	s_nop 0
	v_add_f32_e32 v141, 1.0, v141
	v_rcp_f32_e32 v149, v141
	v_mul_f32_e32 v141, v112, v112
	v_fmamk_f32 v141, v141, 0xbdd2d3e7, v198
	v_mul_f32_e32 v141, v112, v141
	v_exp_f32_e32 v141, v141
	v_pk_mul_f32 v[148:149], v[110:111], v[148:149]
	v_add_f32_e32 v141, 1.0, v141
	v_rcp_f32_e32 v154, v141
	v_mul_f32_e32 v141, v113, v113
	v_fmamk_f32 v141, v141, 0xbdd2d3e7, v198
	v_mul_f32_e32 v141, v113, v141
	v_exp_f32_e32 v141, v141
	v_cvt_pk_bf16_f32 v148, v148, v149
	v_add_f32_e32 v141, 1.0, v141
	v_rcp_f32_e32 v155, v141
; #define GAS __attribute__((address_space(1)))
; __device__ __forceinline__ uint2 pack4(f32x4 v) { return make_uint2(pack2(v[0], v[1]), pack2(v[2], v[3])); }
; __device__ __forceinline__ float gelu_f(float x) {
;   const float c1 = -1.5957691216057308f * 1.4426950408889634f, c2 = c1 * 0.044715f;
;   float u = x * __builtin_fmaf(x * x, c2, c1);
;   return x * __builtin_amdgcn_rcpf(1.0f + __builtin_amdgcn_exp2f(u));
; }
; template <int MODE>
; __device__ __forceinline__ void epi_elem(char* ws, float* outp, const float* b_gate, int g0, int rl, int col, f32x4 v) {
;   if (MODE == E_U || MODE == E_GV) {
;     int lc = col & 1023;
;     f32x4 o; for (int i = 0; i < 4; ++i) o[i] = gelu_f(v[i]);
;     u16* dst = (u16*)(ws + (MODE == E_U ? W_U : W_GV));
;     *(GAS uint2*)(dst + (size_t)rl * 1024 + lc) = pack4(o);
	v_mul_f32_e32 v141, v106, v106
	v_fmamk_f32 v141, v141, 0xbdd2d3e7, v198
	v_mul_f32_e32 v141, v106, v141
	v_exp_f32_e32 v141, v141
	v_pk_mul_f32 v[154:155], v[112:113], v[154:155]
	v_add_f32_e32 v141, 1.0, v141
	v_cvt_pk_bf16_f32 v149, v154, v155
	v_lshl_add_u64 v[154:155], v[156:157], 0, v[144:145]
	global_store_dwordx2 v[154:155], v[148:149], off
	v_rcp_f32_e32 v148, v141
	v_mul_f32_e32 v141, v107, v107
	v_fmamk_f32 v141, v141, 0xbdd2d3e7, v198
	v_mul_f32_e32 v141, v107, v141
	v_exp_f32_e32 v141, v141
	s_nop 0
	v_add_f32_e32 v141, 1.0, v141
	v_rcp_f32_e32 v149, v141
	v_mul_f32_e32 v141, v108, v108
	v_fmamk_f32 v141, v141, 0xbdd2d3e7, v198
	v_mul_f32_e32 v141, v108, v141
	v_exp_f32_e32 v141, v141
	v_pk_mul_f32 v[148:149], v[106:107], v[148:149]
	v_add_f32_e32 v141, 1.0, v141
	v_rcp_f32_e32 v154, v141
	v_mul_f32_e32 v141, v109, v109
	v_fmamk_f32 v141, v141, 0xbdd2d3e7, v198
	v_mul_f32_e32 v141, v109, v141
	v_exp_f32_e32 v141, v141
	v_cvt_pk_bf16_f32 v148, v148, v149
	v_add_f32_e32 v141, 1.0, v141
	v_rcp_f32_e32 v155, v141
	v_mul_f32_e32 v141, v102, v102
	v_fmamk_f32 v141, v141, 0xbdd2d3e7, v198
	v_mul_f32_e32 v141, v102, v141
	v_exp_f32_e32 v141, v141
	v_pk_mul_f32 v[154:155], v[108:109], v[154:155]
	v_add_f32_e32 v141, 1.0, v141
	v_cvt_pk_bf16_f32 v149, v154, v155
	v_lshl_add_u64 v[154:155], v[156:157], 0, v[146:147]
	global_store_dwordx2 v[154:155], v[148:149], off
	v_rcp_f32_e32 v148, v141
	v_mul_f32_e32 v141, v103, v103
	v_fmamk_f32 v141, v141, 0xbdd2d3e7, v198
	v_mul_f32_e32 v141, v103, v141
	v_exp_f32_e32 v141, v141
	v_lshl_add_u64 v[154:155], v[142:143], 0, s[2:3]
	v_add_f32_e32 v141, 1.0, v141
	v_rcp_f32_e32 v149, v141
	v_mul_f32_e32 v141, v104, v104
	v_fmamk_f32 v141, v141, 0xbdd2d3e7, v198
	v_mul_f32_e32 v141, v104, v141
	v_exp_f32_e32 v141, v141
	v_pk_mul_f32 v[148:149], v[102:103], v[148:149]
	v_add_f32_e32 v141, 1.0, v141
	v_rcp_f32_e32 v158, v141
	v_mul_f32_e32 v141, v105, v105
	v_fmamk_f32 v141, v141, 0xbdd2d3e7, v198
	v_mul_f32_e32 v141, v105, v141
	v_exp_f32_e32 v141, v141
	v_cvt_pk_bf16_f32 v148, v148, v149
	v_add_f32_e32 v141, 1.0, v141
	v_rcp_f32_e32 v159, v141
	v_mul_f32_e32 v141, v98, v98
	v_fmamk_f32 v141, v141, 0xbdd2d3e7, v198
	v_mul_f32_e32 v141, v98, v141
	v_exp_f32_e32 v141, v141
	v_pk_mul_f32 v[158:159], v[104:105], v[158:159]
	v_add_f32_e32 v141, 1.0, v141
	v_cvt_pk_bf16_f32 v149, v158, v159
	v_lshl_add_u64 v[158:159], v[154:155], 0, v[144:145]
	global_store_dwordx2 v[158:159], v[148:149], off
	v_rcp_f32_e32 v148, v141
	v_mul_f32_e32 v141, v99, v99
	v_fmamk_f32 v141, v141, 0xbdd2d3e7, v198
	v_mul_f32_e32 v141, v99, v141
	v_exp_f32_e32 v141, v141
	s_nop 0
	v_add_f32_e32 v141, 1.0, v141
	v_rcp_f32_e32 v149, v141
	v_mul_f32_e32 v141, v100, v100
	v_fmamk_f32 v141, v141, 0xbdd2d3e7, v198
	v_mul_f32_e32 v141, v100, v141
	v_exp_f32_e32 v141, v141
	v_pk_mul_f32 v[148:149], v[98:99], v[148:149]
	v_add_f32_e32 v141, 1.0, v141
	v_rcp_f32_e32 v158, v141
	v_mul_f32_e32 v141, v101, v101
	v_fmamk_f32 v141, v141, 0xbdd2d3e7, v198
	v_mul_f32_e32 v141, v101, v141
	v_exp_f32_e32 v141, v141
	v_cvt_pk_bf16_f32 v148, v148, v149
	v_add_f32_e32 v141, 1.0, v141
	v_rcp_f32_e32 v159, v141
	s_nop 0
	v_pk_mul_f32 v[158:159], v[100:101], v[158:159]
	s_nop 0
	v_cvt_pk_bf16_f32 v149, v158, v159
	v_lshl_add_u64 v[158:159], v[154:155], 0, v[146:147]
	global_store_dwordx2 v[158:159], v[148:149], off
	v_mul_f32_e32 v148, v94, v94
	v_mul_f32_e32 v149, v95, v95
	v_fmamk_f32 v148, v148, 0xbdd2d3e7, v198
	v_fmamk_f32 v149, v149, 0xbdd2d3e7, v198
	v_mul_f32_e32 v158, v96, v96
	v_mul_f32_e32 v159, v97, v97
	v_mul_f32_e32 v148, v94, v148
	v_mul_f32_e32 v149, v95, v149
	v_fmamk_f32 v158, v158, 0xbdd2d3e7, v198
	v_fmamk_f32 v159, v159, 0xbdd2d3e7, v198
	v_exp_f32_e32 v148, v148
	v_exp_f32_e32 v149, v149
	v_mul_f32_e32 v158, v96, v158
	v_mul_f32_e32 v159, v97, v159
	v_exp_f32_e32 v158, v158
	v_exp_f32_e32 v159, v159
	v_add_f32_e32 v148, 1.0, v148
	v_add_f32_e32 v149, 1.0, v149
	v_rcp_f32_e32 v148, v148
	v_rcp_f32_e32 v149, v149
	v_add_f32_e32 v158, 1.0, v158
	v_add_f32_e32 v159, 1.0, v159
	v_rcp_f32_e32 v158, v158
	v_rcp_f32_e32 v159, v159
	v_add_u32_e32 v141, 0x80, v140
	v_pk_mul_f32 v[148:149], v[94:95], v[148:149]
	v_and_b32_e32 v141, 0x3ff, v141
	v_pk_mul_f32 v[158:159], v[96:97], v[158:159]
	v_cvt_pk_bf16_f32 v160, v148, v149
	v_lshlrev_b32_e32 v148, 1, v141
	v_mov_b32_e32 v149, v0
	v_cvt_pk_bf16_f32 v161, v158, v159
	v_lshl_add_u64 v[158:159], v[150:151], 0, v[148:149]
	global_store_dwordx2 v[158:159], v[160:161], off
	v_add_u32_e32 v160, 0x90, v140
	v_mul_f32_e32 v140, v90, v90
	v_mul_f32_e32 v141, v91, v91
	v_fmamk_f32 v140, v140, 0xbdd2d3e7, v198
	v_fmamk_f32 v141, v141, 0xbdd2d3e7, v198
	v_mul_f32_e32 v158, v92, v92
	v_mul_f32_e32 v159, v93, v93
	v_mul_f32_e32 v140, v90, v140
	v_mul_f32_e32 v141, v91, v141
	v_fmamk_f32 v158, v158, 0xbdd2d3e7, v198
	v_fmamk_f32 v159, v159, 0xbdd2d3e7, v198
	v_exp_f32_e32 v140, v140
	v_exp_f32_e32 v141, v141
	v_mul_f32_e32 v158, v92, v158
	v_mul_f32_e32 v159, v93, v159
	v_exp_f32_e32 v158, v158
	v_exp_f32_e32 v159, v159
	v_add_f32_e32 v140, 1.0, v140
	v_add_f32_e32 v141, 1.0, v141
	v_rcp_f32_e32 v140, v140
	v_rcp_f32_e32 v141, v141
	v_add_f32_e32 v158, 1.0, v158
	v_add_f32_e32 v159, 1.0, v159
	v_rcp_f32_e32 v158, v158
	v_rcp_f32_e32 v159, v159
	v_pk_mul_f32 v[140:141], v[90:91], v[140:141]
	v_and_b32_e32 v162, 0x3ff, v160
	v_cvt_pk_bf16_f32 v160, v140, v141
	v_pk_mul_f32 v[158:159], v[92:93], v[158:159]
	v_lshlrev_b32_e32 v140, 1, v162
	v_mov_b32_e32 v141, v0
	v_cvt_pk_bf16_f32 v161, v158, v159
	v_lshl_add_u64 v[150:151], v[150:151], 0, v[140:141]
	global_store_dwordx2 v[150:151], v[160:161], off
; #define GAS __attribute__((address_space(1)))
; __device__ __forceinline__ uint2 pack4(f32x4 v) { return make_uint2(pack2(v[0], v[1]), pack2(v[2], v[3])); }
; __device__ __forceinline__ float gelu_f(float x) {
;   const float c1 = -1.5957691216057308f * 1.4426950408889634f, c2 = c1 * 0.044715f;
;   float u = x * __builtin_fmaf(x * x, c2, c1);
;   return x * __builtin_amdgcn_rcpf(1.0f + __builtin_amdgcn_exp2f(u));
; }
; template <int MODE>
; __device__ __forceinline__ void epi_elem(char* ws, float* outp, const float* b_gate, int g0, int rl, int col, f32x4 v) {
;   if (MODE == E_U || MODE == E_GV) {
;     int lc = col & 1023;
;     f32x4 o; for (int i = 0; i < 4; ++i) o[i] = gelu_f(v[i]);
;     u16* dst = (u16*)(ws + (MODE == E_U ? W_U : W_GV));
;     *(GAS uint2*)(dst + (size_t)rl * 1024 + lc) = pack4(o);
	v_mul_f32_e32 v150, v86, v86
	v_mul_f32_e32 v151, v87, v87
	v_mul_f32_e32 v158, v88, v88
	v_mul_f32_e32 v159, v89, v89
	v_fmamk_f32 v150, v150, 0xbdd2d3e7, v198
	v_fmamk_f32 v151, v151, 0xbdd2d3e7, v198
	v_fmamk_f32 v158, v158, 0xbdd2d3e7, v198
	v_fmamk_f32 v159, v159, 0xbdd2d3e7, v198
	v_mul_f32_e32 v150, v86, v150
	v_mul_f32_e32 v151, v87, v151
	v_mul_f32_e32 v158, v88, v158
	v_mul_f32_e32 v159, v89, v159
	v_exp_f32_e32 v150, v150
	v_exp_f32_e32 v151, v151
	v_exp_f32_e32 v158, v158
	v_exp_f32_e32 v159, v159
	v_add_f32_e32 v150, 1.0, v150
	v_add_f32_e32 v151, 1.0, v151
	v_add_f32_e32 v158, 1.0, v158
	v_add_f32_e32 v159, 1.0, v159
	v_rcp_f32_e32 v150, v150
	v_rcp_f32_e32 v151, v151
	v_rcp_f32_e32 v158, v158
	v_rcp_f32_e32 v159, v159
	v_pk_mul_f32 v[150:151], v[86:87], v[150:151]
	s_nop 0
	v_cvt_pk_bf16_f32 v150, v150, v151
	v_pk_mul_f32 v[158:159], v[88:89], v[158:159]
	s_nop 0
	v_cvt_pk_bf16_f32 v151, v158, v159
	v_lshl_add_u64 v[158:159], v[152:153], 0, v[148:149]
	global_store_dwordx2 v[158:159], v[150:151], off
	v_mul_f32_e32 v150, v82, v82
	v_mul_f32_e32 v151, v83, v83
	v_mul_f32_e32 v158, v84, v84
	v_mul_f32_e32 v159, v85, v85
	v_fmamk_f32 v150, v150, 0xbdd2d3e7, v198
	v_fmamk_f32 v151, v151, 0xbdd2d3e7, v198
	v_fmamk_f32 v158, v158, 0xbdd2d3e7, v198
	v_fmamk_f32 v159, v159, 0xbdd2d3e7, v198
	v_mul_f32_e32 v150, v82, v150
	v_mul_f32_e32 v151, v83, v151
	v_mul_f32_e32 v158, v84, v158
	v_mul_f32_e32 v159, v85, v159
	v_exp_f32_e32 v150, v150
	v_exp_f32_e32 v151, v151
	v_exp_f32_e32 v158, v158
	v_exp_f32_e32 v159, v159
	v_add_f32_e32 v150, 1.0, v150
	v_add_f32_e32 v151, 1.0, v151
	v_add_f32_e32 v158, 1.0, v158
	v_add_f32_e32 v159, 1.0, v159
	v_rcp_f32_e32 v150, v150
	v_rcp_f32_e32 v151, v151
	v_rcp_f32_e32 v158, v158
	v_rcp_f32_e32 v159, v159
	v_lshl_add_u64 v[152:153], v[152:153], 0, v[140:141]
	v_pk_mul_f32 v[150:151], v[82:83], v[150:151]
	v_pk_mul_f32 v[158:159], v[84:85], v[158:159]
	v_cvt_pk_bf16_f32 v150, v150, v151
	v_cvt_pk_bf16_f32 v151, v158, v159
	global_store_dwordx2 v[152:153], v[150:151], off
	v_mul_f32_e32 v150, v78, v78
	v_mul_f32_e32 v151, v79, v79
	v_mul_f32_e32 v152, v80, v80
	v_mul_f32_e32 v153, v81, v81
	v_fmamk_f32 v150, v150, 0xbdd2d3e7, v198
	v_fmamk_f32 v151, v151, 0xbdd2d3e7, v198
	v_fmamk_f32 v152, v152, 0xbdd2d3e7, v198
	v_fmamk_f32 v153, v153, 0xbdd2d3e7, v198
	v_mul_f32_e32 v150, v78, v150
	v_mul_f32_e32 v151, v79, v151
	v_mul_f32_e32 v152, v80, v152
	v_mul_f32_e32 v153, v81, v153
	v_exp_f32_e32 v150, v150
	v_exp_f32_e32 v151, v151
	v_exp_f32_e32 v152, v152
	v_exp_f32_e32 v153, v153
	v_add_f32_e32 v150, 1.0, v150
	v_add_f32_e32 v151, 1.0, v151
	v_add_f32_e32 v152, 1.0, v152
	v_add_f32_e32 v153, 1.0, v153
	v_rcp_f32_e32 v150, v150
	v_rcp_f32_e32 v151, v151
	v_rcp_f32_e32 v152, v152
	v_rcp_f32_e32 v153, v153
	v_pk_mul_f32 v[150:151], v[78:79], v[150:151]
	s_nop 0
	v_cvt_pk_bf16_f32 v150, v150, v151
	v_pk_mul_f32 v[152:153], v[80:81], v[152:153]
	s_nop 0
	v_cvt_pk_bf16_f32 v151, v152, v153
	v_lshl_add_u64 v[152:153], v[156:157], 0, v[148:149]
	global_store_dwordx2 v[152:153], v[150:151], off
	v_mul_f32_e32 v150, v74, v74
	v_mul_f32_e32 v151, v75, v75
	v_mul_f32_e32 v152, v76, v76
	v_mul_f32_e32 v153, v77, v77
	v_fmamk_f32 v150, v150, 0xbdd2d3e7, v198
	v_fmamk_f32 v151, v151, 0xbdd2d3e7, v198
	v_fmamk_f32 v152, v152, 0xbdd2d3e7, v198
	v_fmamk_f32 v153, v153, 0xbdd2d3e7, v198
	v_mul_f32_e32 v150, v74, v150
	v_mul_f32_e32 v151, v75, v151
	v_mul_f32_e32 v152, v76, v152
	v_mul_f32_e32 v153, v77, v153
	v_exp_f32_e32 v150, v150
	v_exp_f32_e32 v151, v151
	v_exp_f32_e32 v152, v152
	v_exp_f32_e32 v153, v153
	v_add_f32_e32 v150, 1.0, v150
	v_add_f32_e32 v151, 1.0, v151
	v_add_f32_e32 v152, 1.0, v152
	v_add_f32_e32 v153, 1.0, v153
	v_rcp_f32_e32 v150, v150
	v_rcp_f32_e32 v151, v151
	v_rcp_f32_e32 v152, v152
	v_rcp_f32_e32 v153, v153
	v_pk_mul_f32 v[150:151], v[74:75], v[150:151]
	s_nop 0
	v_cvt_pk_bf16_f32 v150, v150, v151
	v_pk_mul_f32 v[152:153], v[76:77], v[152:153]
	s_nop 0
	v_cvt_pk_bf16_f32 v151, v152, v153
	v_lshl_add_u64 v[152:153], v[156:157], 0, v[140:141]
	global_store_dwordx2 v[152:153], v[150:151], off
	v_mul_f32_e32 v150, v70, v70
	v_mul_f32_e32 v151, v71, v71
	v_mul_f32_e32 v152, v72, v72
	v_mul_f32_e32 v153, v73, v73
	v_fmamk_f32 v150, v150, 0xbdd2d3e7, v198
	v_fmamk_f32 v151, v151, 0xbdd2d3e7, v198
	v_fmamk_f32 v152, v152, 0xbdd2d3e7, v198
	v_fmamk_f32 v153, v153, 0xbdd2d3e7, v198
	v_mul_f32_e32 v150, v70, v150
	v_mul_f32_e32 v151, v71, v151
	v_mul_f32_e32 v152, v72, v152
	v_mul_f32_e32 v153, v73, v153
	v_exp_f32_e32 v150, v150
	v_exp_f32_e32 v151, v151
	v_exp_f32_e32 v152, v152
	v_exp_f32_e32 v153, v153
	v_add_f32_e32 v150, 1.0, v150
	v_add_f32_e32 v151, 1.0, v151
	v_add_f32_e32 v152, 1.0, v152
	v_add_f32_e32 v153, 1.0, v153
	v_rcp_f32_e32 v150, v150
	v_rcp_f32_e32 v151, v151
	v_rcp_f32_e32 v152, v152
	v_rcp_f32_e32 v153, v153
	v_pk_mul_f32 v[150:151], v[70:71], v[150:151]
	s_nop 0
	v_cvt_pk_bf16_f32 v150, v150, v151
	v_pk_mul_f32 v[152:153], v[72:73], v[152:153]
	s_nop 0
	v_cvt_pk_bf16_f32 v151, v152, v153
	v_lshl_add_u64 v[152:153], v[154:155], 0, v[148:149]
	global_store_dwordx2 v[152:153], v[150:151], off
	v_mul_f32_e32 v150, v66, v66
	v_mul_f32_e32 v151, v67, v67
	v_mul_f32_e32 v152, v68, v68
	v_mul_f32_e32 v153, v69, v69
	v_fmamk_f32 v150, v150, 0xbdd2d3e7, v198
	v_fmamk_f32 v151, v151, 0xbdd2d3e7, v198
	v_fmamk_f32 v152, v152, 0xbdd2d3e7, v198
	v_fmamk_f32 v153, v153, 0xbdd2d3e7, v198
	v_mul_f32_e32 v150, v66, v150
	v_mul_f32_e32 v151, v67, v151
	v_mul_f32_e32 v152, v68, v152
	v_mul_f32_e32 v153, v69, v153
	v_exp_f32_e32 v150, v150
	v_exp_f32_e32 v151, v151
	v_exp_f32_e32 v152, v152
; #define GAS __attribute__((address_space(1)))
; __device__ __forceinline__ uint2 pack4(f32x4 v) { return make_uint2(pack2(v[0], v[1]), pack2(v[2], v[3])); }
; __device__ __forceinline__ float gelu_f(float x) {
;   const float c1 = -1.5957691216057308f * 1.4426950408889634f, c2 = c1 * 0.044715f;
;   float u = x * __builtin_fmaf(x * x, c2, c1);
;   return x * __builtin_amdgcn_rcpf(1.0f + __builtin_amdgcn_exp2f(u));
; }
; template <int MODE>
; __device__ __forceinline__ void epi_elem(char* ws, float* outp, const float* b_gate, int g0, int rl, int col, f32x4 v) {
;   if (MODE == E_U || MODE == E_GV) {
;     int lc = col & 1023;
;     f32x4 o; for (int i = 0; i < 4; ++i) o[i] = gelu_f(v[i]);
;     u16* dst = (u16*)(ws + (MODE == E_U ? W_U : W_GV));
;     *(GAS uint2*)(dst + (size_t)rl * 1024 + lc) = pack4(o);
	v_exp_f32_e32 v153, v153
	v_add_f32_e32 v150, 1.0, v150
	v_add_f32_e32 v151, 1.0, v151
	v_add_f32_e32 v152, 1.0, v152
	v_add_f32_e32 v153, 1.0, v153
	v_rcp_f32_e32 v150, v150
	v_rcp_f32_e32 v151, v151
	v_rcp_f32_e32 v152, v152
	v_rcp_f32_e32 v153, v153
	v_pk_mul_f32 v[150:151], v[66:67], v[150:151]
	s_nop 0
	v_cvt_pk_bf16_f32 v150, v150, v151
	v_pk_mul_f32 v[152:153], v[68:69], v[152:153]
	s_nop 0
	v_cvt_pk_bf16_f32 v151, v152, v153
	v_lshl_add_u64 v[152:153], v[154:155], 0, v[140:141]
	global_store_dwordx2 v[152:153], v[150:151], off
	v_mul_f32_e32 v150, v62, v62
	v_mul_f32_e32 v151, v63, v63
	v_mul_f32_e32 v154, v64, v64
	v_mul_f32_e32 v155, v65, v65
	v_fmamk_f32 v150, v150, 0xbdd2d3e7, v198
	v_fmamk_f32 v151, v151, 0xbdd2d3e7, v198
	v_fmamk_f32 v154, v154, 0xbdd2d3e7, v198
	v_fmamk_f32 v155, v155, 0xbdd2d3e7, v198
	v_mul_f32_e32 v150, v62, v150
	v_mul_f32_e32 v151, v63, v151
	v_mul_f32_e32 v154, v64, v154
	v_mul_f32_e32 v155, v65, v155
	v_exp_f32_e32 v150, v150
	v_exp_f32_e32 v151, v151
	v_exp_f32_e32 v154, v154
	v_exp_f32_e32 v155, v155
	v_add_f32_e32 v150, 1.0, v150
	v_add_f32_e32 v151, 1.0, v151
	v_add_f32_e32 v154, 1.0, v154
	v_add_f32_e32 v155, 1.0, v155
	v_rcp_f32_e32 v150, v150
	v_rcp_f32_e32 v151, v151
	v_rcp_f32_e32 v154, v154
	v_rcp_f32_e32 v155, v155
	s_mov_b64 s[2:3], 0x6600000
	v_lshl_add_u64 v[152:153], v[142:143], 0, s[2:3]
	v_pk_mul_f32 v[150:151], v[62:63], v[150:151]
	v_pk_mul_f32 v[154:155], v[64:65], v[154:155]
	v_cvt_pk_bf16_f32 v150, v150, v151
	v_cvt_pk_bf16_f32 v151, v154, v155
	v_lshl_add_u64 v[154:155], v[152:153], 0, v[144:145]
	global_store_dwordx2 v[154:155], v[150:151], off
	v_mul_f32_e32 v150, v58, v58
	v_mul_f32_e32 v151, v59, v59
	v_mul_f32_e32 v154, v60, v60
	v_mul_f32_e32 v155, v61, v61
	v_fmamk_f32 v150, v150, 0xbdd2d3e7, v198
	v_fmamk_f32 v151, v151, 0xbdd2d3e7, v198
	v_fmamk_f32 v154, v154, 0xbdd2d3e7, v198
	v_fmamk_f32 v155, v155, 0xbdd2d3e7, v198
	v_mul_f32_e32 v150, v58, v150
	v_mul_f32_e32 v151, v59, v151
	v_mul_f32_e32 v154, v60, v154
	v_mul_f32_e32 v155, v61, v155
	v_exp_f32_e32 v150, v150
	v_exp_f32_e32 v151, v151
	v_exp_f32_e32 v154, v154
	v_exp_f32_e32 v155, v155
	v_add_f32_e32 v150, 1.0, v150
	v_add_f32_e32 v151, 1.0, v151
	v_add_f32_e32 v154, 1.0, v154
	v_add_f32_e32 v155, 1.0, v155
	v_rcp_f32_e32 v150, v150
	v_rcp_f32_e32 v151, v151
	v_rcp_f32_e32 v154, v154
	v_rcp_f32_e32 v155, v155
	v_mul_f32_e32 v156, v56, v56
	v_pk_mul_f32 v[150:151], v[58:59], v[150:151]
	v_mul_f32_e32 v157, v57, v57
	v_pk_mul_f32 v[154:155], v[60:61], v[154:155]
	v_cvt_pk_bf16_f32 v150, v150, v151
	v_cvt_pk_bf16_f32 v151, v154, v155
	v_lshl_add_u64 v[154:155], v[152:153], 0, v[146:147]
	global_store_dwordx2 v[154:155], v[150:151], off
	v_mul_f32_e32 v154, v54, v54
	v_mul_f32_e32 v155, v55, v55
	v_fmamk_f32 v154, v154, 0xbdd2d3e7, v198
	v_fmamk_f32 v155, v155, 0xbdd2d3e7, v198
	v_fmamk_f32 v156, v156, 0xbdd2d3e7, v198
	v_fmamk_f32 v157, v157, 0xbdd2d3e7, v198
	v_mul_f32_e32 v154, v54, v154
	v_mul_f32_e32 v155, v55, v155
	v_mul_f32_e32 v156, v56, v156
	v_mul_f32_e32 v157, v57, v157
	v_exp_f32_e32 v154, v154
	v_exp_f32_e32 v155, v155
	v_exp_f32_e32 v156, v156
	v_exp_f32_e32 v157, v157
	v_add_f32_e32 v154, 1.0, v154
	v_add_f32_e32 v155, 1.0, v155
	v_add_f32_e32 v156, 1.0, v156
	v_add_f32_e32 v157, 1.0, v157
	v_rcp_f32_e32 v154, v154
	v_rcp_f32_e32 v155, v155
	v_rcp_f32_e32 v156, v156
	v_rcp_f32_e32 v157, v157
	s_mov_b64 s[2:3], 0x6608000
	v_lshl_add_u64 v[150:151], v[142:143], 0, s[2:3]
	v_pk_mul_f32 v[154:155], v[54:55], v[154:155]
	v_pk_mul_f32 v[156:157], v[56:57], v[156:157]
	v_cvt_pk_bf16_f32 v154, v154, v155
	v_cvt_pk_bf16_f32 v155, v156, v157
	v_lshl_add_u64 v[156:157], v[150:151], 0, v[144:145]
	global_store_dwordx2 v[156:157], v[154:155], off
	v_mul_f32_e32 v154, v50, v50
	v_mul_f32_e32 v155, v51, v51
	v_mul_f32_e32 v156, v52, v52
	v_mul_f32_e32 v157, v53, v53
	v_fmamk_f32 v154, v154, 0xbdd2d3e7, v198
	v_fmamk_f32 v155, v155, 0xbdd2d3e7, v198
	v_fmamk_f32 v156, v156, 0xbdd2d3e7, v198
	v_fmamk_f32 v157, v157, 0xbdd2d3e7, v198
	v_mul_f32_e32 v154, v50, v154
	v_mul_f32_e32 v155, v51, v155
	v_mul_f32_e32 v156, v52, v156
	v_mul_f32_e32 v157, v53, v157
	v_exp_f32_e32 v154, v154
	v_exp_f32_e32 v155, v155
	v_exp_f32_e32 v156, v156
	v_exp_f32_e32 v157, v157
	v_add_f32_e32 v154, 1.0, v154
	v_add_f32_e32 v155, 1.0, v155
	v_add_f32_e32 v156, 1.0, v156
	v_add_f32_e32 v157, 1.0, v157
	v_rcp_f32_e32 v154, v154
	v_rcp_f32_e32 v155, v155
	v_rcp_f32_e32 v156, v156
	v_rcp_f32_e32 v157, v157
	v_pk_mul_f32 v[154:155], v[50:51], v[154:155]
	s_nop 0
	v_cvt_pk_bf16_f32 v154, v154, v155
	v_pk_mul_f32 v[156:157], v[52:53], v[156:157]
	s_nop 0
	v_cvt_pk_bf16_f32 v155, v156, v157
	v_lshl_add_u64 v[156:157], v[150:151], 0, v[146:147]
	global_store_dwordx2 v[156:157], v[154:155], off
	v_mul_f32_e32 v156, v46, v46
	v_mul_f32_e32 v157, v47, v47
	v_mul_f32_e32 v158, v48, v48
	v_mul_f32_e32 v159, v49, v49
	v_fmamk_f32 v156, v156, 0xbdd2d3e7, v198
	v_fmamk_f32 v157, v157, 0xbdd2d3e7, v198
	v_fmamk_f32 v158, v158, 0xbdd2d3e7, v198
	v_fmamk_f32 v159, v159, 0xbdd2d3e7, v198
	v_mul_f32_e32 v156, v46, v156
	v_mul_f32_e32 v157, v47, v157
	v_mul_f32_e32 v158, v48, v158
	v_mul_f32_e32 v159, v49, v159
	v_exp_f32_e32 v156, v156
	v_exp_f32_e32 v157, v157
	v_exp_f32_e32 v158, v158
	v_exp_f32_e32 v159, v159
	v_add_f32_e32 v156, 1.0, v156
	v_add_f32_e32 v157, 1.0, v157
	v_add_f32_e32 v158, 1.0, v158
	v_add_f32_e32 v159, 1.0, v159
	v_rcp_f32_e32 v156, v156
	v_rcp_f32_e32 v157, v157
	v_rcp_f32_e32 v158, v158
	v_rcp_f32_e32 v159, v159
	s_mov_b64 s[2:3], 0x6610000
	v_lshl_add_u64 v[154:155], v[142:143], 0, s[2:3]
	v_pk_mul_f32 v[156:157], v[46:47], v[156:157]
; #define GAS __attribute__((address_space(1)))
; __device__ __forceinline__ uint2 pack4(f32x4 v) { return make_uint2(pack2(v[0], v[1]), pack2(v[2], v[3])); }
; __device__ __forceinline__ float gelu_f(float x) {
;   const float c1 = -1.5957691216057308f * 1.4426950408889634f, c2 = c1 * 0.044715f;
;   float u = x * __builtin_fmaf(x * x, c2, c1);
;   return x * __builtin_amdgcn_rcpf(1.0f + __builtin_amdgcn_exp2f(u));
; }
; template <int MODE>
; __device__ __forceinline__ void epi_elem(char* ws, float* outp, const float* b_gate, int g0, int rl, int col, f32x4 v) {
;   if (MODE == E_U || MODE == E_GV) {
;     int lc = col & 1023;
;     f32x4 o; for (int i = 0; i < 4; ++i) o[i] = gelu_f(v[i]);
;     u16* dst = (u16*)(ws + (MODE == E_U ? W_U : W_GV));
;     *(GAS uint2*)(dst + (size_t)rl * 1024 + lc) = pack4(o);
	v_pk_mul_f32 v[158:159], v[48:49], v[158:159]
	v_cvt_pk_bf16_f32 v156, v156, v157
	v_cvt_pk_bf16_f32 v157, v158, v159
	v_lshl_add_u64 v[158:159], v[154:155], 0, v[144:145]
	global_store_dwordx2 v[158:159], v[156:157], off
	v_mul_f32_e32 v156, v42, v42
	v_mul_f32_e32 v157, v43, v43
	v_mul_f32_e32 v158, v44, v44
	v_mul_f32_e32 v159, v45, v45
	v_fmamk_f32 v156, v156, 0xbdd2d3e7, v198
	v_fmamk_f32 v157, v157, 0xbdd2d3e7, v198
	v_fmamk_f32 v158, v158, 0xbdd2d3e7, v198
	v_fmamk_f32 v159, v159, 0xbdd2d3e7, v198
	v_mul_f32_e32 v156, v42, v156
	v_mul_f32_e32 v157, v43, v157
	v_mul_f32_e32 v158, v44, v158
	v_mul_f32_e32 v159, v45, v159
	v_exp_f32_e32 v156, v156
	v_exp_f32_e32 v157, v157
	v_exp_f32_e32 v158, v158
	v_exp_f32_e32 v159, v159
	v_add_f32_e32 v156, 1.0, v156
	v_add_f32_e32 v157, 1.0, v157
	v_add_f32_e32 v158, 1.0, v158
	v_add_f32_e32 v159, 1.0, v159
	v_rcp_f32_e32 v156, v156
	v_rcp_f32_e32 v157, v157
	v_rcp_f32_e32 v158, v158
	v_rcp_f32_e32 v159, v159
	s_mov_b64 s[2:3], 0x6618000
	v_pk_mul_f32 v[156:157], v[42:43], v[156:157]
	v_lshl_add_u64 v[142:143], v[142:143], 0, s[2:3]
	v_pk_mul_f32 v[158:159], v[44:45], v[158:159]
	v_cvt_pk_bf16_f32 v156, v156, v157
	v_cvt_pk_bf16_f32 v157, v158, v159
	v_lshl_add_u64 v[158:159], v[154:155], 0, v[146:147]
	global_store_dwordx2 v[158:159], v[156:157], off
	v_mul_f32_e32 v156, v38, v38
	v_mul_f32_e32 v157, v39, v39
	v_mul_f32_e32 v158, v40, v40
	v_mul_f32_e32 v159, v41, v41
	v_fmamk_f32 v156, v156, 0xbdd2d3e7, v198
	v_fmamk_f32 v157, v157, 0xbdd2d3e7, v198
	v_fmamk_f32 v158, v158, 0xbdd2d3e7, v198
	v_fmamk_f32 v159, v159, 0xbdd2d3e7, v198
	v_mul_f32_e32 v156, v38, v156
	v_mul_f32_e32 v157, v39, v157
	v_mul_f32_e32 v158, v40, v158
	v_mul_f32_e32 v159, v41, v159
	v_exp_f32_e32 v156, v156
	v_exp_f32_e32 v157, v157
	v_exp_f32_e32 v158, v158
	v_exp_f32_e32 v159, v159
	v_add_f32_e32 v156, 1.0, v156
	v_add_f32_e32 v157, 1.0, v157
	v_add_f32_e32 v158, 1.0, v158
	v_add_f32_e32 v159, 1.0, v159
	v_rcp_f32_e32 v156, v156
	v_rcp_f32_e32 v157, v157
	v_rcp_f32_e32 v158, v158
	v_rcp_f32_e32 v159, v159
	v_lshl_add_u64 v[144:145], v[142:143], 0, v[144:145]
	v_pk_mul_f32 v[156:157], v[38:39], v[156:157]
	v_lshl_add_u64 v[146:147], v[142:143], 0, v[146:147]
	v_pk_mul_f32 v[158:159], v[40:41], v[158:159]
	v_cvt_pk_bf16_f32 v156, v156, v157
	v_cvt_pk_bf16_f32 v157, v158, v159
	global_store_dwordx2 v[144:145], v[156:157], off
	v_mul_f32_e32 v144, v34, v34
	v_mul_f32_e32 v145, v35, v35
	v_mul_f32_e32 v156, v36, v36
	v_mul_f32_e32 v157, v37, v37
	v_fmamk_f32 v144, v144, 0xbdd2d3e7, v198
	v_fmamk_f32 v145, v145, 0xbdd2d3e7, v198
	v_fmamk_f32 v156, v156, 0xbdd2d3e7, v198
	v_fmamk_f32 v157, v157, 0xbdd2d3e7, v198
	v_mul_f32_e32 v144, v34, v144
	v_mul_f32_e32 v145, v35, v145
	v_mul_f32_e32 v156, v36, v156
	v_mul_f32_e32 v157, v37, v157
	v_exp_f32_e32 v144, v144
	v_exp_f32_e32 v145, v145
	v_exp_f32_e32 v156, v156
	v_exp_f32_e32 v157, v157
	v_add_f32_e32 v144, 1.0, v144
	v_add_f32_e32 v145, 1.0, v145
	v_add_f32_e32 v156, 1.0, v156
	v_add_f32_e32 v157, 1.0, v157
	v_rcp_f32_e32 v144, v144
	v_rcp_f32_e32 v145, v145
	v_rcp_f32_e32 v156, v156
	v_rcp_f32_e32 v157, v157
	v_pk_mul_f32 v[144:145], v[34:35], v[144:145]
	s_nop 0
	v_cvt_pk_bf16_f32 v144, v144, v145
	v_pk_mul_f32 v[156:157], v[36:37], v[156:157]
	s_nop 0
	v_cvt_pk_bf16_f32 v145, v156, v157
	global_store_dwordx2 v[146:147], v[144:145], off
	v_mul_f32_e32 v144, v30, v30
	v_mul_f32_e32 v145, v31, v31
	v_mul_f32_e32 v146, v32, v32
	v_mul_f32_e32 v147, v33, v33
	v_fmamk_f32 v144, v144, 0xbdd2d3e7, v198
	v_fmamk_f32 v145, v145, 0xbdd2d3e7, v198
	v_fmamk_f32 v146, v146, 0xbdd2d3e7, v198
	v_fmamk_f32 v147, v147, 0xbdd2d3e7, v198
	v_mul_f32_e32 v144, v30, v144
	v_mul_f32_e32 v145, v31, v145
	v_mul_f32_e32 v146, v32, v146
	v_mul_f32_e32 v147, v33, v147
	v_exp_f32_e32 v144, v144
	v_exp_f32_e32 v145, v145
	v_exp_f32_e32 v146, v146
	v_exp_f32_e32 v147, v147
	v_add_f32_e32 v144, 1.0, v144
	v_add_f32_e32 v145, 1.0, v145
	v_add_f32_e32 v146, 1.0, v146
	v_add_f32_e32 v147, 1.0, v147
	v_rcp_f32_e32 v144, v144
	v_rcp_f32_e32 v145, v145
	v_rcp_f32_e32 v146, v146
	v_rcp_f32_e32 v147, v147
	v_pk_mul_f32 v[144:145], v[30:31], v[144:145]
	s_nop 0
	v_cvt_pk_bf16_f32 v144, v144, v145
	v_pk_mul_f32 v[146:147], v[32:33], v[146:147]
	s_nop 0
	v_cvt_pk_bf16_f32 v145, v146, v147
	v_lshl_add_u64 v[146:147], v[152:153], 0, v[148:149]
	global_store_dwordx2 v[146:147], v[144:145], off
	v_mul_f32_e32 v144, v26, v26
	v_mul_f32_e32 v145, v27, v27
	v_mul_f32_e32 v146, v28, v28
	v_mul_f32_e32 v147, v29, v29
	v_fmamk_f32 v144, v144, 0xbdd2d3e7, v198
	v_fmamk_f32 v145, v145, 0xbdd2d3e7, v198
	v_fmamk_f32 v146, v146, 0xbdd2d3e7, v198
	v_fmamk_f32 v147, v147, 0xbdd2d3e7, v198
	v_mul_f32_e32 v144, v26, v144
	v_mul_f32_e32 v145, v27, v145
	v_mul_f32_e32 v146, v28, v146
	v_mul_f32_e32 v147, v29, v147
	v_exp_f32_e32 v144, v144
	v_exp_f32_e32 v145, v145
	v_exp_f32_e32 v146, v146
	v_exp_f32_e32 v147, v147
	v_add_f32_e32 v144, 1.0, v144
	v_add_f32_e32 v145, 1.0, v145
	v_add_f32_e32 v146, 1.0, v146
	v_add_f32_e32 v147, 1.0, v147
	v_rcp_f32_e32 v144, v144
	v_rcp_f32_e32 v145, v145
	v_rcp_f32_e32 v146, v146
	v_rcp_f32_e32 v147, v147
	v_pk_mul_f32 v[144:145], v[26:27], v[144:145]
	s_nop 0
	v_cvt_pk_bf16_f32 v144, v144, v145
	v_pk_mul_f32 v[146:147], v[28:29], v[146:147]
	s_nop 0
	v_cvt_pk_bf16_f32 v145, v146, v147
	v_lshl_add_u64 v[146:147], v[152:153], 0, v[140:141]
	global_store_dwordx2 v[146:147], v[144:145], off
	v_mul_f32_e32 v144, v22, v22
	v_mul_f32_e32 v145, v23, v23
	v_mul_f32_e32 v146, v24, v24
	v_mul_f32_e32 v147, v25, v25
	v_fmamk_f32 v144, v144, 0xbdd2d3e7, v198
	v_fmamk_f32 v145, v145, 0xbdd2d3e7, v198
; #define GAS __attribute__((address_space(1)))
; __device__ __forceinline__ uint2 pack4(f32x4 v) { return make_uint2(pack2(v[0], v[1]), pack2(v[2], v[3])); }
; __device__ __forceinline__ float gelu_f(float x) {
;   const float c1 = -1.5957691216057308f * 1.4426950408889634f, c2 = c1 * 0.044715f;
;   float u = x * __builtin_fmaf(x * x, c2, c1);
;   return x * __builtin_amdgcn_rcpf(1.0f + __builtin_amdgcn_exp2f(u));
; }
; template <int MODE>
; __device__ __forceinline__ void epi_elem(char* ws, float* outp, const float* b_gate, int g0, int rl, int col, f32x4 v) {
;   if (MODE == E_U || MODE == E_GV) {
;     int lc = col & 1023;
;     f32x4 o; for (int i = 0; i < 4; ++i) o[i] = gelu_f(v[i]);
;     u16* dst = (u16*)(ws + (MODE == E_U ? W_U : W_GV));
;     *(GAS uint2*)(dst + (size_t)rl * 1024 + lc) = pack4(o);
	v_fmamk_f32 v146, v146, 0xbdd2d3e7, v198
	v_fmamk_f32 v147, v147, 0xbdd2d3e7, v198
	v_mul_f32_e32 v144, v22, v144
	v_mul_f32_e32 v145, v23, v145
	v_mul_f32_e32 v146, v24, v146
	v_mul_f32_e32 v147, v25, v147
	v_exp_f32_e32 v144, v144
	v_exp_f32_e32 v145, v145
	v_exp_f32_e32 v146, v146
	v_exp_f32_e32 v147, v147
	v_add_f32_e32 v144, 1.0, v144
	v_add_f32_e32 v145, 1.0, v145
	v_add_f32_e32 v146, 1.0, v146
	v_add_f32_e32 v147, 1.0, v147
	v_rcp_f32_e32 v144, v144
	v_rcp_f32_e32 v145, v145
	v_rcp_f32_e32 v146, v146
	v_rcp_f32_e32 v147, v147
	v_pk_mul_f32 v[144:145], v[22:23], v[144:145]
	s_nop 0
	v_cvt_pk_bf16_f32 v144, v144, v145
	v_pk_mul_f32 v[146:147], v[24:25], v[146:147]
	s_nop 0
	v_cvt_pk_bf16_f32 v145, v146, v147
	v_lshl_add_u64 v[146:147], v[150:151], 0, v[148:149]
	global_store_dwordx2 v[146:147], v[144:145], off
	v_mul_f32_e32 v144, v18, v18
	v_mul_f32_e32 v145, v19, v19
	v_mul_f32_e32 v146, v20, v20
	v_mul_f32_e32 v147, v21, v21
	v_fmamk_f32 v144, v144, 0xbdd2d3e7, v198
	v_fmamk_f32 v145, v145, 0xbdd2d3e7, v198
	v_fmamk_f32 v146, v146, 0xbdd2d3e7, v198
	v_fmamk_f32 v147, v147, 0xbdd2d3e7, v198
	v_mul_f32_e32 v144, v18, v144
	v_mul_f32_e32 v145, v19, v145
	v_mul_f32_e32 v146, v20, v146
	v_mul_f32_e32 v147, v21, v147
	v_exp_f32_e32 v144, v144
	v_exp_f32_e32 v145, v145
	v_exp_f32_e32 v146, v146
	v_exp_f32_e32 v147, v147
	v_add_f32_e32 v144, 1.0, v144
	v_add_f32_e32 v145, 1.0, v145
	v_add_f32_e32 v146, 1.0, v146
	v_add_f32_e32 v147, 1.0, v147
	v_rcp_f32_e32 v144, v144
	v_rcp_f32_e32 v145, v145
	v_rcp_f32_e32 v146, v146
	v_rcp_f32_e32 v147, v147
	v_pk_mul_f32 v[144:145], v[18:19], v[144:145]
	s_nop 0
	v_cvt_pk_bf16_f32 v144, v144, v145
	v_pk_mul_f32 v[146:147], v[20:21], v[146:147]
	s_nop 0
	v_cvt_pk_bf16_f32 v145, v146, v147
	v_lshl_add_u64 v[146:147], v[150:151], 0, v[140:141]
	global_store_dwordx2 v[146:147], v[144:145], off
	v_mul_f32_e32 v144, v14, v14
	v_mul_f32_e32 v145, v15, v15
	v_mul_f32_e32 v146, v16, v16
	v_mul_f32_e32 v147, v17, v17
	v_fmamk_f32 v144, v144, 0xbdd2d3e7, v198
	v_fmamk_f32 v145, v145, 0xbdd2d3e7, v198
	v_fmamk_f32 v146, v146, 0xbdd2d3e7, v198
	v_fmamk_f32 v147, v147, 0xbdd2d3e7, v198
	v_mul_f32_e32 v144, v14, v144
	v_mul_f32_e32 v145, v15, v145
	v_mul_f32_e32 v146, v16, v146
	v_mul_f32_e32 v147, v17, v147
	v_exp_f32_e32 v144, v144
	v_exp_f32_e32 v145, v145
	v_exp_f32_e32 v146, v146
	v_exp_f32_e32 v147, v147
	v_add_f32_e32 v144, 1.0, v144
	v_add_f32_e32 v145, 1.0, v145
	v_add_f32_e32 v146, 1.0, v146
	v_add_f32_e32 v147, 1.0, v147
	v_rcp_f32_e32 v144, v144
	v_rcp_f32_e32 v145, v145
	v_rcp_f32_e32 v146, v146
	v_rcp_f32_e32 v147, v147
	v_pk_mul_f32 v[144:145], v[14:15], v[144:145]
	s_nop 0
	v_cvt_pk_bf16_f32 v144, v144, v145
	v_pk_mul_f32 v[146:147], v[16:17], v[146:147]
	s_nop 0
	v_cvt_pk_bf16_f32 v145, v146, v147
	v_lshl_add_u64 v[146:147], v[154:155], 0, v[148:149]
	global_store_dwordx2 v[146:147], v[144:145], off
	v_mul_f32_e32 v144, v10, v10
	v_mul_f32_e32 v145, v11, v11
	v_mul_f32_e32 v146, v12, v12
	v_mul_f32_e32 v147, v13, v13
	v_fmamk_f32 v144, v144, 0xbdd2d3e7, v198
	v_fmamk_f32 v145, v145, 0xbdd2d3e7, v198
	v_fmamk_f32 v146, v146, 0xbdd2d3e7, v198
	v_fmamk_f32 v147, v147, 0xbdd2d3e7, v198
	v_mul_f32_e32 v144, v10, v144
	v_mul_f32_e32 v145, v11, v145
	v_mul_f32_e32 v146, v12, v146
	v_mul_f32_e32 v147, v13, v147
	v_exp_f32_e32 v144, v144
	v_exp_f32_e32 v145, v145
	v_exp_f32_e32 v146, v146
	v_exp_f32_e32 v147, v147
	v_add_f32_e32 v144, 1.0, v144
	v_add_f32_e32 v145, 1.0, v145
	v_add_f32_e32 v146, 1.0, v146
	v_add_f32_e32 v147, 1.0, v147
	v_rcp_f32_e32 v144, v144
	v_rcp_f32_e32 v145, v145
	v_rcp_f32_e32 v146, v146
	v_rcp_f32_e32 v147, v147
	v_pk_mul_f32 v[144:145], v[10:11], v[144:145]
	s_nop 0
	v_cvt_pk_bf16_f32 v144, v144, v145
	v_pk_mul_f32 v[146:147], v[12:13], v[146:147]
	s_nop 0
	v_cvt_pk_bf16_f32 v145, v146, v147
	v_lshl_add_u64 v[146:147], v[154:155], 0, v[140:141]
	global_store_dwordx2 v[146:147], v[144:145], off
	v_mul_f32_e32 v144, v6, v6
	v_mul_f32_e32 v145, v7, v7
	v_mul_f32_e32 v146, v8, v8
	v_mul_f32_e32 v147, v9, v9
	v_fmamk_f32 v144, v144, 0xbdd2d3e7, v198
	v_fmamk_f32 v145, v145, 0xbdd2d3e7, v198
	v_fmamk_f32 v146, v146, 0xbdd2d3e7, v198
	v_fmamk_f32 v147, v147, 0xbdd2d3e7, v198
	v_mul_f32_e32 v144, v6, v144
	v_mul_f32_e32 v145, v7, v145
	v_mul_f32_e32 v146, v8, v146
	v_mul_f32_e32 v147, v9, v147
	v_exp_f32_e32 v144, v144
	v_exp_f32_e32 v145, v145
	v_exp_f32_e32 v146, v146
	v_exp_f32_e32 v147, v147
	v_add_f32_e32 v144, 1.0, v144
	v_add_f32_e32 v145, 1.0, v145
	v_add_f32_e32 v146, 1.0, v146
	v_add_f32_e32 v147, 1.0, v147
	v_rcp_f32_e32 v144, v144
	v_rcp_f32_e32 v145, v145
	v_rcp_f32_e32 v146, v146
	v_rcp_f32_e32 v147, v147
	v_lshl_add_u64 v[140:141], v[142:143], 0, v[140:141]
	v_pk_mul_f32 v[144:145], v[6:7], v[144:145]
	v_pk_mul_f32 v[146:147], v[8:9], v[146:147]
	v_cvt_pk_bf16_f32 v144, v144, v145
	v_cvt_pk_bf16_f32 v145, v146, v147
	v_lshl_add_u64 v[146:147], v[142:143], 0, v[148:149]
	global_store_dwordx2 v[146:147], v[144:145], off
	v_mul_f32_e32 v144, v2, v2
	v_mul_f32_e32 v145, v3, v3
	v_mul_f32_e32 v146, v4, v4
	v_mul_f32_e32 v147, v5, v5
	v_fmamk_f32 v144, v144, 0xbdd2d3e7, v198
	v_fmamk_f32 v145, v145, 0xbdd2d3e7, v198
	v_fmamk_f32 v146, v146, 0xbdd2d3e7, v198
	v_fmamk_f32 v147, v147, 0xbdd2d3e7, v198
	v_mul_f32_e32 v144, v2, v144
	v_mul_f32_e32 v145, v3, v145
	v_mul_f32_e32 v146, v4, v146
	v_mul_f32_e32 v147, v5, v147
	v_exp_f32_e32 v144, v144
	v_exp_f32_e32 v145, v145
	v_exp_f32_e32 v146, v146
	v_exp_f32_e32 v147, v147
	v_add_f32_e32 v144, 1.0, v144
	v_add_f32_e32 v145, 1.0, v145
	v_add_f32_e32 v146, 1.0, v146
	v_add_f32_e32 v147, 1.0, v147
	v_rcp_f32_e32 v144, v144
	v_rcp_f32_e32 v145, v145
	v_rcp_f32_e32 v146, v146
	v_rcp_f32_e32 v147, v147
	v_pk_mul_f32 v[144:145], v[2:3], v[144:145]
	s_nop 0
	v_cvt_pk_bf16_f32 v144, v144, v145
	v_pk_mul_f32 v[146:147], v[4:5], v[146:147]
	s_nop 0
	v_cvt_pk_bf16_f32 v145, v146, v147
	global_store_dwordx2 v[140:141], v[144:145], off
